# fixed-hoist version + in-proj tile-prologue vmcnt(0) drain removed + counted lgkmcnt waits inside MFMA clusters, run 1
# speedup vs baseline: 1.0094x; 1.0018x over previous
; #define PG8_STAGE(bufoff, gbase, voff) do { _Pragma("unroll") for (int _i = 0; _i < 2; ++_i) \
;         __builtin_amdgcn_global_load_lds((const unsigned*)((const char*)(gbase) + (voff)[_i]), (LAS unsigned*)(lds + (bufoff) + ldsw + _i * 8192), 16, 0, 0); } while (0)
; #define PG8_LDA(dst, b, h) do { _Pragma("unroll") for (int m = 0; m < 4; ++m) _Pragma("unroll") for (int k = 0; k < 2; ++k) dst[m][k] = *(const LAS bf16x8*)(lds + PG8_SA(b, h) + aoff + m * 2048 + k * 1024); } while (0)
; #define PG8_LDB(dst, b, h) do { _Pragma("unroll") for (int n = 0; n < 2; ++n) _Pragma("unroll") for (int k = 0; k < 2; ++k) dst[n][k] = *(const LAS bf16x8*)(lds + PG8_SB(b, h) + boff + n * 2048 + k * 1024); } while (0)
; #define PG8_MMA(ai, bj, At, Bt) do { __builtin_amdgcn_s_setprio(1); _Pragma("unroll") for (int m = 0; m < 4; ++m) _Pragma("unroll") for (int n = 0; n < 2; ++n) _Pragma("unroll") for (int k = 0; k < 2; ++k) \
;         acc[ai][bj][m][n] = __builtin_amdgcn_mfma_f32_16x16x32_bf16(Bt[n][k], At[m][k], acc[ai][bj][m][n], 0, 0, 0); __builtin_amdgcn_s_setprio(0); } while (0)
; #define PG8_WAIT_V(n) asm volatile("s_waitcnt vmcnt(" #n ")" ::: "memory")
; #define PG8_WAIT_L(n) asm volatile("s_waitcnt lgkmcnt(" #n ")" ::: "memory")
; #define PG8_BAR __builtin_amdgcn_s_barrier()
; #define PG8_SCHED __builtin_amdgcn_sched_barrier(0)
; template <class Epi>
; __device__ __forceinline__ void gemm_phase(LAS unsigned char* lds, const Gemm g, const StaticOrder& S, const Epi& E) {
;     ...
;             PG8_LDB(B0, 0, 0); PG8_SCHED; PG8_LDA(At, 0, 0); PG8_STAGE(PG8_SA(1, 1), a1 + hstepA, voffA);
;             PG8_WAIT_L(8); PG8_BAR; PG8_WAIT_L(0); PG8_MMA(0, 0, At, B0); PG8_BAR; PG8_SCHED;
;             PG8_LDB(B1, 0, 1); PG8_STAGE(PG8_SB(0, 0), b2, voffB);
;             PG8_BAR; PG8_WAIT_L(0); PG8_MMA(0, 1, At, B1); PG8_BAR;
;             PG8_LDA(At, 0, 1); PG8_STAGE(PG8_SA(0, 0), a2, voffA);
;             PG8_BAR; PG8_WAIT_L(0); PG8_MMA(1, 0, At, B0); PG8_BAR; PG8_SCHED;
;             PG8_STAGE(PG8_SB(0, 1), b2 + hstepB, voffB);
;             PG8_WAIT_V(6); PG8_BAR; PG8_MMA(1, 1, At, B1); PG8_BAR;
.LBB0_158:
	s_add_u32 s42, s38, 0x100
	s_addc_u32 s43, s39, 0
	s_add_i32 s60, 0, 0x10000
	ds_read_b128 v[146:149], v250
	ds_read_b128 v[162:165], v250 offset:1024
	ds_read_b128 v[166:169], v250 offset:2048
	ds_read_b128 v[170:173], v250 offset:3072
	s_cmp_eq_u32 s59, 28
	s_cselect_b32 s25, s23, s43
	s_cselect_b32 s24, s55, s42
	s_cselect_b32 s5, s21, s58
	s_cselect_b32 s4, s56, s57
	s_add_i32 m0, s46, 0xc000
	ds_read_b128 v[174:177], v154
	ds_read_b128 v[192:195], v154 offset:2048
	ds_read_b128 v[200:203], v154 offset:4096
	ds_read_b128 v[208:211], v154 offset:6144
	ds_read_b128 v[188:191], v154 offset:1024
	ds_read_b128 v[196:199], v154 offset:3072
	ds_read_b128 v[204:207], v154 offset:5120
	ds_read_b128 v[212:215], v154 offset:7168
	global_load_lds_dwordx4 v140, s[38:39]
	s_add_i32 m0, s46, 0xe000
	s_nop 0
	global_load_lds_dwordx4 v142, s[38:39]
	s_waitcnt lgkmcnt(8)
	s_barrier
	s_waitcnt lgkmcnt(4)
	v_mfma_f32_16x16x32_bf16 v[126:129], v[146:149], v[174:177], v[126:129]
	v_mfma_f32_16x16x32_bf16 v[122:125], v[166:169], v[174:177], v[122:125]
	v_mfma_f32_16x16x32_bf16 v[110:113], v[146:149], v[192:195], v[110:113]
	v_mfma_f32_16x16x32_bf16 v[106:109], v[166:169], v[192:195], v[106:109]
	v_mfma_f32_16x16x32_bf16 v[94:97], v[146:149], v[200:203], v[94:97]
	v_mfma_f32_16x16x32_bf16 v[90:93], v[166:169], v[200:203], v[90:93]
	v_mfma_f32_16x16x32_bf16 v[78:81], v[146:149], v[208:211], v[78:81]
	v_mfma_f32_16x16x32_bf16 v[74:77], v[166:169], v[208:211], v[74:77]
	s_waitcnt lgkmcnt(0)
	v_mfma_f32_16x16x32_bf16 v[126:129], v[162:165], v[188:191], v[126:129]
	v_mfma_f32_16x16x32_bf16 v[122:125], v[170:173], v[188:191], v[122:125]
	v_mfma_f32_16x16x32_bf16 v[110:113], v[162:165], v[196:199], v[110:113]
	v_mfma_f32_16x16x32_bf16 v[106:109], v[170:173], v[196:199], v[106:109]
	v_mfma_f32_16x16x32_bf16 v[94:97], v[162:165], v[204:207], v[94:97]
	v_mfma_f32_16x16x32_bf16 v[90:93], v[170:173], v[204:207], v[90:93]
	v_mfma_f32_16x16x32_bf16 v[78:81], v[162:165], v[212:215], v[78:81]
	v_mfma_f32_16x16x32_bf16 v[74:77], v[170:173], v[212:215], v[74:77]
	s_barrier
	s_add_i32 s61, 0, 0x14000
	s_add_i32 s38, s60, s45
	s_add_u32 s100, s4, s6
	s_addc_u32 s101, s5, s7
	s_mov_b32 m0, s38
	ds_read_b128 v[216:219], v250 offset:16384
	ds_read_b128 v[224:227], v250 offset:18432
	ds_read_b128 v[220:223], v250 offset:17408
	ds_read_b128 v[228:231], v250 offset:19456
	global_load_lds_dwordx4 v134, s[4:5]
	s_add_i32 m0, s38, 0x2000
	s_nop 0
	global_load_lds_dwordx4 v130, s[4:5]
	s_barrier
	s_waitcnt lgkmcnt(2)
	v_mfma_f32_16x16x32_bf16 v[118:121], v[216:219], v[174:177], v[118:121]
	v_mfma_f32_16x16x32_bf16 v[114:117], v[224:227], v[174:177], v[114:117]
	v_mfma_f32_16x16x32_bf16 v[102:105], v[216:219], v[192:195], v[102:105]
	v_mfma_f32_16x16x32_bf16 v[98:101], v[224:227], v[192:195], v[98:101]
	v_mfma_f32_16x16x32_bf16 v[86:89], v[216:219], v[200:203], v[86:89]
	v_mfma_f32_16x16x32_bf16 v[82:85], v[224:227], v[200:203], v[82:85]
	v_mfma_f32_16x16x32_bf16 v[70:73], v[216:219], v[208:211], v[70:73]
	v_mfma_f32_16x16x32_bf16 v[66:69], v[224:227], v[208:211], v[66:69]
	s_waitcnt lgkmcnt(0)
	v_mfma_f32_16x16x32_bf16 v[118:121], v[220:223], v[188:191], v[118:121]
	v_mfma_f32_16x16x32_bf16 v[114:117], v[228:231], v[188:191], v[114:117]
	v_mfma_f32_16x16x32_bf16 v[102:105], v[220:223], v[196:199], v[102:105]
	v_mfma_f32_16x16x32_bf16 v[98:101], v[228:231], v[196:199], v[98:101]
	v_mfma_f32_16x16x32_bf16 v[86:89], v[220:223], v[204:207], v[86:89]
	v_mfma_f32_16x16x32_bf16 v[82:85], v[228:231], v[204:207], v[82:85]
	v_mfma_f32_16x16x32_bf16 v[70:73], v[220:223], v[212:215], v[70:73]
	v_mfma_f32_16x16x32_bf16 v[66:69], v[228:231], v[212:215], v[66:69]
	s_mov_b32 m0, s46
	s_add_u32 vcc_lo, s24, s6
	s_addc_u32 vcc_hi, s25, s7
	s_barrier
	ds_read_b128 v[174:177], v154 offset:16384
	ds_read_b128 v[192:195], v154 offset:18432
	ds_read_b128 v[200:203], v154 offset:20480
	ds_read_b128 v[208:211], v154 offset:22528
	ds_read_b128 v[188:191], v154 offset:17408
	ds_read_b128 v[196:199], v154 offset:19456
	ds_read_b128 v[204:207], v154 offset:21504
	ds_read_b128 v[212:215], v154 offset:23552
	global_load_lds_dwordx4 v136, s[24:25]
	s_mov_b32 m0, s47
	s_nop 0
	global_load_lds_dwordx4 v132, s[24:25]
	s_barrier
	s_waitcnt lgkmcnt(4)
	v_mfma_f32_16x16x32_bf16 v[62:65], v[146:149], v[174:177], v[62:65]
	v_mfma_f32_16x16x32_bf16 v[58:61], v[166:169], v[174:177], v[58:61]
	v_mfma_f32_16x16x32_bf16 v[46:49], v[146:149], v[192:195], v[46:49]
	v_mfma_f32_16x16x32_bf16 v[42:45], v[166:169], v[192:195], v[42:45]
	v_mfma_f32_16x16x32_bf16 v[30:33], v[146:149], v[200:203], v[30:33]
	v_mfma_f32_16x16x32_bf16 v[26:29], v[166:169], v[200:203], v[26:29]
	v_mfma_f32_16x16x32_bf16 v[14:17], v[146:149], v[208:211], v[14:17]
	v_mfma_f32_16x16x32_bf16 v[10:13], v[166:169], v[208:211], v[10:13]
	s_waitcnt lgkmcnt(0)
	v_mfma_f32_16x16x32_bf16 v[62:65], v[162:165], v[188:191], v[62:65]
	v_mfma_f32_16x16x32_bf16 v[58:61], v[170:173], v[188:191], v[58:61]
	v_mfma_f32_16x16x32_bf16 v[46:49], v[162:165], v[196:199], v[46:49]
	v_mfma_f32_16x16x32_bf16 v[42:45], v[170:173], v[196:199], v[42:45]
	v_mfma_f32_16x16x32_bf16 v[30:33], v[162:165], v[204:207], v[30:33]
	v_mfma_f32_16x16x32_bf16 v[26:29], v[170:173], v[204:207], v[26:29]
	v_mfma_f32_16x16x32_bf16 v[14:17], v[162:165], v[212:215], v[14:17]
	v_mfma_f32_16x16x32_bf16 v[10:13], v[170:173], v[212:215], v[10:13]
	s_barrier
	s_add_u32 s38, s4, 0x80000
	s_addc_u32 s39, s5, 0
	s_add_i32 s60, s61, s45
	s_mov_b32 m0, s60
	s_nop 0
	global_load_lds_dwordx4 v134, s[38:39]
	s_add_i32 m0, s60, 0x2000
	s_nop 0
	global_load_lds_dwordx4 v130, s[38:39]
	s_waitcnt vmcnt(6)
	s_barrier
; #define PG8_STAGE(bufoff, gbase, voff) do { _Pragma("unroll") for (int _i = 0; _i < 2; ++_i) \
;         __builtin_amdgcn_global_load_lds((const unsigned*)((const char*)(gbase) + (voff)[_i]), (LAS unsigned*)(lds + (bufoff) + ldsw + _i * 8192), 16, 0, 0); } while (0)
; #define PG8_LDA(dst, b, h) do { _Pragma("unroll") for (int m = 0; m < 4; ++m) _Pragma("unroll") for (int k = 0; k < 2; ++k) dst[m][k] = *(const LAS bf16x8*)(lds + PG8_SA(b, h) + aoff + m * 2048 + k * 1024); } while (0)
; #define PG8_LDB(dst, b, h) do { _Pragma("unroll") for (int n = 0; n < 2; ++n) _Pragma("unroll") for (int k = 0; k < 2; ++k) dst[n][k] = *(const LAS bf16x8*)(lds + PG8_SB(b, h) + boff + n * 2048 + k * 1024); } while (0)
; #define PG8_MMA(ai, bj, At, Bt) do { __builtin_amdgcn_s_setprio(1); _Pragma("unroll") for (int m = 0; m < 4; ++m) _Pragma("unroll") for (int n = 0; n < 2; ++n) _Pragma("unroll") for (int k = 0; k < 2; ++k) \
;         acc[ai][bj][m][n] = __builtin_amdgcn_mfma_f32_16x16x32_bf16(Bt[n][k], At[m][k], acc[ai][bj][m][n], 0, 0, 0); __builtin_amdgcn_s_setprio(0); } while (0)
; #define PG8_WAIT_V(n) asm volatile("s_waitcnt vmcnt(" #n ")" ::: "memory")
; #define PG8_WAIT_L(n) asm volatile("s_waitcnt lgkmcnt(" #n ")" ::: "memory")
; #define PG8_BAR __builtin_amdgcn_s_barrier()
; #define PG8_SCHED __builtin_amdgcn_sched_barrier(0)
; template <class Epi>
; __device__ __forceinline__ void gemm_phase(LAS unsigned char* lds, const Gemm g, const StaticOrder& S, const Epi& E) {
;     ...
;             PG8_WAIT_V(6); PG8_BAR; PG8_MMA(1, 1, At, B1); PG8_BAR;
;             PG8_LDB(B0, 1, 0); PG8_SCHED; PG8_LDA(At, 1, 0); PG8_STAGE(PG8_SA(0, 1), a2 + hstepA, voffA);
;             PG8_WAIT_L(8); PG8_BAR; PG8_WAIT_L(0); PG8_MMA(0, 0, At, B0); PG8_BAR; PG8_SCHED;
;             PG8_LDB(B1, 1, 1); PG8_STAGE(PG8_SB(1, 0), b3, voffB);
;             PG8_BAR; PG8_WAIT_L(0); PG8_MMA(0, 1, At, B1); PG8_BAR;
	v_mfma_f32_16x16x32_bf16 v[54:57], v[216:219], v[174:177], v[54:57]
	v_mfma_f32_16x16x32_bf16 v[50:53], v[224:227], v[174:177], v[50:53]
	v_mfma_f32_16x16x32_bf16 v[38:41], v[216:219], v[192:195], v[38:41]
	v_mfma_f32_16x16x32_bf16 v[34:37], v[224:227], v[192:195], v[34:37]
	v_mfma_f32_16x16x32_bf16 v[22:25], v[216:219], v[200:203], v[22:25]
	v_mfma_f32_16x16x32_bf16 v[18:21], v[224:227], v[200:203], v[18:21]
	v_mfma_f32_16x16x32_bf16 v[6:9], v[216:219], v[208:211], v[6:9]
	v_mfma_f32_16x16x32_bf16 v[2:5], v[224:227], v[208:211], v[2:5]
	v_mfma_f32_16x16x32_bf16 v[54:57], v[220:223], v[188:191], v[54:57]
	v_mfma_f32_16x16x32_bf16 v[50:53], v[228:231], v[188:191], v[50:53]
	v_mfma_f32_16x16x32_bf16 v[38:41], v[220:223], v[196:199], v[38:41]
	v_mfma_f32_16x16x32_bf16 v[34:37], v[228:231], v[196:199], v[34:37]
	v_mfma_f32_16x16x32_bf16 v[22:25], v[220:223], v[204:207], v[22:25]
	v_mfma_f32_16x16x32_bf16 v[18:21], v[228:231], v[204:207], v[18:21]
	v_mfma_f32_16x16x32_bf16 v[6:9], v[220:223], v[212:215], v[6:9]
	v_mfma_f32_16x16x32_bf16 v[2:5], v[228:231], v[212:215], v[2:5]
	s_add_i32 s38, 0, 0x18000
	s_barrier
	ds_read_b128 v[146:149], v250 offset:32768
	ds_read_b128 v[162:165], v250 offset:33792
	ds_read_b128 v[166:169], v250 offset:34816
	ds_read_b128 v[170:173], v250 offset:35840
	s_add_u32 s24, s24, 0x80000
	s_addc_u32 s25, s25, 0
	s_mov_b32 m0, s48
	ds_read_b128 v[174:177], v154 offset:32768
	ds_read_b128 v[192:195], v154 offset:34816
	ds_read_b128 v[200:203], v154 offset:36864
	ds_read_b128 v[208:211], v154 offset:38912
	ds_read_b128 v[188:191], v154 offset:33792
	ds_read_b128 v[196:199], v154 offset:35840
	ds_read_b128 v[204:207], v154 offset:37888
	ds_read_b128 v[212:215], v154 offset:39936
	global_load_lds_dwordx4 v136, s[24:25]
	s_mov_b32 m0, s49
	s_nop 0
	global_load_lds_dwordx4 v132, s[24:25]
	s_waitcnt lgkmcnt(8)
	s_barrier
	s_waitcnt lgkmcnt(4)
	v_mfma_f32_16x16x32_bf16 v[126:129], v[146:149], v[174:177], v[126:129]
	v_mfma_f32_16x16x32_bf16 v[122:125], v[166:169], v[174:177], v[122:125]
	v_mfma_f32_16x16x32_bf16 v[110:113], v[146:149], v[192:195], v[110:113]
	v_mfma_f32_16x16x32_bf16 v[106:109], v[166:169], v[192:195], v[106:109]
	v_mfma_f32_16x16x32_bf16 v[94:97], v[146:149], v[200:203], v[94:97]
	v_mfma_f32_16x16x32_bf16 v[90:93], v[166:169], v[200:203], v[90:93]
	v_mfma_f32_16x16x32_bf16 v[78:81], v[146:149], v[208:211], v[78:81]
	v_mfma_f32_16x16x32_bf16 v[74:77], v[166:169], v[208:211], v[74:77]
	s_waitcnt lgkmcnt(0)
	v_mfma_f32_16x16x32_bf16 v[126:129], v[162:165], v[188:191], v[126:129]
	v_mfma_f32_16x16x32_bf16 v[122:125], v[170:173], v[188:191], v[122:125]
	v_mfma_f32_16x16x32_bf16 v[110:113], v[162:165], v[196:199], v[110:113]
	v_mfma_f32_16x16x32_bf16 v[106:109], v[170:173], v[196:199], v[106:109]
	v_mfma_f32_16x16x32_bf16 v[94:97], v[162:165], v[204:207], v[94:97]
	v_mfma_f32_16x16x32_bf16 v[90:93], v[170:173], v[204:207], v[90:93]
	v_mfma_f32_16x16x32_bf16 v[78:81], v[162:165], v[212:215], v[78:81]
	v_mfma_f32_16x16x32_bf16 v[74:77], v[170:173], v[212:215], v[74:77]
	s_barrier
	s_add_i32 s24, 0, 0x1c000
	s_add_i32 s25, s38, s45
	s_mov_b32 m0, s25
	ds_read_b128 v[216:219], v250 offset:49152
	ds_read_b128 v[224:227], v250 offset:51200
	ds_read_b128 v[220:223], v250 offset:50176
	ds_read_b128 v[228:231], v250 offset:52224
	global_load_lds_dwordx4 v134, s[100:101]
	s_add_i32 m0, s25, 0x2000
	s_nop 0
	global_load_lds_dwordx4 v130, s[100:101]
	s_barrier
	s_waitcnt lgkmcnt(2)
	v_mfma_f32_16x16x32_bf16 v[118:121], v[216:219], v[174:177], v[118:121]
	v_mfma_f32_16x16x32_bf16 v[114:117], v[224:227], v[174:177], v[114:117]
	v_mfma_f32_16x16x32_bf16 v[102:105], v[216:219], v[192:195], v[102:105]
	v_mfma_f32_16x16x32_bf16 v[98:101], v[224:227], v[192:195], v[98:101]
	v_mfma_f32_16x16x32_bf16 v[86:89], v[216:219], v[200:203], v[86:89]
	v_mfma_f32_16x16x32_bf16 v[82:85], v[224:227], v[200:203], v[82:85]
	v_mfma_f32_16x16x32_bf16 v[70:73], v[216:219], v[208:211], v[70:73]
	v_mfma_f32_16x16x32_bf16 v[66:69], v[224:227], v[208:211], v[66:69]
	s_waitcnt lgkmcnt(0)
	v_mfma_f32_16x16x32_bf16 v[118:121], v[220:223], v[188:191], v[118:121]
	v_mfma_f32_16x16x32_bf16 v[114:117], v[228:231], v[188:191], v[114:117]
	v_mfma_f32_16x16x32_bf16 v[102:105], v[220:223], v[196:199], v[102:105]
	v_mfma_f32_16x16x32_bf16 v[98:101], v[228:231], v[196:199], v[98:101]
	v_mfma_f32_16x16x32_bf16 v[86:89], v[220:223], v[204:207], v[86:89]
	v_mfma_f32_16x16x32_bf16 v[82:85], v[228:231], v[204:207], v[82:85]
	v_mfma_f32_16x16x32_bf16 v[70:73], v[220:223], v[212:215], v[70:73]
	v_mfma_f32_16x16x32_bf16 v[66:69], v[228:231], v[212:215], v[66:69]
	s_mov_b32 m0, s50
	s_barrier
; __device__ __forceinline__ unsigned cvt_pk_bf16(float lo, float hi) { unsigned r; asm volatile("v_cvt_pk_bf16_f32 %0, %1, %2" : "=v"(r) : "v"(lo), "v"(hi)); return r; }
; #define PG8_STAGE(bufoff, gbase, voff) do { _Pragma("unroll") for (int _i = 0; _i < 2; ++_i) \
;         __builtin_amdgcn_global_load_lds((const unsigned*)((const char*)(gbase) + (voff)[_i]), (LAS unsigned*)(lds + (bufoff) + ldsw + _i * 8192), 16, 0, 0); } while (0)
; #define PG8_LDA(dst, b, h) do { _Pragma("unroll") for (int m = 0; m < 4; ++m) _Pragma("unroll") for (int k = 0; k < 2; ++k) dst[m][k] = *(const LAS bf16x8*)(lds + PG8_SA(b, h) + aoff + m * 2048 + k * 1024); } while (0)
; #define PG8_WAIT_V(n) asm volatile("s_waitcnt vmcnt(" #n ")" ::: "memory")
; #define PG8_WAIT_L(n) asm volatile("s_waitcnt lgkmcnt(" #n ")" ::: "memory")
; #define PG8_BAR __builtin_amdgcn_s_barrier()
; #define PG8_SCHED __builtin_amdgcn_sched_barrier(0)
; template <class Epi>
; __device__ __forceinline__ void gemm_phase(LAS unsigned char* lds, const Gemm g, const StaticOrder& S, const Epi& E) {
;     ...
;             PG8_LDA(At, 1, 1); PG8_STAGE(PG8_SA(1, 0), a3, voffA);
;             PG8_BAR; PG8_WAIT_L(0); PG8_MMA(1, 0, At, B0); PG8_BAR; PG8_SCHED;
;             PG8_STAGE(PG8_SB(1, 1), b3 + hstepB, voffB);
;             PG8_WAIT_V(6); PG8_BAR; PG8_MMA(1, 1, At, B1); PG8_BAR;
;     __device__ __forceinline__ void operator()(const f32x4 (&acc)[2][2][4][2], const Unit& u, int wr, int wc, int fr, int fq, const Pre& pp) const {
;         const int row0 = u.pm * BM + wr * 64 + fr, col0 = u.pn * BM + wc * 32 + 8 * fq;
;         const bool gm = (UG != nullptr) && (u.pn < DE / BM);
;         const float (&rs)[8] = pp.rs;
; #pragma unroll
;         for (int ai = 0; ai < 2; ++ai)
; #pragma unroll
;             for (int m = 0; m < 4; ++m) { const int r = row0 + ai * HALF + m * 16; const float inv = rsqrtf(rs[ai * 4 + m] * (1.0f / DM) + EPS);
; #pragma unroll
;                 for (int bj = 0; bj < 2; ++bj) { const f32x4 v0 = acc[ai][bj][m][0] * inv, v1 = acc[ai][bj][m][1] * inv; const int c = col0 + bj * HALF;
;                     u32x4 w; w.x = cvt_pk_bf16(v0[0], v0[1]); w.y = cvt_pk_bf16(v0[2], v0[3]); w.z = cvt_pk_bf16(v1[0], v1[1]); w.w = cvt_pk_bf16(v1[2], v1[3]);
;                     bf16_t* dst = gm ? UG + (size_t)(c >> 4) * GSTR + r * 16 + (c & 15) : O + (size_t)r * DE2 + c;
	ds_read_b128 v[174:177], v154 offset:49152
	ds_read_b128 v[192:195], v154 offset:51200
	ds_read_b128 v[200:203], v154 offset:53248
	ds_read_b128 v[208:211], v154 offset:55296
	ds_read_b128 v[188:191], v154 offset:50176
	ds_read_b128 v[196:199], v154 offset:52224
	ds_read_b128 v[204:207], v154 offset:54272
	ds_read_b128 v[212:215], v154 offset:56320
	global_load_lds_dwordx4 v136, vcc
	s_mov_b32 m0, s51
	s_nop 0
	global_load_lds_dwordx4 v132, vcc
	s_barrier
	s_waitcnt lgkmcnt(4)
	v_mfma_f32_16x16x32_bf16 v[62:65], v[146:149], v[174:177], v[62:65]
	v_mfma_f32_16x16x32_bf16 v[58:61], v[166:169], v[174:177], v[58:61]
	v_mfma_f32_16x16x32_bf16 v[46:49], v[146:149], v[192:195], v[46:49]
	v_mfma_f32_16x16x32_bf16 v[42:45], v[166:169], v[192:195], v[42:45]
	v_mfma_f32_16x16x32_bf16 v[30:33], v[146:149], v[200:203], v[30:33]
	v_mfma_f32_16x16x32_bf16 v[26:29], v[166:169], v[200:203], v[26:29]
	v_mfma_f32_16x16x32_bf16 v[14:17], v[146:149], v[208:211], v[14:17]
	v_mfma_f32_16x16x32_bf16 v[10:13], v[166:169], v[208:211], v[10:13]
	s_waitcnt lgkmcnt(0)
	v_mfma_f32_16x16x32_bf16 v[62:65], v[162:165], v[188:191], v[62:65]
	v_mfma_f32_16x16x32_bf16 v[58:61], v[170:173], v[188:191], v[58:61]
	v_mfma_f32_16x16x32_bf16 v[46:49], v[162:165], v[196:199], v[46:49]
	v_mfma_f32_16x16x32_bf16 v[42:45], v[170:173], v[196:199], v[42:45]
	v_mfma_f32_16x16x32_bf16 v[30:33], v[162:165], v[204:207], v[30:33]
	v_mfma_f32_16x16x32_bf16 v[26:29], v[170:173], v[204:207], v[26:29]
	v_mfma_f32_16x16x32_bf16 v[14:17], v[162:165], v[212:215], v[14:17]
	v_mfma_f32_16x16x32_bf16 v[10:13], v[170:173], v[212:215], v[10:13]
	s_barrier
	s_add_u32 s4, s4, 0x80080
	s_addc_u32 s5, s5, 0
	s_add_i32 s24, s24, s45
	s_mov_b32 m0, s24
	s_nop 0
	global_load_lds_dwordx4 v134, s[4:5]
	s_add_i32 m0, s24, 0x2000
	s_nop 0
	global_load_lds_dwordx4 v130, s[4:5]
	s_waitcnt vmcnt(6)
	s_barrier
	v_mfma_f32_16x16x32_bf16 v[54:57], v[216:219], v[174:177], v[54:57]
	v_mfma_f32_16x16x32_bf16 v[50:53], v[224:227], v[174:177], v[50:53]
	v_mfma_f32_16x16x32_bf16 v[38:41], v[216:219], v[192:195], v[38:41]
	v_mfma_f32_16x16x32_bf16 v[34:37], v[224:227], v[192:195], v[34:37]
	v_mfma_f32_16x16x32_bf16 v[22:25], v[216:219], v[200:203], v[22:25]
	v_mfma_f32_16x16x32_bf16 v[18:21], v[224:227], v[200:203], v[18:21]
	v_mfma_f32_16x16x32_bf16 v[6:9], v[216:219], v[208:211], v[6:9]
	v_mfma_f32_16x16x32_bf16 v[2:5], v[224:227], v[208:211], v[2:5]
	v_mfma_f32_16x16x32_bf16 v[54:57], v[220:223], v[188:191], v[54:57]
	v_mfma_f32_16x16x32_bf16 v[50:53], v[228:231], v[188:191], v[50:53]
	v_mfma_f32_16x16x32_bf16 v[38:41], v[220:223], v[196:199], v[38:41]
	v_mfma_f32_16x16x32_bf16 v[34:37], v[228:231], v[196:199], v[34:37]
	v_mfma_f32_16x16x32_bf16 v[22:25], v[220:223], v[204:207], v[22:25]
	v_mfma_f32_16x16x32_bf16 v[18:21], v[228:231], v[204:207], v[18:21]
	v_mfma_f32_16x16x32_bf16 v[6:9], v[220:223], v[212:215], v[6:9]
	v_mfma_f32_16x16x32_bf16 v[2:5], v[228:231], v[212:215], v[2:5]
	s_add_i32 s59, s59, 2
	s_add_u32 s57, s57, 0x100
	s_addc_u32 s58, s58, 0
	s_cmp_gt_u32 s59, 29
	s_mov_b64 s[38:39], s[42:43]
	s_barrier
	s_cbranch_scc0 .LBB0_158
	v_fmamk_f32 v0, v145, 0x3a000000, v233
	v_cmp_gt_f32_e32 vcc, s66, v0
	v_mul_f32_e32 v145, 0x4b800000, v0
	v_readlane_b32 s38, v254, 47
	v_cndmask_b32_e32 v0, v0, v145, vcc
	v_rsq_f32_e32 v0, v0
	v_lshl_add_u32 v146, s54, 8, v139
	s_cmp_gt_i32 s53, 15
	v_readlane_b32 s39, v254, 48
	v_mul_f32_e32 v145, 0x45800000, v0
	s_cselect_b64 s[4:5], -1, 0
	s_xor_b64 s[38:39], s[38:39], -1
	v_cndmask_b32_e32 v148, v0, v145, vcc
	v_ashrrev_i32_e32 v147, 31, v146
	s_or_b64 s[4:5], s[38:39], s[4:5]
	v_lshl_or_b32 v144, s53, 8, v153
	v_lshlrev_b64 v[150:151], 14, v[146:147]
	v_pk_mul_f32 v[128:129], v[148:149], v[128:129] op_sel_hi:[0,1]
	s_mov_b64 s[24:25], -1
	v_pk_mul_f32 v[126:127], v[148:149], v[126:127] op_sel_hi:[0,1]
	v_pk_mul_f32 v[162:163], v[148:149], v[124:125] op_sel_hi:[0,1]
	v_pk_mul_f32 v[124:125], v[148:149], v[122:123] op_sel_hi:[0,1]
	v_cvt_pk_bf16_f32 v122, v126, v127
	v_cvt_pk_bf16_f32 v123, v128, v129
	s_and_b64 vcc, exec, s[4:5]
	v_lshl_add_u64 v[128:129], s[16:17], 0, v[150:151]
	v_ashrrev_i32_e32 v145, 31, v144
	v_cvt_pk_bf16_f32 v124, v124, v125
	v_cvt_pk_bf16_f32 v125, v162, v163
	s_cbranch_vccz .LBB0_161
	v_lshl_add_u64 v[150:151], v[144:145], 1, v[128:129]
	s_mov_b64 s[24:25], 0

; #define PG8_STAGE(bufoff, gbase, voff) do { _Pragma("unroll") for (int _i = 0; _i < 2; ++_i) \
;         __builtin_amdgcn_global_load_lds((const unsigned*)((const char*)(gbase) + (voff)[_i]), (LAS unsigned*)(lds + (bufoff) + ldsw + _i * 8192), 16, 0, 0); } while (0)
; #define PG8_LDA(dst, b, h) do { _Pragma("unroll") for (int m = 0; m < 4; ++m) _Pragma("unroll") for (int k = 0; k < 2; ++k) dst[m][k] = *(const LAS bf16x8*)(lds + PG8_SA(b, h) + aoff + m * 2048 + k * 1024); } while (0)
; #define PG8_LDB(dst, b, h) do { _Pragma("unroll") for (int n = 0; n < 2; ++n) _Pragma("unroll") for (int k = 0; k < 2; ++k) dst[n][k] = *(const LAS bf16x8*)(lds + PG8_SB(b, h) + boff + n * 2048 + k * 1024); } while (0)
; #define PG8_MMA(ai, bj, At, Bt) do { __builtin_amdgcn_s_setprio(1); _Pragma("unroll") for (int m = 0; m < 4; ++m) _Pragma("unroll") for (int n = 0; n < 2; ++n) _Pragma("unroll") for (int k = 0; k < 2; ++k) \
;         acc[ai][bj][m][n] = __builtin_amdgcn_mfma_f32_16x16x32_bf16(Bt[n][k], At[m][k], acc[ai][bj][m][n], 0, 0, 0); __builtin_amdgcn_s_setprio(0); } while (0)
; #define PG8_WAIT_V(n) asm volatile("s_waitcnt vmcnt(" #n ")" ::: "memory")
; #define PG8_WAIT_L(n) asm volatile("s_waitcnt lgkmcnt(" #n ")" ::: "memory")
; #define PG8_BAR __builtin_amdgcn_s_barrier()
; #define PG8_SCHED __builtin_amdgcn_sched_barrier(0)
; template <class Epi>
; __device__ __forceinline__ void gemm_phase(LAS unsigned char* lds, const Gemm g, const StaticOrder& S, const Epi& E) {
;     ...
;             PG8_LDB(B0, 0, 0); PG8_SCHED; PG8_LDA(At, 0, 0); PG8_STAGE(PG8_SA(1, 1), a1 + hstepA, voffA);
;             PG8_WAIT_L(8); PG8_BAR; PG8_WAIT_L(0); PG8_MMA(0, 0, At, B0); PG8_BAR; PG8_SCHED;
;             PG8_LDB(B1, 0, 1); PG8_STAGE(PG8_SB(0, 0), b2, voffB);
;             PG8_BAR; PG8_WAIT_L(0); PG8_MMA(0, 1, At, B1); PG8_BAR;
;             PG8_LDA(At, 0, 1); PG8_STAGE(PG8_SA(0, 0), a2, voffA);
;             PG8_BAR; PG8_WAIT_L(0); PG8_MMA(1, 0, At, B0); PG8_BAR; PG8_SCHED;
;             PG8_STAGE(PG8_SB(0, 1), b2 + hstepB, voffB);
;             PG8_WAIT_V(6); PG8_BAR; PG8_MMA(1, 1, At, B1); PG8_BAR;
.LBB0_359:
	s_add_u32 s26, s22, 0x100
	s_addc_u32 s27, s23, 0
	s_add_i32 s65, 0, 0x10000
	ds_read_b128 v[70:73], v250
	ds_read_b128 v[74:77], v250 offset:1024
	ds_read_b128 v[82:85], v250 offset:2048
	ds_read_b128 v[86:89], v250 offset:3072
	s_cmp_eq_u32 s64, 60
	s_cselect_b32 s25, s17, s27
	s_cselect_b32 s24, s60, s26
	s_cselect_b32 s37, s15, s63
	s_cselect_b32 s36, s61, s62
	s_add_i32 m0, s53, 0xc000
	ds_read_b128 v[146:149], v211
	ds_read_b128 v[154:157], v211 offset:2048
	ds_read_b128 v[162:165], v211 offset:4096
	ds_read_b128 v[170:173], v211 offset:6144
	ds_read_b128 v[150:153], v211 offset:1024
	ds_read_b128 v[158:161], v211 offset:3072
	ds_read_b128 v[166:169], v211 offset:5120
	ds_read_b128 v[184:187], v211 offset:7168
	global_load_lds_dwordx4 v190, s[22:23]
	s_add_i32 m0, s53, 0xe000
	s_nop 0
	global_load_lds_dwordx4 v192, s[22:23]
	s_waitcnt lgkmcnt(8)
	s_barrier
	s_waitcnt lgkmcnt(4)
	v_mfma_f32_16x16x32_bf16 v[142:145], v[70:73], v[146:149], v[142:145]
	v_mfma_f32_16x16x32_bf16 v[138:141], v[82:85], v[146:149], v[138:141]
	v_mfma_f32_16x16x32_bf16 v[126:129], v[70:73], v[154:157], v[126:129]
	v_mfma_f32_16x16x32_bf16 v[122:125], v[82:85], v[154:157], v[122:125]
	v_mfma_f32_16x16x32_bf16 v[110:113], v[70:73], v[162:165], v[110:113]
	v_mfma_f32_16x16x32_bf16 v[106:109], v[82:85], v[162:165], v[106:109]
	v_mfma_f32_16x16x32_bf16 v[94:97], v[70:73], v[170:173], v[94:97]
	v_mfma_f32_16x16x32_bf16 v[90:93], v[82:85], v[170:173], v[90:93]
	s_waitcnt lgkmcnt(0)
	v_mfma_f32_16x16x32_bf16 v[142:145], v[74:77], v[150:153], v[142:145]
	v_mfma_f32_16x16x32_bf16 v[138:141], v[86:89], v[150:153], v[138:141]
	v_mfma_f32_16x16x32_bf16 v[126:129], v[74:77], v[158:161], v[126:129]
	v_mfma_f32_16x16x32_bf16 v[122:125], v[86:89], v[158:161], v[122:125]
	v_mfma_f32_16x16x32_bf16 v[110:113], v[74:77], v[166:169], v[110:113]
	v_mfma_f32_16x16x32_bf16 v[106:109], v[86:89], v[166:169], v[106:109]
	v_mfma_f32_16x16x32_bf16 v[94:97], v[74:77], v[184:187], v[94:97]
	v_mfma_f32_16x16x32_bf16 v[90:93], v[86:89], v[184:187], v[90:93]
	s_barrier
	s_add_i32 s66, 0, 0x14000
	s_add_i32 s22, s65, s52
	ds_read_b128 v[194:197], v250 offset:16384
	ds_read_b128 v[202:205], v250 offset:18432
	ds_read_b128 v[198:201], v250 offset:17408
	ds_read_b128 v[212:215], v250 offset:19456
	s_add_u32 s100, s36, s6
	s_addc_u32 s101, s37, s7
	s_mov_b32 m0, s22
	s_nop 0
	global_load_lds_dwordx4 v0, s[36:37]
	s_add_i32 m0, s22, 0x2000
	s_nop 0
	global_load_lds_dwordx4 v174, s[36:37]
	s_barrier
	s_waitcnt lgkmcnt(2)
	v_mfma_f32_16x16x32_bf16 v[134:137], v[194:197], v[146:149], v[134:137]
	v_mfma_f32_16x16x32_bf16 v[130:133], v[202:205], v[146:149], v[130:133]
	v_mfma_f32_16x16x32_bf16 v[118:121], v[194:197], v[154:157], v[118:121]
	v_mfma_f32_16x16x32_bf16 v[114:117], v[202:205], v[154:157], v[114:117]
	v_mfma_f32_16x16x32_bf16 v[102:105], v[194:197], v[162:165], v[102:105]
	v_mfma_f32_16x16x32_bf16 v[98:101], v[202:205], v[162:165], v[98:101]
	v_mfma_f32_16x16x32_bf16 v[78:81], v[194:197], v[170:173], v[78:81]
	v_mfma_f32_16x16x32_bf16 v[66:69], v[202:205], v[170:173], v[66:69]
	s_waitcnt lgkmcnt(0)
	v_mfma_f32_16x16x32_bf16 v[134:137], v[198:201], v[150:153], v[134:137]
	v_mfma_f32_16x16x32_bf16 v[130:133], v[212:215], v[150:153], v[130:133]
	v_mfma_f32_16x16x32_bf16 v[118:121], v[198:201], v[158:161], v[118:121]
	v_mfma_f32_16x16x32_bf16 v[114:117], v[212:215], v[158:161], v[114:117]
	v_mfma_f32_16x16x32_bf16 v[102:105], v[198:201], v[166:169], v[102:105]
	v_mfma_f32_16x16x32_bf16 v[98:101], v[212:215], v[166:169], v[98:101]
	v_mfma_f32_16x16x32_bf16 v[78:81], v[198:201], v[184:187], v[78:81]
	v_mfma_f32_16x16x32_bf16 v[66:69], v[212:215], v[184:187], v[66:69]
	s_mov_b32 m0, s53
	s_add_u32 vcc_lo, s24, s6
	s_addc_u32 vcc_hi, s25, s7
	s_barrier
	ds_read_b128 v[146:149], v211 offset:16384
	ds_read_b128 v[154:157], v211 offset:18432
	ds_read_b128 v[162:165], v211 offset:20480
	ds_read_b128 v[170:173], v211 offset:22528
	ds_read_b128 v[150:153], v211 offset:17408
	ds_read_b128 v[158:161], v211 offset:19456
	ds_read_b128 v[166:169], v211 offset:21504
	ds_read_b128 v[184:187], v211 offset:23552
	global_load_lds_dwordx4 v188, s[24:25]
	s_mov_b32 m0, s54
	s_nop 0
	global_load_lds_dwordx4 v176, s[24:25]
	s_barrier
	s_waitcnt lgkmcnt(4)
	v_mfma_f32_16x16x32_bf16 v[62:65], v[70:73], v[146:149], v[62:65]
	v_mfma_f32_16x16x32_bf16 v[58:61], v[82:85], v[146:149], v[58:61]
	v_mfma_f32_16x16x32_bf16 v[46:49], v[70:73], v[154:157], v[46:49]
	v_mfma_f32_16x16x32_bf16 v[42:45], v[82:85], v[154:157], v[42:45]
	v_mfma_f32_16x16x32_bf16 v[30:33], v[70:73], v[162:165], v[30:33]
	v_mfma_f32_16x16x32_bf16 v[26:29], v[82:85], v[162:165], v[26:29]
	v_mfma_f32_16x16x32_bf16 v[14:17], v[70:73], v[170:173], v[14:17]
	v_mfma_f32_16x16x32_bf16 v[10:13], v[82:85], v[170:173], v[10:13]
	s_waitcnt lgkmcnt(0)
	v_mfma_f32_16x16x32_bf16 v[62:65], v[74:77], v[150:153], v[62:65]
	v_mfma_f32_16x16x32_bf16 v[58:61], v[86:89], v[150:153], v[58:61]
	v_mfma_f32_16x16x32_bf16 v[46:49], v[74:77], v[158:161], v[46:49]
	v_mfma_f32_16x16x32_bf16 v[42:45], v[86:89], v[158:161], v[42:45]
	v_mfma_f32_16x16x32_bf16 v[30:33], v[74:77], v[166:169], v[30:33]
	v_mfma_f32_16x16x32_bf16 v[26:29], v[86:89], v[166:169], v[26:29]
	v_mfma_f32_16x16x32_bf16 v[14:17], v[74:77], v[184:187], v[14:17]
	v_mfma_f32_16x16x32_bf16 v[10:13], v[86:89], v[184:187], v[10:13]
	s_barrier
	s_add_u32 s22, s36, 0x100000
	s_addc_u32 s23, s37, 0
	s_add_i32 s65, s66, s52
	s_mov_b32 m0, s65
	s_nop 0
	global_load_lds_dwordx4 v0, s[22:23]
	s_add_i32 m0, s65, 0x2000
	s_nop 0
	global_load_lds_dwordx4 v174, s[22:23]
	s_waitcnt vmcnt(6)
	s_barrier
; #define PG8_STAGE(bufoff, gbase, voff) do { _Pragma("unroll") for (int _i = 0; _i < 2; ++_i) \
;         __builtin_amdgcn_global_load_lds((const unsigned*)((const char*)(gbase) + (voff)[_i]), (LAS unsigned*)(lds + (bufoff) + ldsw + _i * 8192), 16, 0, 0); } while (0)
; #define PG8_LDA(dst, b, h) do { _Pragma("unroll") for (int m = 0; m < 4; ++m) _Pragma("unroll") for (int k = 0; k < 2; ++k) dst[m][k] = *(const LAS bf16x8*)(lds + PG8_SA(b, h) + aoff + m * 2048 + k * 1024); } while (0)
; #define PG8_LDB(dst, b, h) do { _Pragma("unroll") for (int n = 0; n < 2; ++n) _Pragma("unroll") for (int k = 0; k < 2; ++k) dst[n][k] = *(const LAS bf16x8*)(lds + PG8_SB(b, h) + boff + n * 2048 + k * 1024); } while (0)
; #define PG8_MMA(ai, bj, At, Bt) do { __builtin_amdgcn_s_setprio(1); _Pragma("unroll") for (int m = 0; m < 4; ++m) _Pragma("unroll") for (int n = 0; n < 2; ++n) _Pragma("unroll") for (int k = 0; k < 2; ++k) \
;         acc[ai][bj][m][n] = __builtin_amdgcn_mfma_f32_16x16x32_bf16(Bt[n][k], At[m][k], acc[ai][bj][m][n], 0, 0, 0); __builtin_amdgcn_s_setprio(0); } while (0)
; #define PG8_WAIT_V(n) asm volatile("s_waitcnt vmcnt(" #n ")" ::: "memory")
; #define PG8_WAIT_L(n) asm volatile("s_waitcnt lgkmcnt(" #n ")" ::: "memory")
; #define PG8_BAR __builtin_amdgcn_s_barrier()
; #define PG8_SCHED __builtin_amdgcn_sched_barrier(0)
; template <class Epi>
; __device__ __forceinline__ void gemm_phase(LAS unsigned char* lds, const Gemm g, const StaticOrder& S, const Epi& E) {
;     ...
;             PG8_WAIT_V(6); PG8_BAR; PG8_MMA(1, 1, At, B1); PG8_BAR;
;             PG8_LDB(B0, 1, 0); PG8_SCHED; PG8_LDA(At, 1, 0); PG8_STAGE(PG8_SA(0, 1), a2 + hstepA, voffA);
;             PG8_WAIT_L(8); PG8_BAR; PG8_WAIT_L(0); PG8_MMA(0, 0, At, B0); PG8_BAR; PG8_SCHED;
;             PG8_LDB(B1, 1, 1); PG8_STAGE(PG8_SB(1, 0), b3, voffB);
;             PG8_BAR; PG8_WAIT_L(0); PG8_MMA(0, 1, At, B1); PG8_BAR;
;             PG8_LDA(At, 1, 1); PG8_STAGE(PG8_SA(1, 0), a3, voffA);
	v_mfma_f32_16x16x32_bf16 v[54:57], v[194:197], v[146:149], v[54:57]
	v_mfma_f32_16x16x32_bf16 v[50:53], v[202:205], v[146:149], v[50:53]
	v_mfma_f32_16x16x32_bf16 v[38:41], v[194:197], v[154:157], v[38:41]
	v_mfma_f32_16x16x32_bf16 v[34:37], v[202:205], v[154:157], v[34:37]
	v_mfma_f32_16x16x32_bf16 v[22:25], v[194:197], v[162:165], v[22:25]
	v_mfma_f32_16x16x32_bf16 v[18:21], v[202:205], v[162:165], v[18:21]
	v_mfma_f32_16x16x32_bf16 v[6:9], v[194:197], v[170:173], v[6:9]
	v_mfma_f32_16x16x32_bf16 v[2:5], v[202:205], v[170:173], v[2:5]
	v_mfma_f32_16x16x32_bf16 v[54:57], v[198:201], v[150:153], v[54:57]
	v_mfma_f32_16x16x32_bf16 v[50:53], v[212:215], v[150:153], v[50:53]
	v_mfma_f32_16x16x32_bf16 v[38:41], v[198:201], v[158:161], v[38:41]
	v_mfma_f32_16x16x32_bf16 v[34:37], v[212:215], v[158:161], v[34:37]
	v_mfma_f32_16x16x32_bf16 v[22:25], v[198:201], v[166:169], v[22:25]
	v_mfma_f32_16x16x32_bf16 v[18:21], v[212:215], v[166:169], v[18:21]
	v_mfma_f32_16x16x32_bf16 v[6:9], v[198:201], v[184:187], v[6:9]
	v_mfma_f32_16x16x32_bf16 v[2:5], v[212:215], v[184:187], v[2:5]
	s_add_i32 s65, 0, 0x18000
	s_barrier
	ds_read_b128 v[70:73], v250 offset:32768
	ds_read_b128 v[74:77], v250 offset:33792
	ds_read_b128 v[82:85], v250 offset:34816
	ds_read_b128 v[86:89], v250 offset:35840
	s_add_u32 s22, s24, 0x100000
	s_addc_u32 s23, s25, 0
	s_mov_b32 m0, s55
	ds_read_b128 v[146:149], v211 offset:32768
	ds_read_b128 v[154:157], v211 offset:34816
	ds_read_b128 v[162:165], v211 offset:36864
	ds_read_b128 v[170:173], v211 offset:38912
	ds_read_b128 v[150:153], v211 offset:33792
	ds_read_b128 v[158:161], v211 offset:35840
	ds_read_b128 v[166:169], v211 offset:37888
	ds_read_b128 v[184:187], v211 offset:39936
	global_load_lds_dwordx4 v188, s[22:23]
	s_mov_b32 m0, s56
	s_nop 0
	global_load_lds_dwordx4 v176, s[22:23]
	s_waitcnt lgkmcnt(8)
	s_barrier
	s_waitcnt lgkmcnt(4)
	v_mfma_f32_16x16x32_bf16 v[142:145], v[70:73], v[146:149], v[142:145]
	v_mfma_f32_16x16x32_bf16 v[138:141], v[82:85], v[146:149], v[138:141]
	v_mfma_f32_16x16x32_bf16 v[126:129], v[70:73], v[154:157], v[126:129]
	v_mfma_f32_16x16x32_bf16 v[122:125], v[82:85], v[154:157], v[122:125]
	v_mfma_f32_16x16x32_bf16 v[110:113], v[70:73], v[162:165], v[110:113]
	v_mfma_f32_16x16x32_bf16 v[106:109], v[82:85], v[162:165], v[106:109]
	v_mfma_f32_16x16x32_bf16 v[94:97], v[70:73], v[170:173], v[94:97]
	v_mfma_f32_16x16x32_bf16 v[90:93], v[82:85], v[170:173], v[90:93]
	s_waitcnt lgkmcnt(0)
	v_mfma_f32_16x16x32_bf16 v[142:145], v[74:77], v[150:153], v[142:145]
	v_mfma_f32_16x16x32_bf16 v[138:141], v[86:89], v[150:153], v[138:141]
	v_mfma_f32_16x16x32_bf16 v[126:129], v[74:77], v[158:161], v[126:129]
	v_mfma_f32_16x16x32_bf16 v[122:125], v[86:89], v[158:161], v[122:125]
	v_mfma_f32_16x16x32_bf16 v[110:113], v[74:77], v[166:169], v[110:113]
	v_mfma_f32_16x16x32_bf16 v[106:109], v[86:89], v[166:169], v[106:109]
	v_mfma_f32_16x16x32_bf16 v[94:97], v[74:77], v[184:187], v[94:97]
	v_mfma_f32_16x16x32_bf16 v[90:93], v[86:89], v[184:187], v[90:93]
	s_barrier
	s_add_i32 s24, 0, 0x1c000
	s_add_i32 s22, s65, s52
	s_mov_b32 m0, s22
	ds_read_b128 v[194:197], v250 offset:49152
	ds_read_b128 v[202:205], v250 offset:51200
	ds_read_b128 v[198:201], v250 offset:50176
	ds_read_b128 v[212:215], v250 offset:52224
	global_load_lds_dwordx4 v0, s[100:101]
	s_add_i32 m0, s22, 0x2000
	s_nop 0
	global_load_lds_dwordx4 v174, s[100:101]
	s_barrier
	s_waitcnt lgkmcnt(2)
	v_mfma_f32_16x16x32_bf16 v[134:137], v[194:197], v[146:149], v[134:137]
	v_mfma_f32_16x16x32_bf16 v[130:133], v[202:205], v[146:149], v[130:133]
	v_mfma_f32_16x16x32_bf16 v[118:121], v[194:197], v[154:157], v[118:121]
	v_mfma_f32_16x16x32_bf16 v[114:117], v[202:205], v[154:157], v[114:117]
	v_mfma_f32_16x16x32_bf16 v[102:105], v[194:197], v[162:165], v[102:105]
	v_mfma_f32_16x16x32_bf16 v[98:101], v[202:205], v[162:165], v[98:101]
	v_mfma_f32_16x16x32_bf16 v[78:81], v[194:197], v[170:173], v[78:81]
	v_mfma_f32_16x16x32_bf16 v[66:69], v[202:205], v[170:173], v[66:69]
	s_waitcnt lgkmcnt(0)
	v_mfma_f32_16x16x32_bf16 v[134:137], v[198:201], v[150:153], v[134:137]
	v_mfma_f32_16x16x32_bf16 v[130:133], v[212:215], v[150:153], v[130:133]
	v_mfma_f32_16x16x32_bf16 v[118:121], v[198:201], v[158:161], v[118:121]
	v_mfma_f32_16x16x32_bf16 v[114:117], v[212:215], v[158:161], v[114:117]
	v_mfma_f32_16x16x32_bf16 v[102:105], v[198:201], v[166:169], v[102:105]
	v_mfma_f32_16x16x32_bf16 v[98:101], v[212:215], v[166:169], v[98:101]
	v_mfma_f32_16x16x32_bf16 v[78:81], v[198:201], v[184:187], v[78:81]
	v_mfma_f32_16x16x32_bf16 v[66:69], v[212:215], v[184:187], v[66:69]
	s_mov_b32 m0, s58
	s_barrier
	ds_read_b128 v[146:149], v211 offset:49152
	ds_read_b128 v[154:157], v211 offset:51200
	ds_read_b128 v[162:165], v211 offset:53248
	ds_read_b128 v[170:173], v211 offset:55296
	ds_read_b128 v[150:153], v211 offset:50176
	ds_read_b128 v[158:161], v211 offset:52224
	ds_read_b128 v[166:169], v211 offset:54272
	ds_read_b128 v[184:187], v211 offset:56320
	global_load_lds_dwordx4 v188, vcc
	s_mov_b32 m0, s59
	s_nop 0
	global_load_lds_dwordx4 v176, vcc
	s_barrier
; __device__ __forceinline__ unsigned cvt_pk_bf16(float lo, float hi) { unsigned r; asm volatile("v_cvt_pk_bf16_f32 %0, %1, %2" : "=v"(r) : "v"(lo), "v"(hi)); return r; }
; #define PG8_WAIT_V(n) asm volatile("s_waitcnt vmcnt(" #n ")" ::: "memory")
; template <class Epi>
; __device__ __forceinline__ void gemm_phase(LAS unsigned char* lds, const Gemm g, const StaticOrder& S, const Epi& E) {
;     ...
;             PG8_BAR; PG8_WAIT_L(0); PG8_MMA(1, 0, At, B0); PG8_BAR; PG8_SCHED;
;             PG8_STAGE(PG8_SB(1, 1), b3 + hstepB, voffB);
;             PG8_WAIT_V(6); PG8_BAR; PG8_MMA(1, 1, At, B1); PG8_BAR;
;     __device__ __forceinline__ void operator()(const f32x4 (&acc)[2][2][4][2], const Unit& u, int wr, int wc, int fr, int fq, const Pre&) const {
;         const int row0 = u.pm * BM + wr * 64 + fr, col0 = u.pn * BM + wc * 32 + 4 * fq;
;         f32x4 gv[2][2];
; #pragma unroll
;         for (int bj = 0; bj < 2; ++bj)
; #pragma unroll
;             for (int n = 0; n < 2; ++n) gv[bj][n] = *(const f32x4*)(gnext + col0 + bj * HALF + n * 16);
;         f32x4 xb[2][2][2];
; #pragma unroll
;         for (int bj = 0; bj < 2; ++bj)
; #pragma unroll
;             for (int n = 0; n < 2; ++n) xb[0][bj][n] = *(const f32x4*)(Xin + (size_t)row0 * DM + col0 + bj * HALF + n * 16);
; #pragma unroll
;         for (int grp = 0; grp < 8; ++grp) { const int ai = grp >> 2, m = grp & 3, cur = grp & 1; const int r = row0 + ai * HALF + m * 16; float ss = 0.f;
;             if (grp < 7) { const int rn = row0 + ((grp + 1) >> 2) * HALF + ((grp + 1) & 3) * 16;
; #pragma unroll
;                 for (int bj = 0; bj < 2; ++bj)
; #pragma unroll
;                     for (int n = 0; n < 2; ++n) xb[cur ^ 1][bj][n] = *(const f32x4*)(Xin + (size_t)rn * DM + col0 + bj * HALF + n * 16); }
; #pragma unroll
;             for (int bj = 0; bj < 2; ++bj)
; #pragma unroll
;                 for (int n = 0; n < 2; ++n) { const int c = col0 + bj * HALF + n * 16;
;                     const f32x4 xv = xb[cur][bj][n] + acc[ai][bj][m][n]; *(f32x4*)(X + (size_t)r * DM + c) = xv;
;                     ss += (xv[0] * xv[0] + xv[1] * xv[1]) + (xv[2] * xv[2] + xv[3] * xv[3]);
;                     if (H) { const f32x4 hv = xv * gv[bj][n]; u32x2 w; w.x = cvt_pk_bf16(hv[0], hv[1]); w.y = cvt_pk_bf16(hv[2], hv[3]);
;                         *(u32x2*)(H + (size_t)r * DM + c) = w; } }
	s_waitcnt lgkmcnt(4)
	v_mfma_f32_16x16x32_bf16 v[62:65], v[70:73], v[146:149], v[62:65]
	v_mfma_f32_16x16x32_bf16 v[58:61], v[82:85], v[146:149], v[58:61]
	v_mfma_f32_16x16x32_bf16 v[46:49], v[70:73], v[154:157], v[46:49]
	v_mfma_f32_16x16x32_bf16 v[42:45], v[82:85], v[154:157], v[42:45]
	v_mfma_f32_16x16x32_bf16 v[30:33], v[70:73], v[162:165], v[30:33]
	v_mfma_f32_16x16x32_bf16 v[26:29], v[82:85], v[162:165], v[26:29]
	v_mfma_f32_16x16x32_bf16 v[14:17], v[70:73], v[170:173], v[14:17]
	v_mfma_f32_16x16x32_bf16 v[10:13], v[82:85], v[170:173], v[10:13]
	s_waitcnt lgkmcnt(0)
	v_mfma_f32_16x16x32_bf16 v[62:65], v[74:77], v[150:153], v[62:65]
	v_mfma_f32_16x16x32_bf16 v[58:61], v[86:89], v[150:153], v[58:61]
	v_mfma_f32_16x16x32_bf16 v[46:49], v[74:77], v[158:161], v[46:49]
	v_mfma_f32_16x16x32_bf16 v[42:45], v[86:89], v[158:161], v[42:45]
	v_mfma_f32_16x16x32_bf16 v[30:33], v[74:77], v[166:169], v[30:33]
	v_mfma_f32_16x16x32_bf16 v[26:29], v[86:89], v[166:169], v[26:29]
	v_mfma_f32_16x16x32_bf16 v[14:17], v[74:77], v[184:187], v[14:17]
	v_mfma_f32_16x16x32_bf16 v[10:13], v[86:89], v[184:187], v[10:13]
	s_barrier
	s_add_u32 s22, s36, 0x100080
	s_addc_u32 s23, s37, 0
	s_add_i32 s24, s24, s52
	s_mov_b32 m0, s24
	s_nop 0
	global_load_lds_dwordx4 v0, s[22:23]
	s_add_i32 m0, s24, 0x2000
	s_nop 0
	global_load_lds_dwordx4 v174, s[22:23]
	s_waitcnt vmcnt(6)
	s_barrier
	v_mfma_f32_16x16x32_bf16 v[54:57], v[194:197], v[146:149], v[54:57]
	v_mfma_f32_16x16x32_bf16 v[50:53], v[202:205], v[146:149], v[50:53]
	v_mfma_f32_16x16x32_bf16 v[38:41], v[194:197], v[154:157], v[38:41]
	v_mfma_f32_16x16x32_bf16 v[34:37], v[202:205], v[154:157], v[34:37]
	v_mfma_f32_16x16x32_bf16 v[22:25], v[194:197], v[162:165], v[22:25]
	v_mfma_f32_16x16x32_bf16 v[18:21], v[202:205], v[162:165], v[18:21]
	v_mfma_f32_16x16x32_bf16 v[6:9], v[194:197], v[170:173], v[6:9]
	v_mfma_f32_16x16x32_bf16 v[2:5], v[202:205], v[170:173], v[2:5]
	v_mfma_f32_16x16x32_bf16 v[54:57], v[198:201], v[150:153], v[54:57]
	v_mfma_f32_16x16x32_bf16 v[50:53], v[212:215], v[150:153], v[50:53]
	v_mfma_f32_16x16x32_bf16 v[38:41], v[198:201], v[158:161], v[38:41]
	v_mfma_f32_16x16x32_bf16 v[34:37], v[212:215], v[158:161], v[34:37]
	v_mfma_f32_16x16x32_bf16 v[22:25], v[198:201], v[166:169], v[22:25]
	v_mfma_f32_16x16x32_bf16 v[18:21], v[212:215], v[166:169], v[18:21]
	v_mfma_f32_16x16x32_bf16 v[6:9], v[198:201], v[184:187], v[6:9]
	v_mfma_f32_16x16x32_bf16 v[2:5], v[212:215], v[184:187], v[2:5]
	s_add_i32 s64, s64, 2
	s_add_u32 s62, s62, 0x100
	s_addc_u32 s63, s63, 0
	s_cmp_gt_u32 s64, 61
	s_mov_b64 s[22:23], s[26:27]
	s_barrier
	s_cbranch_scc0 .LBB0_359
	v_lshl_add_u32 v198, s44, 8, v208
	v_lshl_or_b32 v194, s45, 8, v210
	v_ashrrev_i32_e32 v199, 31, v198
	v_ashrrev_i32_e32 v195, 31, v194
	v_lshlrev_b64 v[204:205], 13, v[198:199]
	v_or_b32_e32 v202, 16, v198
	v_lshlrev_b64 v[196:197], 2, v[194:195]
	v_lshl_add_u64 v[146:147], s[0:1], 0, v[204:205]
	v_ashrrev_i32_e32 v203, 31, v202
	v_lshl_add_u64 v[70:71], s[4:5], 0, v[196:197]
	v_lshl_add_u64 v[146:147], v[146:147], 0, v[196:197]
	v_lshlrev_b64 v[200:201], 13, v[202:203]
	global_load_dwordx4 v[86:89], v[70:71], off
	global_load_dwordx4 v[82:85], v[70:71], off offset:64
	global_load_dwordx4 v[74:77], v[70:71], off offset:512
	s_nop 0
	global_load_dwordx4 v[70:73], v[70:71], off offset:576
	s_nop 0
	global_load_dwordx4 v[184:187], v[146:147], off
	global_load_dwordx4 v[170:173], v[146:147], off offset:64
	global_load_dwordx4 v[166:169], v[146:147], off offset:512
	global_load_dwordx4 v[162:165], v[146:147], off offset:576
	v_lshl_add_u64 v[146:147], s[0:1], 0, v[200:201]
	v_lshl_add_u64 v[146:147], v[146:147], 0, v[196:197]
	global_load_dwordx4 v[158:161], v[146:147], off
	global_load_dwordx4 v[154:157], v[146:147], off offset:64
	global_load_dwordx4 v[150:153], v[146:147], off offset:512
	s_nop 0
	global_load_dwordx4 v[146:149], v[146:147], off offset:576
	v_cndmask_b32_e64 v206, 0, 1, s[10:11]
	v_lshlrev_b64 v[212:213], 11, v[198:199]
	v_lshl_add_u64 v[204:205], s[48:49], 0, v[204:205]
	v_cmp_ne_u32_e64 s[44:45], 1, v206
	s_andn2_b64 vcc, exec, s[10:11]
	v_lshl_add_u64 v[206:207], v[204:205], 0, v[196:197]
	v_lshl_add_u64 v[204:205], v[212:213], 1, s[50:51]
	s_waitcnt vmcnt(0)
	v_pk_add_f32 v[144:145], v[144:145], v[186:187]
	v_pk_add_f32 v[142:143], v[142:143], v[184:185]
	global_store_dwordx4 v[206:207], v[142:145], off
	s_cbranch_vccnz .LBB0_362
	v_pk_mul_f32 v[184:185], v[88:89], v[144:145]
	v_pk_mul_f32 v[186:187], v[86:87], v[142:143]
	s_nop 0
	v_cvt_pk_bf16_f32 v186, v186, v187
	v_cvt_pk_bf16_f32 v187, v184, v185
	v_lshl_add_u64 v[184:185], v[194:195], 1, v[204:205]
	global_store_dwordx2 v[184:185], v[186:187], off

; #define PG8_STAGE(bufoff, gbase, voff) do { _Pragma("unroll") for (int _i = 0; _i < 2; ++_i) \
;         __builtin_amdgcn_global_load_lds((const unsigned*)((const char*)(gbase) + (voff)[_i]), (LAS unsigned*)(lds + (bufoff) + ldsw + _i * 8192), 16, 0, 0); } while (0)
; #define PG8_LDA(dst, b, h) do { _Pragma("unroll") for (int m = 0; m < 4; ++m) _Pragma("unroll") for (int k = 0; k < 2; ++k) dst[m][k] = *(const LAS bf16x8*)(lds + PG8_SA(b, h) + aoff + m * 2048 + k * 1024); } while (0)
; #define PG8_LDB(dst, b, h) do { _Pragma("unroll") for (int n = 0; n < 2; ++n) _Pragma("unroll") for (int k = 0; k < 2; ++k) dst[n][k] = *(const LAS bf16x8*)(lds + PG8_SB(b, h) + boff + n * 2048 + k * 1024); } while (0)
; #define PG8_MMA(ai, bj, At, Bt) do { __builtin_amdgcn_s_setprio(1); _Pragma("unroll") for (int m = 0; m < 4; ++m) _Pragma("unroll") for (int n = 0; n < 2; ++n) _Pragma("unroll") for (int k = 0; k < 2; ++k) \
;         acc[ai][bj][m][n] = __builtin_amdgcn_mfma_f32_16x16x32_bf16(Bt[n][k], At[m][k], acc[ai][bj][m][n], 0, 0, 0); __builtin_amdgcn_s_setprio(0); } while (0)
; #define PG8_WAIT_V(n) asm volatile("s_waitcnt vmcnt(" #n ")" ::: "memory")
; #define PG8_WAIT_L(n) asm volatile("s_waitcnt lgkmcnt(" #n ")" ::: "memory")
; #define PG8_BAR __builtin_amdgcn_s_barrier()
; #define PG8_SCHED __builtin_amdgcn_sched_barrier(0)
; template <class Epi>
; __device__ __forceinline__ void gemm_phase(LAS unsigned char* lds, const Gemm g, const StaticOrder& S, const Epi& E) {
;     ...
;             PG8_LDB(B0, 0, 0); PG8_SCHED; PG8_LDA(At, 0, 0); PG8_STAGE(PG8_SA(1, 1), a1 + hstepA, voffA);
;             PG8_WAIT_L(8); PG8_BAR; PG8_WAIT_L(0); PG8_MMA(0, 0, At, B0); PG8_BAR; PG8_SCHED;
;             PG8_LDB(B1, 0, 1); PG8_STAGE(PG8_SB(0, 0), b2, voffB);
;             PG8_BAR; PG8_WAIT_L(0); PG8_MMA(0, 1, At, B1); PG8_BAR;
;             PG8_LDA(At, 0, 1); PG8_STAGE(PG8_SA(0, 0), a2, voffA);
;             PG8_BAR; PG8_WAIT_L(0); PG8_MMA(1, 0, At, B0); PG8_BAR; PG8_SCHED;
;             PG8_STAGE(PG8_SB(0, 1), b2 + hstepB, voffB);
;             PG8_WAIT_V(6); PG8_BAR; PG8_MMA(1, 1, At, B1); PG8_BAR;
;             PG8_LDB(B0, 1, 0); PG8_SCHED; PG8_LDA(At, 1, 0); PG8_STAGE(PG8_SA(0, 1), a2 + hstepA, voffA);
;             PG8_WAIT_L(8); PG8_BAR; PG8_WAIT_L(0); PG8_MMA(0, 0, At, B0); PG8_BAR; PG8_SCHED;
.LBB0_472:
	s_add_u32 s22, s4, s20
	s_addc_u32 s23, s5, s21
	s_add_u32 s22, s22, 0x100
	s_addc_u32 s23, s23, 0
	s_add_u32 s62, s17, s20
	s_addc_u32 s63, s58, s21
	s_add_i32 s64, 0, 0x10000
	ds_read_b128 v[148:151], v250
	ds_read_b128 v[152:155], v250 offset:1024
	ds_read_b128 v[156:159], v250 offset:2048
	ds_read_b128 v[160:163], v250 offset:3072
	s_cmpk_eq_i32 s20, 0x1f00
	s_cselect_b32 s25, s11, s23
	s_cselect_b32 s24, s59, s22
	s_cselect_b32 s23, s9, s63
	s_cselect_b32 s22, s60, s62
	v_lshl_add_u64 v[176:177], v[140:141], 0, s[20:21]
	s_add_i32 m0, s48, 0xc000
	ds_read_b128 v[164:167], v147
	ds_read_b128 v[172:175], v147 offset:2048
	ds_read_b128 v[188:191], v147 offset:4096
	ds_read_b128 v[196:199], v147 offset:6144
	ds_read_b128 v[168:171], v147 offset:1024
	ds_read_b128 v[184:187], v147 offset:3072
	ds_read_b128 v[192:195], v147 offset:5120
	ds_read_b128 v[200:203], v147 offset:7168
	global_load_lds_dwordx4 v[176:177], off
	v_lshl_add_u64 v[176:177], v[142:143], 0, s[20:21]
	s_add_i32 m0, s48, 0xe000
	s_nop 0
	global_load_lds_dwordx4 v[176:177], off
	s_waitcnt lgkmcnt(8)
	s_barrier
	s_waitcnt lgkmcnt(4)
	v_mfma_f32_16x16x32_bf16 v[126:129], v[148:151], v[164:167], v[126:129]
	v_mfma_f32_16x16x32_bf16 v[122:125], v[156:159], v[164:167], v[122:125]
	v_mfma_f32_16x16x32_bf16 v[110:113], v[148:151], v[172:175], v[110:113]
	v_mfma_f32_16x16x32_bf16 v[106:109], v[156:159], v[172:175], v[106:109]
	v_mfma_f32_16x16x32_bf16 v[94:97], v[148:151], v[188:191], v[94:97]
	v_mfma_f32_16x16x32_bf16 v[90:93], v[156:159], v[188:191], v[90:93]
	v_mfma_f32_16x16x32_bf16 v[78:81], v[148:151], v[196:199], v[78:81]
	v_mfma_f32_16x16x32_bf16 v[74:77], v[156:159], v[196:199], v[74:77]
	s_waitcnt lgkmcnt(0)
	v_mfma_f32_16x16x32_bf16 v[126:129], v[152:155], v[168:171], v[126:129]
	v_mfma_f32_16x16x32_bf16 v[122:125], v[160:163], v[168:171], v[122:125]
	v_mfma_f32_16x16x32_bf16 v[110:113], v[152:155], v[184:187], v[110:113]
	v_mfma_f32_16x16x32_bf16 v[106:109], v[160:163], v[184:187], v[106:109]
	v_mfma_f32_16x16x32_bf16 v[94:97], v[152:155], v[192:195], v[94:97]
	v_mfma_f32_16x16x32_bf16 v[90:93], v[160:163], v[192:195], v[90:93]
	v_mfma_f32_16x16x32_bf16 v[78:81], v[152:155], v[200:203], v[78:81]
	v_mfma_f32_16x16x32_bf16 v[74:77], v[160:163], v[200:203], v[74:77]
	s_barrier
	s_add_i32 s65, 0, 0x14000
	s_add_i32 s62, s64, s39
	ds_read_b128 v[204:207], v250 offset:16384
	ds_read_b128 v[212:215], v250 offset:18432
	ds_read_b128 v[208:211], v250 offset:17408
	ds_read_b128 v[216:219], v250 offset:19456
	s_add_u32 s100, s22, s6
	s_addc_u32 s101, s23, s7
	s_mov_b32 m0, s62
	s_nop 0
	global_load_lds_dwordx4 v0, s[22:23]
	s_add_i32 m0, s62, 0x2000
	s_nop 0
	global_load_lds_dwordx4 v130, s[22:23]
	s_barrier
	s_waitcnt lgkmcnt(2)
	v_mfma_f32_16x16x32_bf16 v[118:121], v[204:207], v[164:167], v[118:121]
	v_mfma_f32_16x16x32_bf16 v[114:117], v[212:215], v[164:167], v[114:117]
	v_mfma_f32_16x16x32_bf16 v[102:105], v[204:207], v[172:175], v[102:105]
	v_mfma_f32_16x16x32_bf16 v[98:101], v[212:215], v[172:175], v[98:101]
	v_mfma_f32_16x16x32_bf16 v[86:89], v[204:207], v[188:191], v[86:89]
	v_mfma_f32_16x16x32_bf16 v[82:85], v[212:215], v[188:191], v[82:85]
	v_mfma_f32_16x16x32_bf16 v[70:73], v[204:207], v[196:199], v[70:73]
	v_mfma_f32_16x16x32_bf16 v[66:69], v[212:215], v[196:199], v[66:69]
	s_waitcnt lgkmcnt(0)
	v_mfma_f32_16x16x32_bf16 v[118:121], v[208:211], v[168:171], v[118:121]
	v_mfma_f32_16x16x32_bf16 v[114:117], v[216:219], v[168:171], v[114:117]
	v_mfma_f32_16x16x32_bf16 v[102:105], v[208:211], v[184:187], v[102:105]
	v_mfma_f32_16x16x32_bf16 v[98:101], v[216:219], v[184:187], v[98:101]
	v_mfma_f32_16x16x32_bf16 v[86:89], v[208:211], v[192:195], v[86:89]
	v_mfma_f32_16x16x32_bf16 v[82:85], v[216:219], v[192:195], v[82:85]
	v_mfma_f32_16x16x32_bf16 v[70:73], v[208:211], v[200:203], v[70:73]
	v_mfma_f32_16x16x32_bf16 v[66:69], v[216:219], v[200:203], v[66:69]
	s_mov_b32 m0, s48
	s_add_u32 vcc_lo, s24, s6
	s_addc_u32 vcc_hi, s25, s7
	s_barrier
	ds_read_b128 v[164:167], v147 offset:16384
	ds_read_b128 v[172:175], v147 offset:18432
	ds_read_b128 v[188:191], v147 offset:20480
	ds_read_b128 v[196:199], v147 offset:22528
	ds_read_b128 v[168:171], v147 offset:17408
	ds_read_b128 v[184:187], v147 offset:19456
	ds_read_b128 v[192:195], v147 offset:21504
	ds_read_b128 v[200:203], v147 offset:23552
	global_load_lds_dwordx4 v134, s[24:25]
	s_mov_b32 m0, s49
	s_nop 0
	global_load_lds_dwordx4 v132, s[24:25]
	s_barrier
	s_waitcnt lgkmcnt(4)
	v_mfma_f32_16x16x32_bf16 v[62:65], v[148:151], v[164:167], v[62:65]
	v_mfma_f32_16x16x32_bf16 v[58:61], v[156:159], v[164:167], v[58:61]
	v_mfma_f32_16x16x32_bf16 v[46:49], v[148:151], v[172:175], v[46:49]
	v_mfma_f32_16x16x32_bf16 v[42:45], v[156:159], v[172:175], v[42:45]
	v_mfma_f32_16x16x32_bf16 v[30:33], v[148:151], v[188:191], v[30:33]
	v_mfma_f32_16x16x32_bf16 v[26:29], v[156:159], v[188:191], v[26:29]
	v_mfma_f32_16x16x32_bf16 v[18:21], v[148:151], v[196:199], v[18:21]
	v_mfma_f32_16x16x32_bf16 v[10:13], v[156:159], v[196:199], v[10:13]
	s_waitcnt lgkmcnt(0)
	v_mfma_f32_16x16x32_bf16 v[62:65], v[152:155], v[168:171], v[62:65]
	v_mfma_f32_16x16x32_bf16 v[58:61], v[160:163], v[168:171], v[58:61]
	v_mfma_f32_16x16x32_bf16 v[46:49], v[152:155], v[184:187], v[46:49]
	v_mfma_f32_16x16x32_bf16 v[42:45], v[160:163], v[184:187], v[42:45]
	v_mfma_f32_16x16x32_bf16 v[30:33], v[152:155], v[192:195], v[30:33]
	v_mfma_f32_16x16x32_bf16 v[26:29], v[160:163], v[192:195], v[26:29]
	v_mfma_f32_16x16x32_bf16 v[18:21], v[152:155], v[200:203], v[18:21]
	v_mfma_f32_16x16x32_bf16 v[10:13], v[160:163], v[200:203], v[10:13]
	s_barrier
; #define PG8_STAGE(bufoff, gbase, voff) do { _Pragma("unroll") for (int _i = 0; _i < 2; ++_i) \
;         __builtin_amdgcn_global_load_lds((const unsigned*)((const char*)(gbase) + (voff)[_i]), (LAS unsigned*)(lds + (bufoff) + ldsw + _i * 8192), 16, 0, 0); } while (0)
; #define PG8_LDA(dst, b, h) do { _Pragma("unroll") for (int m = 0; m < 4; ++m) _Pragma("unroll") for (int k = 0; k < 2; ++k) dst[m][k] = *(const LAS bf16x8*)(lds + PG8_SA(b, h) + aoff + m * 2048 + k * 1024); } while (0)
; #define PG8_LDB(dst, b, h) do { _Pragma("unroll") for (int n = 0; n < 2; ++n) _Pragma("unroll") for (int k = 0; k < 2; ++k) dst[n][k] = *(const LAS bf16x8*)(lds + PG8_SB(b, h) + boff + n * 2048 + k * 1024); } while (0)
; #define PG8_MMA(ai, bj, At, Bt) do { __builtin_amdgcn_s_setprio(1); _Pragma("unroll") for (int m = 0; m < 4; ++m) _Pragma("unroll") for (int n = 0; n < 2; ++n) _Pragma("unroll") for (int k = 0; k < 2; ++k) \
;         acc[ai][bj][m][n] = __builtin_amdgcn_mfma_f32_16x16x32_bf16(Bt[n][k], At[m][k], acc[ai][bj][m][n], 0, 0, 0); __builtin_amdgcn_s_setprio(0); } while (0)
; #define PG8_WAIT_V(n) asm volatile("s_waitcnt vmcnt(" #n ")" ::: "memory")
; #define PG8_WAIT_L(n) asm volatile("s_waitcnt lgkmcnt(" #n ")" ::: "memory")
; #define PG8_BAR __builtin_amdgcn_s_barrier()
; #define PG8_SCHED __builtin_amdgcn_sched_barrier(0)
; template <class Epi>
; __device__ __forceinline__ void gemm_phase(LAS unsigned char* lds, const Gemm g, const StaticOrder& S, const Epi& E) {
;     ...
;             PG8_WAIT_V(6); PG8_BAR; PG8_MMA(1, 1, At, B1); PG8_BAR;
;             PG8_LDB(B0, 1, 0); PG8_SCHED; PG8_LDA(At, 1, 0); PG8_STAGE(PG8_SA(0, 1), a2 + hstepA, voffA);
;             PG8_WAIT_L(8); PG8_BAR; PG8_WAIT_L(0); PG8_MMA(0, 0, At, B0); PG8_BAR; PG8_SCHED;
;             PG8_LDB(B1, 1, 1); PG8_STAGE(PG8_SB(1, 0), b3, voffB);
;             PG8_BAR; PG8_WAIT_L(0); PG8_MMA(0, 1, At, B1); PG8_BAR;
;             PG8_LDA(At, 1, 1); PG8_STAGE(PG8_SA(1, 0), a3, voffA);
;             PG8_BAR; PG8_WAIT_L(0); PG8_MMA(1, 0, At, B0); PG8_BAR; PG8_SCHED;
	s_add_u32 s62, s22, 0x100000
	s_addc_u32 s63, s23, 0
	s_add_i32 s64, s65, s39
	s_mov_b32 m0, s64
	s_nop 0
	global_load_lds_dwordx4 v0, s[62:63]
	s_add_i32 m0, s64, 0x2000
	s_nop 0
	global_load_lds_dwordx4 v130, s[62:63]
	s_waitcnt vmcnt(6)
	s_barrier
	v_mfma_f32_16x16x32_bf16 v[54:57], v[204:207], v[164:167], v[54:57]
	v_mfma_f32_16x16x32_bf16 v[50:53], v[212:215], v[164:167], v[50:53]
	v_mfma_f32_16x16x32_bf16 v[38:41], v[204:207], v[172:175], v[38:41]
	v_mfma_f32_16x16x32_bf16 v[34:37], v[212:215], v[172:175], v[34:37]
	v_mfma_f32_16x16x32_bf16 v[22:25], v[204:207], v[188:191], v[22:25]
	v_mfma_f32_16x16x32_bf16 v[14:17], v[212:215], v[188:191], v[14:17]
	v_mfma_f32_16x16x32_bf16 v[6:9], v[204:207], v[196:199], v[6:9]
	v_mfma_f32_16x16x32_bf16 v[2:5], v[212:215], v[196:199], v[2:5]
	v_mfma_f32_16x16x32_bf16 v[54:57], v[208:211], v[168:171], v[54:57]
	v_mfma_f32_16x16x32_bf16 v[50:53], v[216:219], v[168:171], v[50:53]
	v_mfma_f32_16x16x32_bf16 v[38:41], v[208:211], v[184:187], v[38:41]
	v_mfma_f32_16x16x32_bf16 v[34:37], v[216:219], v[184:187], v[34:37]
	v_mfma_f32_16x16x32_bf16 v[22:25], v[208:211], v[192:195], v[22:25]
	v_mfma_f32_16x16x32_bf16 v[14:17], v[216:219], v[192:195], v[14:17]
	v_mfma_f32_16x16x32_bf16 v[6:9], v[208:211], v[200:203], v[6:9]
	v_mfma_f32_16x16x32_bf16 v[2:5], v[216:219], v[200:203], v[2:5]
	s_add_i32 s62, 0, 0x18000
	s_barrier
	ds_read_b128 v[148:151], v250 offset:32768
	ds_read_b128 v[152:155], v250 offset:33792
	ds_read_b128 v[156:159], v250 offset:34816
	ds_read_b128 v[160:163], v250 offset:35840
	s_add_u32 s24, s24, 0x100000
	s_addc_u32 s25, s25, 0
	s_mov_b32 m0, s50
	ds_read_b128 v[164:167], v147 offset:32768
	ds_read_b128 v[172:175], v147 offset:34816
	ds_read_b128 v[188:191], v147 offset:36864
	ds_read_b128 v[196:199], v147 offset:38912
	ds_read_b128 v[168:171], v147 offset:33792
	ds_read_b128 v[184:187], v147 offset:35840
	ds_read_b128 v[192:195], v147 offset:37888
	ds_read_b128 v[200:203], v147 offset:39936
	global_load_lds_dwordx4 v134, s[24:25]
	s_mov_b32 m0, s51
	s_nop 0
	global_load_lds_dwordx4 v132, s[24:25]
	s_waitcnt lgkmcnt(8)
	s_barrier
	s_waitcnt lgkmcnt(4)
	v_mfma_f32_16x16x32_bf16 v[126:129], v[148:151], v[164:167], v[126:129]
	v_mfma_f32_16x16x32_bf16 v[122:125], v[156:159], v[164:167], v[122:125]
	v_mfma_f32_16x16x32_bf16 v[110:113], v[148:151], v[172:175], v[110:113]
	v_mfma_f32_16x16x32_bf16 v[106:109], v[156:159], v[172:175], v[106:109]
	v_mfma_f32_16x16x32_bf16 v[94:97], v[148:151], v[188:191], v[94:97]
	v_mfma_f32_16x16x32_bf16 v[90:93], v[156:159], v[188:191], v[90:93]
	v_mfma_f32_16x16x32_bf16 v[78:81], v[148:151], v[196:199], v[78:81]
	v_mfma_f32_16x16x32_bf16 v[74:77], v[156:159], v[196:199], v[74:77]
	s_waitcnt lgkmcnt(0)
	v_mfma_f32_16x16x32_bf16 v[126:129], v[152:155], v[168:171], v[126:129]
	v_mfma_f32_16x16x32_bf16 v[122:125], v[160:163], v[168:171], v[122:125]
	v_mfma_f32_16x16x32_bf16 v[110:113], v[152:155], v[184:187], v[110:113]
	v_mfma_f32_16x16x32_bf16 v[106:109], v[160:163], v[184:187], v[106:109]
	v_mfma_f32_16x16x32_bf16 v[94:97], v[152:155], v[192:195], v[94:97]
	v_mfma_f32_16x16x32_bf16 v[90:93], v[160:163], v[192:195], v[90:93]
	v_mfma_f32_16x16x32_bf16 v[78:81], v[152:155], v[200:203], v[78:81]
	v_mfma_f32_16x16x32_bf16 v[74:77], v[160:163], v[200:203], v[74:77]
	s_barrier
	s_add_i32 s24, 0, 0x1c000
	s_add_i32 s25, s62, s39
	s_mov_b32 m0, s25
	ds_read_b128 v[204:207], v250 offset:49152
	ds_read_b128 v[212:215], v250 offset:51200
	ds_read_b128 v[208:211], v250 offset:50176
	ds_read_b128 v[216:219], v250 offset:52224
	global_load_lds_dwordx4 v0, s[100:101]
	s_add_i32 m0, s25, 0x2000
	s_nop 0
	global_load_lds_dwordx4 v130, s[100:101]
	s_barrier
	s_waitcnt lgkmcnt(2)
	v_mfma_f32_16x16x32_bf16 v[118:121], v[204:207], v[164:167], v[118:121]
	v_mfma_f32_16x16x32_bf16 v[114:117], v[212:215], v[164:167], v[114:117]
	v_mfma_f32_16x16x32_bf16 v[102:105], v[204:207], v[172:175], v[102:105]
	v_mfma_f32_16x16x32_bf16 v[98:101], v[212:215], v[172:175], v[98:101]
	v_mfma_f32_16x16x32_bf16 v[86:89], v[204:207], v[188:191], v[86:89]
	v_mfma_f32_16x16x32_bf16 v[82:85], v[212:215], v[188:191], v[82:85]
	v_mfma_f32_16x16x32_bf16 v[70:73], v[204:207], v[196:199], v[70:73]
	v_mfma_f32_16x16x32_bf16 v[66:69], v[212:215], v[196:199], v[66:69]
	s_waitcnt lgkmcnt(0)
	v_mfma_f32_16x16x32_bf16 v[118:121], v[208:211], v[168:171], v[118:121]
	v_mfma_f32_16x16x32_bf16 v[114:117], v[216:219], v[168:171], v[114:117]
	v_mfma_f32_16x16x32_bf16 v[102:105], v[208:211], v[184:187], v[102:105]
	v_mfma_f32_16x16x32_bf16 v[98:101], v[216:219], v[184:187], v[98:101]
	v_mfma_f32_16x16x32_bf16 v[86:89], v[208:211], v[192:195], v[86:89]
	v_mfma_f32_16x16x32_bf16 v[82:85], v[216:219], v[192:195], v[82:85]
	v_mfma_f32_16x16x32_bf16 v[70:73], v[208:211], v[200:203], v[70:73]
	v_mfma_f32_16x16x32_bf16 v[66:69], v[216:219], v[200:203], v[66:69]
	s_mov_b32 m0, s54
	s_barrier
	ds_read_b128 v[164:167], v147 offset:49152
	ds_read_b128 v[172:175], v147 offset:51200
	ds_read_b128 v[188:191], v147 offset:53248
	ds_read_b128 v[196:199], v147 offset:55296
	ds_read_b128 v[168:171], v147 offset:50176
	ds_read_b128 v[184:187], v147 offset:52224
	ds_read_b128 v[192:195], v147 offset:54272
	ds_read_b128 v[200:203], v147 offset:56320
	global_load_lds_dwordx4 v134, vcc
	s_mov_b32 m0, s55
	s_nop 0
	global_load_lds_dwordx4 v132, vcc
	s_barrier
; #define PG8_STAGE(bufoff, gbase, voff) do { _Pragma("unroll") for (int _i = 0; _i < 2; ++_i) \
;         __builtin_amdgcn_global_load_lds((const unsigned*)((const char*)(gbase) + (voff)[_i]), (LAS unsigned*)(lds + (bufoff) + ldsw + _i * 8192), 16, 0, 0); } while (0)
; #define PG8_MMA(ai, bj, At, Bt) do { __builtin_amdgcn_s_setprio(1); _Pragma("unroll") for (int m = 0; m < 4; ++m) _Pragma("unroll") for (int n = 0; n < 2; ++n) _Pragma("unroll") for (int k = 0; k < 2; ++k) \
;         acc[ai][bj][m][n] = __builtin_amdgcn_mfma_f32_16x16x32_bf16(Bt[n][k], At[m][k], acc[ai][bj][m][n], 0, 0, 0); __builtin_amdgcn_s_setprio(0); } while (0)
; #define PG8_WAIT_V(n) asm volatile("s_waitcnt vmcnt(" #n ")" ::: "memory")
; #define PG8_WAIT_L(n) asm volatile("s_waitcnt lgkmcnt(" #n ")" ::: "memory")
; #define PG8_BAR __builtin_amdgcn_s_barrier()
; #define PG8_SCHED __builtin_amdgcn_sched_barrier(0)
; template <class Epi>
; __device__ __forceinline__ void gemm_phase(LAS unsigned char* lds, const Gemm g, const StaticOrder& S, const Epi& E) {
;     ...
;             PG8_BAR; PG8_WAIT_L(0); PG8_MMA(1, 0, At, B0); PG8_BAR; PG8_SCHED;
;             PG8_STAGE(PG8_SB(1, 1), b3 + hstepB, voffB);
;             PG8_WAIT_V(6); PG8_BAR; PG8_MMA(1, 1, At, B1); PG8_BAR;
;         }
;         if constexpr (!Epi::AFTER_DRAIN) E(acc, cur, wr, wc, fr, fq, pre);
;         if (!has_next) break;
; #pragma unroll
;         for (int a = 0; a < 2; ++a)
; #pragma unroll
;             for (int b = 0; b < 2; ++b)
; #pragma unroll
;                 for (int m = 0; m < 4; ++m)
; #pragma unroll
;                     for (int n = 0; n < 2; ++n) acc[a][b][m][n] = (f32x4){0.f, 0.f, 0.f, 0.f};
;         cur = nxt; cA = nA; cB = nB; ++ui;
	s_waitcnt lgkmcnt(4)
	v_mfma_f32_16x16x32_bf16 v[62:65], v[148:151], v[164:167], v[62:65]
	v_mfma_f32_16x16x32_bf16 v[58:61], v[156:159], v[164:167], v[58:61]
	v_mfma_f32_16x16x32_bf16 v[46:49], v[148:151], v[172:175], v[46:49]
	v_mfma_f32_16x16x32_bf16 v[42:45], v[156:159], v[172:175], v[42:45]
	v_mfma_f32_16x16x32_bf16 v[30:33], v[148:151], v[188:191], v[30:33]
	v_mfma_f32_16x16x32_bf16 v[26:29], v[156:159], v[188:191], v[26:29]
	v_mfma_f32_16x16x32_bf16 v[18:21], v[148:151], v[196:199], v[18:21]
	v_mfma_f32_16x16x32_bf16 v[10:13], v[156:159], v[196:199], v[10:13]
	s_waitcnt lgkmcnt(0)
	v_mfma_f32_16x16x32_bf16 v[62:65], v[152:155], v[168:171], v[62:65]
	v_mfma_f32_16x16x32_bf16 v[58:61], v[160:163], v[168:171], v[58:61]
	v_mfma_f32_16x16x32_bf16 v[46:49], v[152:155], v[184:187], v[46:49]
	v_mfma_f32_16x16x32_bf16 v[42:45], v[160:163], v[184:187], v[42:45]
	v_mfma_f32_16x16x32_bf16 v[30:33], v[152:155], v[192:195], v[30:33]
	v_mfma_f32_16x16x32_bf16 v[26:29], v[160:163], v[192:195], v[26:29]
	v_mfma_f32_16x16x32_bf16 v[18:21], v[152:155], v[200:203], v[18:21]
	v_mfma_f32_16x16x32_bf16 v[10:13], v[160:163], v[200:203], v[10:13]
	s_barrier
	s_add_u32 s22, s22, 0x100080
	s_addc_u32 s23, s23, 0
	s_add_i32 s24, s24, s39
	s_mov_b32 m0, s24
	s_nop 0
	global_load_lds_dwordx4 v0, s[22:23]
	s_add_i32 m0, s24, 0x2000
	s_nop 0
	global_load_lds_dwordx4 v130, s[22:23]
	s_waitcnt vmcnt(6)
	s_barrier
	v_mfma_f32_16x16x32_bf16 v[54:57], v[204:207], v[164:167], v[54:57]
	v_mfma_f32_16x16x32_bf16 v[50:53], v[212:215], v[164:167], v[50:53]
	v_mfma_f32_16x16x32_bf16 v[38:41], v[204:207], v[172:175], v[38:41]
	v_mfma_f32_16x16x32_bf16 v[34:37], v[212:215], v[172:175], v[34:37]
	v_mfma_f32_16x16x32_bf16 v[22:25], v[204:207], v[188:191], v[22:25]
	v_mfma_f32_16x16x32_bf16 v[14:17], v[212:215], v[188:191], v[14:17]
	v_mfma_f32_16x16x32_bf16 v[6:9], v[204:207], v[196:199], v[6:9]
	v_mfma_f32_16x16x32_bf16 v[2:5], v[212:215], v[196:199], v[2:5]
	v_mfma_f32_16x16x32_bf16 v[54:57], v[208:211], v[168:171], v[54:57]
	v_mfma_f32_16x16x32_bf16 v[50:53], v[216:219], v[168:171], v[50:53]
	v_mfma_f32_16x16x32_bf16 v[38:41], v[208:211], v[184:187], v[38:41]
	v_mfma_f32_16x16x32_bf16 v[34:37], v[216:219], v[184:187], v[34:37]
	v_mfma_f32_16x16x32_bf16 v[22:25], v[208:211], v[192:195], v[22:25]
	v_mfma_f32_16x16x32_bf16 v[14:17], v[216:219], v[192:195], v[14:17]
	v_mfma_f32_16x16x32_bf16 v[6:9], v[208:211], v[200:203], v[6:9]
	v_mfma_f32_16x16x32_bf16 v[2:5], v[216:219], v[200:203], v[2:5]
	s_add_i32 s61, s61, 2
	s_add_u32 s20, s20, 0x100
	s_addc_u32 s21, s21, 0
	s_cmp_gt_u32 s61, 61
	s_barrier
	s_cbranch_scc0 .LBB0_472
	s_add_u32 s20, s17, 0xffffff00
	s_addc_u32 s21, s58, -1
	s_andn2_b64 vcc, exec, s[42:43]
	s_cbranch_vccnz .LBB0_463
	v_mov_b32_e32 v2, 0
	s_mov_b32 s57, s8
	s_mov_b32 s26, s10
	s_mov_b64 s[4:5], s[18:19]
	s_mov_b32 s56, s16
	v_mov_b32_e32 v3, v2
	v_mov_b32_e32 v4, v2
	v_mov_b32_e32 v5, v2
	v_mov_b32_e32 v6, v2
	v_mov_b32_e32 v7, v2
	v_mov_b32_e32 v8, v2
	v_mov_b32_e32 v9, v2
	v_mov_b32_e32 v14, v2
	v_mov_b32_e32 v15, v2
	v_mov_b32_e32 v16, v2
	v_mov_b32_e32 v17, v2
	v_mov_b32_e32 v22, v2
	v_mov_b32_e32 v23, v2
	v_mov_b32_e32 v24, v2
	v_mov_b32_e32 v25, v2
	v_mov_b32_e32 v34, v2
	v_mov_b32_e32 v35, v2
	v_mov_b32_e32 v36, v2
	v_mov_b32_e32 v37, v2
	v_mov_b32_e32 v38, v2
	v_mov_b32_e32 v39, v2
	v_mov_b32_e32 v40, v2
	v_mov_b32_e32 v41, v2
	v_mov_b32_e32 v50, v2
	v_mov_b32_e32 v51, v2
	v_mov_b32_e32 v52, v2
	v_mov_b32_e32 v53, v2
	v_mov_b32_e32 v54, v2
	v_mov_b32_e32 v55, v2
	v_mov_b32_e32 v56, v2
	v_mov_b32_e32 v57, v2
	v_mov_b32_e32 v10, v2
	v_mov_b32_e32 v11, v2
	v_mov_b32_e32 v12, v2
	v_mov_b32_e32 v13, v2
	v_mov_b32_e32 v18, v2
	v_mov_b32_e32 v19, v2
	v_mov_b32_e32 v20, v2
	v_mov_b32_e32 v21, v2
	v_mov_b32_e32 v26, v2
	v_mov_b32_e32 v27, v2
	v_mov_b32_e32 v28, v2
	v_mov_b32_e32 v29, v2
	v_mov_b32_e32 v30, v2
	v_mov_b32_e32 v31, v2
	v_mov_b32_e32 v32, v2
	v_mov_b32_e32 v33, v2
	v_mov_b32_e32 v42, v2
	v_mov_b32_e32 v43, v2
	v_mov_b32_e32 v44, v2
	v_mov_b32_e32 v45, v2
	v_mov_b32_e32 v46, v2
	v_mov_b32_e32 v47, v2
	v_mov_b32_e32 v48, v2
	v_mov_b32_e32 v49, v2
	v_mov_b32_e32 v58, v2
	v_mov_b32_e32 v59, v2
	v_mov_b32_e32 v60, v2
	v_mov_b32_e32 v61, v2
	v_mov_b32_e32 v62, v2
	v_mov_b32_e32 v63, v2
	v_mov_b32_e32 v64, v2
	v_mov_b32_e32 v65, v2
	v_mov_b32_e32 v66, v2
	v_mov_b32_e32 v67, v2
	v_mov_b32_e32 v68, v2
	v_mov_b32_e32 v69, v2
	v_mov_b32_e32 v70, v2
	v_mov_b32_e32 v71, v2
	v_mov_b32_e32 v72, v2
	v_mov_b32_e32 v73, v2
	v_mov_b32_e32 v82, v2
	v_mov_b32_e32 v83, v2
	v_mov_b32_e32 v84, v2
	v_mov_b32_e32 v85, v2
	v_mov_b32_e32 v86, v2
	v_mov_b32_e32 v87, v2
	v_mov_b32_e32 v88, v2
	v_mov_b32_e32 v89, v2
	v_mov_b32_e32 v98, v2
	v_mov_b32_e32 v99, v2
	v_mov_b32_e32 v100, v2
	v_mov_b32_e32 v101, v2
	v_mov_b32_e32 v102, v2
	v_mov_b32_e32 v103, v2
	v_mov_b32_e32 v104, v2
	v_mov_b32_e32 v105, v2
	v_mov_b32_e32 v114, v2
	v_mov_b32_e32 v115, v2
	v_mov_b32_e32 v116, v2
	v_mov_b32_e32 v117, v2
	v_mov_b32_e32 v118, v2
	v_mov_b32_e32 v119, v2
	v_mov_b32_e32 v120, v2
	v_mov_b32_e32 v121, v2
	v_mov_b32_e32 v74, v2
	v_mov_b32_e32 v75, v2
	v_mov_b32_e32 v76, v2
	v_mov_b32_e32 v77, v2
	v_mov_b32_e32 v78, v2
	v_mov_b32_e32 v79, v2
	v_mov_b32_e32 v80, v2
	v_mov_b32_e32 v81, v2
	v_mov_b32_e32 v90, v2
	v_mov_b32_e32 v91, v2
	v_mov_b32_e32 v92, v2
	v_mov_b32_e32 v93, v2
	v_mov_b32_e32 v94, v2
	v_mov_b32_e32 v95, v2
	v_mov_b32_e32 v96, v2
	v_mov_b32_e32 v97, v2
	v_mov_b32_e32 v106, v2
	v_mov_b32_e32 v107, v2
	v_mov_b32_e32 v108, v2
	v_mov_b32_e32 v109, v2
	v_mov_b32_e32 v110, v2
	v_mov_b32_e32 v111, v2
	v_mov_b32_e32 v112, v2
	v_mov_b32_e32 v113, v2
	v_mov_b32_e32 v122, v2
	v_mov_b32_e32 v123, v2
	v_mov_b32_e32 v124, v2
	v_mov_b32_e32 v125, v2
	v_mov_b32_e32 v126, v2
	v_mov_b32_e32 v127, v2
	v_mov_b32_e32 v128, v2
	v_mov_b32_e32 v129, v2
	s_andn2_b64 vcc, exec, s[40:41]
	s_cbranch_vccnz .LBB0_464

; #define PG8_STAGE(bufoff, gbase, voff) do { _Pragma("unroll") for (int _i = 0; _i < 2; ++_i) \
;         __builtin_amdgcn_global_load_lds((const unsigned*)((const char*)(gbase) + (voff)[_i]), (LAS unsigned*)(lds + (bufoff) + ldsw + _i * 8192), 16, 0, 0); } while (0)
; #define PG8_LDA(dst, b, h) do { _Pragma("unroll") for (int m = 0; m < 4; ++m) _Pragma("unroll") for (int k = 0; k < 2; ++k) dst[m][k] = *(const LAS bf16x8*)(lds + PG8_SA(b, h) + aoff + m * 2048 + k * 1024); } while (0)
; #define PG8_LDB(dst, b, h) do { _Pragma("unroll") for (int n = 0; n < 2; ++n) _Pragma("unroll") for (int k = 0; k < 2; ++k) dst[n][k] = *(const LAS bf16x8*)(lds + PG8_SB(b, h) + boff + n * 2048 + k * 1024); } while (0)
; #define PG8_MMA(ai, bj, At, Bt) do { __builtin_amdgcn_s_setprio(1); _Pragma("unroll") for (int m = 0; m < 4; ++m) _Pragma("unroll") for (int n = 0; n < 2; ++n) _Pragma("unroll") for (int k = 0; k < 2; ++k) \
;         acc[ai][bj][m][n] = __builtin_amdgcn_mfma_f32_16x16x32_bf16(Bt[n][k], At[m][k], acc[ai][bj][m][n], 0, 0, 0); __builtin_amdgcn_s_setprio(0); } while (0)
; #define PG8_WAIT_V(n) asm volatile("s_waitcnt vmcnt(" #n ")" ::: "memory")
; #define PG8_WAIT_L(n) asm volatile("s_waitcnt lgkmcnt(" #n ")" ::: "memory")
; #define PG8_BAR __builtin_amdgcn_s_barrier()
; #define PG8_SCHED __builtin_amdgcn_sched_barrier(0)
; template <class Epi>
; __device__ __forceinline__ void gemm_phase(LAS unsigned char* lds, const Gemm g, const StaticOrder& S, const Epi& E) {
;     ...
;             PG8_LDB(B0, 0, 0); PG8_SCHED; PG8_LDA(At, 0, 0); PG8_STAGE(PG8_SA(1, 1), a1 + hstepA, voffA);
;             PG8_WAIT_L(8); PG8_BAR; PG8_WAIT_L(0); PG8_MMA(0, 0, At, B0); PG8_BAR; PG8_SCHED;
;             PG8_LDB(B1, 0, 1); PG8_STAGE(PG8_SB(0, 0), b2, voffB);
;             PG8_BAR; PG8_WAIT_L(0); PG8_MMA(0, 1, At, B1); PG8_BAR;
;             PG8_LDA(At, 0, 1); PG8_STAGE(PG8_SA(0, 0), a2, voffA);
;             PG8_BAR; PG8_WAIT_L(0); PG8_MMA(1, 0, At, B0); PG8_BAR; PG8_SCHED;
;             PG8_STAGE(PG8_SB(0, 1), b2 + hstepB, voffB);
;             PG8_WAIT_V(6); PG8_BAR; PG8_MMA(1, 1, At, B1); PG8_BAR;
.LBB0_603:
	s_add_u32 s8, s0, 0x100
	s_addc_u32 s9, s1, 0
	s_add_i32 s60, 0, 0x10000
	ds_read_b128 v[34:37], v250
	ds_read_b128 v[38:41], v250 offset:1024
	ds_read_b128 v[98:101], v250 offset:2048
	ds_read_b128 v[102:105], v250 offset:3072
	s_cmp_eq_u32 s59, 12
	s_cselect_b32 s11, s35, s9
	s_cselect_b32 s10, s36, s8
	s_cselect_b32 s5, s37, s58
	s_cselect_b32 s4, s51, s53
	s_add_i32 m0, s20, 0xc000
	ds_read_b128 v[106:109], v231
	ds_read_b128 v[130:133], v231 offset:2048
	ds_read_b128 v[154:157], v231 offset:4096
	ds_read_b128 v[170:173], v231 offset:6144
	ds_read_b128 v[118:121], v231 offset:1024
	ds_read_b128 v[142:145], v231 offset:3072
	ds_read_b128 v[158:161], v231 offset:5120
	ds_read_b128 v[174:177], v231 offset:7168
	global_load_lds_dwordx4 v194, s[0:1]
	s_add_i32 m0, s20, 0xe000
	s_nop 0
	global_load_lds_dwordx4 v196, s[0:1]
	s_waitcnt lgkmcnt(8)
	s_barrier
	s_waitcnt lgkmcnt(4)
	v_mfma_f32_16x16x32_bf16 v[166:169], v[34:37], v[106:109], v[166:169]
	v_mfma_f32_16x16x32_bf16 v[162:165], v[98:101], v[106:109], v[162:165]
	v_mfma_f32_16x16x32_bf16 v[150:153], v[34:37], v[130:133], v[150:153]
	v_mfma_f32_16x16x32_bf16 v[146:149], v[98:101], v[130:133], v[146:149]
	v_mfma_f32_16x16x32_bf16 v[138:141], v[34:37], v[154:157], v[138:141]
	v_mfma_f32_16x16x32_bf16 v[134:137], v[98:101], v[154:157], v[134:137]
	v_mfma_f32_16x16x32_bf16 v[126:129], v[34:37], v[170:173], v[126:129]
	v_mfma_f32_16x16x32_bf16 v[122:125], v[98:101], v[170:173], v[122:125]
	s_waitcnt lgkmcnt(0)
	v_mfma_f32_16x16x32_bf16 v[166:169], v[38:41], v[118:121], v[166:169]
	v_mfma_f32_16x16x32_bf16 v[162:165], v[102:105], v[118:121], v[162:165]
	v_mfma_f32_16x16x32_bf16 v[150:153], v[38:41], v[142:145], v[150:153]
	v_mfma_f32_16x16x32_bf16 v[146:149], v[102:105], v[142:145], v[146:149]
	v_mfma_f32_16x16x32_bf16 v[138:141], v[38:41], v[158:161], v[138:141]
	v_mfma_f32_16x16x32_bf16 v[134:137], v[102:105], v[158:161], v[134:137]
	v_mfma_f32_16x16x32_bf16 v[126:129], v[38:41], v[174:177], v[126:129]
	v_mfma_f32_16x16x32_bf16 v[122:125], v[102:105], v[174:177], v[122:125]
	s_barrier
	s_add_i32 s61, 0, 0x14000
	s_add_i32 s0, s60, s19
	ds_read_b128 v[198:201], v250 offset:16384
	ds_read_b128 v[206:209], v250 offset:18432
	ds_read_b128 v[202:205], v250 offset:17408
	ds_read_b128 v[210:213], v250 offset:19456
	s_add_u32 s100, s4, s6
	s_addc_u32 s101, s5, s7
	s_mov_b32 m0, s0
	s_nop 0
	global_load_lds_dwordx4 v0, s[4:5]
	s_add_i32 m0, s0, 0x2000
	s_nop 0
	global_load_lds_dwordx4 v188, s[4:5]
	s_barrier
	s_waitcnt lgkmcnt(2)
	v_mfma_f32_16x16x32_bf16 v[70:73], v[198:201], v[106:109], v[70:73]
	v_mfma_f32_16x16x32_bf16 v[66:69], v[206:209], v[106:109], v[66:69]
	v_mfma_f32_16x16x32_bf16 v[62:65], v[198:201], v[130:133], v[62:65]
	v_mfma_f32_16x16x32_bf16 v[58:61], v[206:209], v[130:133], v[58:61]
	v_mfma_f32_16x16x32_bf16 v[54:57], v[198:201], v[154:157], v[54:57]
	v_mfma_f32_16x16x32_bf16 v[50:53], v[206:209], v[154:157], v[50:53]
	v_mfma_f32_16x16x32_bf16 v[46:49], v[198:201], v[170:173], v[46:49]
	v_mfma_f32_16x16x32_bf16 v[42:45], v[206:209], v[170:173], v[42:45]
	s_waitcnt lgkmcnt(0)
	v_mfma_f32_16x16x32_bf16 v[70:73], v[202:205], v[118:121], v[70:73]
	v_mfma_f32_16x16x32_bf16 v[66:69], v[210:213], v[118:121], v[66:69]
	v_mfma_f32_16x16x32_bf16 v[62:65], v[202:205], v[142:145], v[62:65]
	v_mfma_f32_16x16x32_bf16 v[58:61], v[210:213], v[142:145], v[58:61]
	v_mfma_f32_16x16x32_bf16 v[54:57], v[202:205], v[158:161], v[54:57]
	v_mfma_f32_16x16x32_bf16 v[50:53], v[210:213], v[158:161], v[50:53]
	v_mfma_f32_16x16x32_bf16 v[46:49], v[202:205], v[174:177], v[46:49]
	v_mfma_f32_16x16x32_bf16 v[42:45], v[210:213], v[174:177], v[42:45]
	s_mov_b32 m0, s20
	s_add_u32 vcc_lo, s10, s6
	s_addc_u32 vcc_hi, s11, s7
	s_barrier
	ds_read_b128 v[106:109], v231 offset:16384
	ds_read_b128 v[118:121], v231 offset:17408
	ds_read_b128 v[130:133], v231 offset:18432
	ds_read_b128 v[154:157], v231 offset:20480
	ds_read_b128 v[170:173], v231 offset:22528
	ds_read_b128 v[142:145], v231 offset:19456
	ds_read_b128 v[158:161], v231 offset:21504
	ds_read_b128 v[174:177], v231 offset:23552
	global_load_lds_dwordx4 v192, s[10:11]
	s_mov_b32 m0, s21
	s_nop 0
	global_load_lds_dwordx4 v190, s[10:11]
	s_barrier
	s_waitcnt lgkmcnt(3)
	v_mfma_f32_16x16x32_bf16 v[114:117], v[34:37], v[106:109], v[114:117]
	v_mfma_f32_16x16x32_bf16 v[110:113], v[98:101], v[106:109], v[110:113]
	v_mfma_f32_16x16x32_bf16 v[94:97], v[34:37], v[130:133], v[94:97]
	v_mfma_f32_16x16x32_bf16 v[90:93], v[98:101], v[130:133], v[90:93]
	v_mfma_f32_16x16x32_bf16 v[86:89], v[34:37], v[154:157], v[86:89]
	v_mfma_f32_16x16x32_bf16 v[82:85], v[98:101], v[154:157], v[82:85]
	v_mfma_f32_16x16x32_bf16 v[34:37], v[34:37], v[170:173], v[78:81]
	v_mfma_f32_16x16x32_bf16 v[114:117], v[38:41], v[118:121], v[114:117]
	s_waitcnt lgkmcnt(0)
	v_mfma_f32_16x16x32_bf16 v[110:113], v[102:105], v[118:121], v[110:113]
	v_mfma_f32_16x16x32_bf16 v[94:97], v[38:41], v[142:145], v[94:97]
	v_mfma_f32_16x16x32_bf16 v[90:93], v[102:105], v[142:145], v[90:93]
	v_mfma_f32_16x16x32_bf16 v[86:89], v[38:41], v[158:161], v[86:89]
	v_mfma_f32_16x16x32_bf16 v[82:85], v[102:105], v[158:161], v[82:85]
	v_mfma_f32_16x16x32_bf16 v[34:37], v[38:41], v[174:177], v[34:37]
	v_mfma_f32_16x16x32_bf16 v[38:41], v[98:101], v[170:173], v[74:77]
	v_mfma_f32_16x16x32_bf16 v[38:41], v[102:105], v[174:177], v[38:41]
	s_barrier
	s_add_u32 s0, s4, 0x40000
	s_addc_u32 s1, s5, 0
	s_add_i32 s60, s61, s19
	s_mov_b32 m0, s60
	s_nop 0
	global_load_lds_dwordx4 v0, s[0:1]
	s_add_i32 m0, s60, 0x2000
	s_nop 0
	global_load_lds_dwordx4 v188, s[0:1]
	s_waitcnt vmcnt(6)
	s_barrier
; #define PG8_STAGE(bufoff, gbase, voff) do { _Pragma("unroll") for (int _i = 0; _i < 2; ++_i) \
;         __builtin_amdgcn_global_load_lds((const unsigned*)((const char*)(gbase) + (voff)[_i]), (LAS unsigned*)(lds + (bufoff) + ldsw + _i * 8192), 16, 0, 0); } while (0)
; #define PG8_LDA(dst, b, h) do { _Pragma("unroll") for (int m = 0; m < 4; ++m) _Pragma("unroll") for (int k = 0; k < 2; ++k) dst[m][k] = *(const LAS bf16x8*)(lds + PG8_SA(b, h) + aoff + m * 2048 + k * 1024); } while (0)
; #define PG8_LDB(dst, b, h) do { _Pragma("unroll") for (int n = 0; n < 2; ++n) _Pragma("unroll") for (int k = 0; k < 2; ++k) dst[n][k] = *(const LAS bf16x8*)(lds + PG8_SB(b, h) + boff + n * 2048 + k * 1024); } while (0)
; #define PG8_MMA(ai, bj, At, Bt) do { __builtin_amdgcn_s_setprio(1); _Pragma("unroll") for (int m = 0; m < 4; ++m) _Pragma("unroll") for (int n = 0; n < 2; ++n) _Pragma("unroll") for (int k = 0; k < 2; ++k) \
;         acc[ai][bj][m][n] = __builtin_amdgcn_mfma_f32_16x16x32_bf16(Bt[n][k], At[m][k], acc[ai][bj][m][n], 0, 0, 0); __builtin_amdgcn_s_setprio(0); } while (0)
; #define PG8_WAIT_V(n) asm volatile("s_waitcnt vmcnt(" #n ")" ::: "memory")
; #define PG8_WAIT_L(n) asm volatile("s_waitcnt lgkmcnt(" #n ")" ::: "memory")
; #define PG8_BAR __builtin_amdgcn_s_barrier()
; #define PG8_SCHED __builtin_amdgcn_sched_barrier(0)
; template <class Epi>
; __device__ __forceinline__ void gemm_phase(LAS unsigned char* lds, const Gemm g, const StaticOrder& S, const Epi& E) {
;     ...
;             PG8_WAIT_V(6); PG8_BAR; PG8_MMA(1, 1, At, B1); PG8_BAR;
;             PG8_LDB(B0, 1, 0); PG8_SCHED; PG8_LDA(At, 1, 0); PG8_STAGE(PG8_SA(0, 1), a2 + hstepA, voffA);
;             PG8_WAIT_L(8); PG8_BAR; PG8_WAIT_L(0); PG8_MMA(0, 0, At, B0); PG8_BAR; PG8_SCHED;
;             PG8_LDB(B1, 1, 1); PG8_STAGE(PG8_SB(1, 0), b3, voffB);
;             PG8_BAR; PG8_WAIT_L(0); PG8_MMA(0, 1, At, B1); PG8_BAR;
;             PG8_LDA(At, 1, 1); PG8_STAGE(PG8_SA(1, 0), a3, voffA);
;             PG8_BAR; PG8_WAIT_L(0); PG8_MMA(1, 0, At, B0); PG8_BAR; PG8_SCHED;
	v_mfma_f32_16x16x32_bf16 v[30:33], v[198:201], v[106:109], v[30:33]
	v_mfma_f32_16x16x32_bf16 v[26:29], v[206:209], v[106:109], v[26:29]
	v_mfma_f32_16x16x32_bf16 v[22:25], v[198:201], v[130:133], v[22:25]
	v_mfma_f32_16x16x32_bf16 v[18:21], v[206:209], v[130:133], v[18:21]
	v_mfma_f32_16x16x32_bf16 v[14:17], v[198:201], v[154:157], v[14:17]
	v_mfma_f32_16x16x32_bf16 v[10:13], v[206:209], v[154:157], v[10:13]
	v_mfma_f32_16x16x32_bf16 v[6:9], v[198:201], v[170:173], v[6:9]
	v_mfma_f32_16x16x32_bf16 v[2:5], v[206:209], v[170:173], v[2:5]
	v_mfma_f32_16x16x32_bf16 v[30:33], v[202:205], v[118:121], v[30:33]
	v_mfma_f32_16x16x32_bf16 v[26:29], v[210:213], v[118:121], v[26:29]
	v_mfma_f32_16x16x32_bf16 v[22:25], v[202:205], v[142:145], v[22:25]
	v_mfma_f32_16x16x32_bf16 v[18:21], v[210:213], v[142:145], v[18:21]
	v_mfma_f32_16x16x32_bf16 v[14:17], v[202:205], v[158:161], v[14:17]
	v_mfma_f32_16x16x32_bf16 v[10:13], v[210:213], v[158:161], v[10:13]
	v_mfma_f32_16x16x32_bf16 v[6:9], v[202:205], v[174:177], v[6:9]
	v_mfma_f32_16x16x32_bf16 v[2:5], v[210:213], v[174:177], v[2:5]
	s_add_i32 s60, 0, 0x18000
	s_barrier
	ds_read_b128 v[74:77], v250 offset:32768
	ds_read_b128 v[78:81], v250 offset:33792
	ds_read_b128 v[98:101], v250 offset:34816
	ds_read_b128 v[102:105], v250 offset:35840
	s_add_u32 s0, s10, 0x100000
	s_addc_u32 s1, s11, 0
	s_mov_b32 m0, s22
	ds_read_b128 v[106:109], v231 offset:32768
	ds_read_b128 v[130:133], v231 offset:34816
	ds_read_b128 v[154:157], v231 offset:36864
	ds_read_b128 v[170:173], v231 offset:38912
	ds_read_b128 v[118:121], v231 offset:33792
	ds_read_b128 v[142:145], v231 offset:35840
	ds_read_b128 v[158:161], v231 offset:37888
	ds_read_b128 v[174:177], v231 offset:39936
	global_load_lds_dwordx4 v192, s[0:1]
	s_mov_b32 m0, s23
	s_nop 0
	global_load_lds_dwordx4 v190, s[0:1]
	s_waitcnt lgkmcnt(8)
	s_barrier
	s_waitcnt lgkmcnt(4)
	v_mfma_f32_16x16x32_bf16 v[166:169], v[74:77], v[106:109], v[166:169]
	v_mfma_f32_16x16x32_bf16 v[162:165], v[98:101], v[106:109], v[162:165]
	v_mfma_f32_16x16x32_bf16 v[150:153], v[74:77], v[130:133], v[150:153]
	v_mfma_f32_16x16x32_bf16 v[146:149], v[98:101], v[130:133], v[146:149]
	v_mfma_f32_16x16x32_bf16 v[138:141], v[74:77], v[154:157], v[138:141]
	v_mfma_f32_16x16x32_bf16 v[134:137], v[98:101], v[154:157], v[134:137]
	v_mfma_f32_16x16x32_bf16 v[126:129], v[74:77], v[170:173], v[126:129]
	v_mfma_f32_16x16x32_bf16 v[122:125], v[98:101], v[170:173], v[122:125]
	s_waitcnt lgkmcnt(0)
	v_mfma_f32_16x16x32_bf16 v[166:169], v[78:81], v[118:121], v[166:169]
	v_mfma_f32_16x16x32_bf16 v[162:165], v[102:105], v[118:121], v[162:165]
	v_mfma_f32_16x16x32_bf16 v[150:153], v[78:81], v[142:145], v[150:153]
	v_mfma_f32_16x16x32_bf16 v[146:149], v[102:105], v[142:145], v[146:149]
	v_mfma_f32_16x16x32_bf16 v[138:141], v[78:81], v[158:161], v[138:141]
	v_mfma_f32_16x16x32_bf16 v[134:137], v[102:105], v[158:161], v[134:137]
	v_mfma_f32_16x16x32_bf16 v[126:129], v[78:81], v[174:177], v[126:129]
	v_mfma_f32_16x16x32_bf16 v[122:125], v[102:105], v[174:177], v[122:125]
	s_barrier
	s_add_i32 s10, 0, 0x1c000
	s_add_i32 s0, s60, s19
	s_mov_b32 m0, s0
	ds_read_b128 v[198:201], v250 offset:49152
	ds_read_b128 v[206:209], v250 offset:51200
	ds_read_b128 v[202:205], v250 offset:50176
	ds_read_b128 v[210:213], v250 offset:52224
	global_load_lds_dwordx4 v0, s[100:101]
	s_add_i32 m0, s0, 0x2000
	s_nop 0
	global_load_lds_dwordx4 v188, s[100:101]
	s_barrier
	s_waitcnt lgkmcnt(2)
	v_mfma_f32_16x16x32_bf16 v[70:73], v[198:201], v[106:109], v[70:73]
	v_mfma_f32_16x16x32_bf16 v[66:69], v[206:209], v[106:109], v[66:69]
	v_mfma_f32_16x16x32_bf16 v[62:65], v[198:201], v[130:133], v[62:65]
	v_mfma_f32_16x16x32_bf16 v[58:61], v[206:209], v[130:133], v[58:61]
	v_mfma_f32_16x16x32_bf16 v[54:57], v[198:201], v[154:157], v[54:57]
	v_mfma_f32_16x16x32_bf16 v[50:53], v[206:209], v[154:157], v[50:53]
	v_mfma_f32_16x16x32_bf16 v[46:49], v[198:201], v[170:173], v[46:49]
	v_mfma_f32_16x16x32_bf16 v[42:45], v[206:209], v[170:173], v[42:45]
	s_waitcnt lgkmcnt(0)
	v_mfma_f32_16x16x32_bf16 v[70:73], v[202:205], v[118:121], v[70:73]
	v_mfma_f32_16x16x32_bf16 v[66:69], v[210:213], v[118:121], v[66:69]
	v_mfma_f32_16x16x32_bf16 v[62:65], v[202:205], v[142:145], v[62:65]
	v_mfma_f32_16x16x32_bf16 v[58:61], v[210:213], v[142:145], v[58:61]
	v_mfma_f32_16x16x32_bf16 v[54:57], v[202:205], v[158:161], v[54:57]
	v_mfma_f32_16x16x32_bf16 v[50:53], v[210:213], v[158:161], v[50:53]
	v_mfma_f32_16x16x32_bf16 v[46:49], v[202:205], v[174:177], v[46:49]
	v_mfma_f32_16x16x32_bf16 v[42:45], v[210:213], v[174:177], v[42:45]
	s_mov_b32 m0, s24
	s_barrier
	ds_read_b128 v[106:109], v231 offset:49152
	ds_read_b128 v[118:121], v231 offset:50176
	ds_read_b128 v[130:133], v231 offset:51200
	ds_read_b128 v[142:145], v231 offset:52224
	ds_read_b128 v[154:157], v231 offset:53248
	ds_read_b128 v[170:173], v231 offset:55296
	ds_read_b128 v[158:161], v231 offset:54272
	ds_read_b128 v[174:177], v231 offset:56320
	global_load_lds_dwordx4 v192, vcc
	s_mov_b32 m0, s25
	s_nop 0
	global_load_lds_dwordx4 v190, vcc
	s_barrier
; #define PG8_STAGE(bufoff, gbase, voff) do { _Pragma("unroll") for (int _i = 0; _i < 2; ++_i) \
;         __builtin_amdgcn_global_load_lds((const unsigned*)((const char*)(gbase) + (voff)[_i]), (LAS unsigned*)(lds + (bufoff) + ldsw + _i * 8192), 16, 0, 0); } while (0)
; #define PG8_MMA(ai, bj, At, Bt) do { __builtin_amdgcn_s_setprio(1); _Pragma("unroll") for (int m = 0; m < 4; ++m) _Pragma("unroll") for (int n = 0; n < 2; ++n) _Pragma("unroll") for (int k = 0; k < 2; ++k) \
;         acc[ai][bj][m][n] = __builtin_amdgcn_mfma_f32_16x16x32_bf16(Bt[n][k], At[m][k], acc[ai][bj][m][n], 0, 0, 0); __builtin_amdgcn_s_setprio(0); } while (0)
; #define PG8_WAIT_V(n) asm volatile("s_waitcnt vmcnt(" #n ")" ::: "memory")
; #define PG8_WAIT_L(n) asm volatile("s_waitcnt lgkmcnt(" #n ")" ::: "memory")
; #define PG8_BAR __builtin_amdgcn_s_barrier()
; #define PG8_SCHED __builtin_amdgcn_sched_barrier(0)
; template <class Epi>
; __device__ __forceinline__ void gemm_phase(LAS unsigned char* lds, const Gemm g, const StaticOrder& S, const Epi& E) {
;     ...
;             PG8_BAR; PG8_WAIT_L(0); PG8_MMA(1, 0, At, B0); PG8_BAR; PG8_SCHED;
;             PG8_STAGE(PG8_SB(1, 1), b3 + hstepB, voffB);
;             PG8_WAIT_V(6); PG8_BAR; PG8_MMA(1, 1, At, B1); PG8_BAR;
;     __device__ __forceinline__ void operator()(const f32x4 (&acc)[2][2][4][2], const Unit& u, int wr, int wc, int fr, int fq, const Pre&) const {
;         const int row0 = u.pm * BM + wr * 64 + fr, col0 = u.pn * BM + wc * 32 + 8 * fq;
;         f32x4 sc[2][2];
; #pragma unroll
;         for (int bj = 0; bj < 2; ++bj) { sc[bj][0] = *(const f32x4*)(scale + col0 + bj * HALF); sc[bj][1] = *(const f32x4*)(scale + col0 + bj * HALF + 4); }
; #pragma unroll
;         for (int bj = 0; bj < 2; ++bj) { const int c = col0 + bj * HALF;
;             u32x4 zv[8];
; #pragma unroll
;             for (int g8 = 0; g8 < 8; ++g8) zv[g8] = *(const u32x4*)(Z + (size_t)(row0 + (g8 >> 2) * HALF + (g8 & 3) * 16) * DE2 + c);
	s_waitcnt lgkmcnt(2)
	v_mfma_f32_16x16x32_bf16 v[114:117], v[74:77], v[106:109], v[114:117]
	v_mfma_f32_16x16x32_bf16 v[94:97], v[74:77], v[130:133], v[94:97]
	v_mfma_f32_16x16x32_bf16 v[86:89], v[74:77], v[154:157], v[86:89]
	v_mfma_f32_16x16x32_bf16 v[34:37], v[74:77], v[170:173], v[34:37]
	v_mfma_f32_16x16x32_bf16 v[114:117], v[78:81], v[118:121], v[114:117]
	v_mfma_f32_16x16x32_bf16 v[110:113], v[98:101], v[106:109], v[110:113]
	v_mfma_f32_16x16x32_bf16 v[94:97], v[78:81], v[142:145], v[94:97]
	v_mfma_f32_16x16x32_bf16 v[90:93], v[98:101], v[130:133], v[90:93]
	s_waitcnt lgkmcnt(0)
	v_mfma_f32_16x16x32_bf16 v[86:89], v[78:81], v[158:161], v[86:89]
	v_mfma_f32_16x16x32_bf16 v[82:85], v[98:101], v[154:157], v[82:85]
	v_mfma_f32_16x16x32_bf16 v[78:81], v[78:81], v[174:177], v[34:37]
	v_mfma_f32_16x16x32_bf16 v[34:37], v[98:101], v[170:173], v[38:41]
	v_mfma_f32_16x16x32_bf16 v[110:113], v[102:105], v[118:121], v[110:113]
	v_mfma_f32_16x16x32_bf16 v[90:93], v[102:105], v[142:145], v[90:93]
	v_mfma_f32_16x16x32_bf16 v[82:85], v[102:105], v[158:161], v[82:85]
	v_mfma_f32_16x16x32_bf16 v[74:77], v[102:105], v[174:177], v[34:37]
	s_barrier
	s_add_u32 s0, s4, 0x40080
	s_addc_u32 s1, s5, 0
	s_add_i32 s4, s10, s19
	s_mov_b32 m0, s4
	s_nop 0
	global_load_lds_dwordx4 v0, s[0:1]
	s_add_i32 m0, s4, 0x2000
	s_nop 0
	global_load_lds_dwordx4 v188, s[0:1]
	s_waitcnt vmcnt(6)
	s_barrier
	v_mfma_f32_16x16x32_bf16 v[30:33], v[198:201], v[106:109], v[30:33]
	v_mfma_f32_16x16x32_bf16 v[26:29], v[206:209], v[106:109], v[26:29]
	v_mfma_f32_16x16x32_bf16 v[22:25], v[198:201], v[130:133], v[22:25]
	v_mfma_f32_16x16x32_bf16 v[18:21], v[206:209], v[130:133], v[18:21]
	v_mfma_f32_16x16x32_bf16 v[14:17], v[198:201], v[154:157], v[14:17]
	v_mfma_f32_16x16x32_bf16 v[10:13], v[206:209], v[154:157], v[10:13]
	v_mfma_f32_16x16x32_bf16 v[6:9], v[198:201], v[170:173], v[6:9]
	v_mfma_f32_16x16x32_bf16 v[2:5], v[206:209], v[170:173], v[2:5]
	v_mfma_f32_16x16x32_bf16 v[30:33], v[202:205], v[118:121], v[30:33]
	v_mfma_f32_16x16x32_bf16 v[26:29], v[210:213], v[118:121], v[26:29]
	v_mfma_f32_16x16x32_bf16 v[22:25], v[202:205], v[142:145], v[22:25]
	v_mfma_f32_16x16x32_bf16 v[18:21], v[210:213], v[142:145], v[18:21]
	v_mfma_f32_16x16x32_bf16 v[14:17], v[202:205], v[158:161], v[14:17]
	v_mfma_f32_16x16x32_bf16 v[10:13], v[210:213], v[158:161], v[10:13]
	v_mfma_f32_16x16x32_bf16 v[6:9], v[202:205], v[174:177], v[6:9]
	v_mfma_f32_16x16x32_bf16 v[2:5], v[210:213], v[174:177], v[2:5]
	s_add_i32 s59, s59, 2
	s_add_u32 s53, s53, 0x100
	s_addc_u32 s58, s58, 0
	s_cmp_gt_u32 s59, 13
	s_mov_b64 s[0:1], s[8:9]
	s_barrier
	s_cbranch_scc0 .LBB0_603
	v_lshl_or_b32 v200, s34, 8, v230
	v_ashrrev_i32_e32 v201, 31, v200
	v_lshl_add_u32 v226, s27, 8, v228
	v_lshlrev_b64 v[216:217], 1, v[200:201]
	v_ashrrev_i32_e32 v227, 31, v226
	v_lshl_add_u64 v[106:107], s[46:47], 0, v[216:217]
	v_lshlrev_b64 v[204:205], 14, v[226:227]
	v_lshl_add_u64 v[38:39], v[200:201], 2, s[48:49]
	v_lshl_add_u64 v[108:109], v[106:107], 0, v[204:205]
	global_load_dwordx4 v[98:101], v[38:39], off offset:16
	global_load_dwordx4 v[102:105], v[38:39], off
	global_load_dwordx4 v[34:37], v[38:39], off offset:528
	s_nop 0
	global_load_dwordx4 v[38:41], v[38:39], off offset:512
	v_or_b32_e32 v224, 16, v226
	global_load_dwordx4 v[174:177], v[108:109], off
	v_ashrrev_i32_e32 v225, 31, v224
	v_or_b32_e32 v222, 32, v226
	v_lshlrev_b64 v[198:199], 14, v[224:225]
	v_ashrrev_i32_e32 v223, 31, v222
	v_or_b32_e32 v220, 48, v226
	v_lshl_add_u64 v[108:109], v[106:107], 0, v[198:199]
	v_lshlrev_b64 v[202:203], 14, v[222:223]
	v_ashrrev_i32_e32 v221, 31, v220
	v_add_u32_e32 v218, 0x80, v226
	global_load_dwordx4 v[170:173], v[108:109], off
	v_lshl_add_u64 v[108:109], v[106:107], 0, v[202:203]
	v_lshlrev_b64 v[206:207], 14, v[220:221]
	v_ashrrev_i32_e32 v219, 31, v218
	global_load_dwordx4 v[158:161], v[108:109], off
	v_lshl_add_u64 v[108:109], v[106:107], 0, v[206:207]
	v_lshlrev_b64 v[208:209], 14, v[218:219]
	global_load_dwordx4 v[154:157], v[108:109], off
	v_lshl_add_u64 v[108:109], v[106:107], 0, v[208:209]
	global_load_dwordx4 v[142:145], v[108:109], off
	v_add_u32_e32 v108, 0x90, v226
	v_ashrrev_i32_e32 v109, 31, v108
	v_lshlrev_b64 v[210:211], 14, v[108:109]
	v_lshl_add_u64 v[108:109], v[106:107], 0, v[210:211]
	global_load_dwordx4 v[130:133], v[108:109], off
	v_add_u32_e32 v108, 0xa0, v226
	v_ashrrev_i32_e32 v109, 31, v108
	v_lshlrev_b64 v[212:213], 14, v[108:109]
	v_lshl_add_u64 v[108:109], v[106:107], 0, v[212:213]
	global_load_dwordx4 v[118:121], v[108:109], off
	v_add_u32_e32 v108, 0xb0, v226
	v_ashrrev_i32_e32 v109, 31, v108
	v_lshlrev_b64 v[214:215], 14, v[108:109]
	v_lshl_add_u64 v[106:107], v[106:107], 0, v[214:215]
	global_load_dwordx4 v[106:109], v[106:107], off
	s_mov_b64 s[0:1], 0x120000
	s_mov_b32 s27, s52
	s_mov_b32 s34, s50
	s_mov_b64 s[8:9], s[56:57]
	s_waitcnt vmcnt(0)
; __device__ __forceinline__ unsigned cvt_pk_bf16(float lo, float hi) { unsigned r; asm volatile("v_cvt_pk_bf16_f32 %0, %1, %2" : "=v"(r) : "v"(lo), "v"(hi)); return r; }
; __device__ __forceinline__ float bf_lo(unsigned w) { return __uint_as_float(w << 16); }
; __device__ __forceinline__ float bf_hi(unsigned w) { return __uint_as_float(w & 0xffff0000u); }
; __device__ __forceinline__ float silu_f(float z) { return z * fast_rcp(1.0f + __builtin_amdgcn_exp2f(z * -1.44269504f)); }
;     __device__ __forceinline__ void operator()(const f32x4 (&acc)[2][2][4][2], const Unit& u, int wr, int wc, int fr, int fq, const Pre&) const {
;     ...
;             for (int ai = 0; ai < 2; ++ai)
; #pragma unroll
;                 for (int m = 0; m < 4; ++m) { const int r = row0 + ai * HALF + m * 16;
;                     const u32x4 zw = zv[ai * 4 + m];
;                     const f32x4 a0 = acc[ai][bj][m][0] * sc[bj][0], a1 = acc[ai][bj][m][1] * sc[bj][1];
;                     u32x4 w;
;                     w.x = cvt_pk_bf16(a0[0] * silu_f(bf_lo(zw.x)), a0[1] * silu_f(bf_hi(zw.x)));
;                     w.y = cvt_pk_bf16(a0[2] * silu_f(bf_lo(zw.y)), a0[3] * silu_f(bf_hi(zw.y)));
;                     w.z = cvt_pk_bf16(a1[0] * silu_f(bf_lo(zw.z)), a1[1] * silu_f(bf_hi(zw.z)));
;                     w.w = cvt_pk_bf16(a1[2] * silu_f(bf_lo(zw.w)), a1[3] * silu_f(bf_hi(zw.w)));
;                     *(u32x4*)(O + (size_t)r * DE + c) = w; } }
	v_pk_mul_f32 v[146:147], v[146:147], v[98:99]
	v_pk_mul_f32 v[184:185], v[166:167], v[102:103]
	v_pk_mul_f32 v[166:167], v[164:165], v[100:101]
	v_pk_mul_f32 v[164:165], v[162:163], v[98:99]
	v_pk_mul_f32 v[168:169], v[168:169], v[104:105]
	v_lshlrev_b32_e32 v162, 16, v174
	v_mul_f32_e32 v163, 0xbfb8aa3b, v162
	v_exp_f32_e32 v163, v163
	v_pk_mul_f32 v[150:151], v[150:151], v[102:103]
	v_pk_mul_f32 v[152:153], v[152:153], v[104:105]
	v_pk_mul_f32 v[148:149], v[148:149], v[100:101]
	v_add_f32_e32 v163, 1.0, v163
	v_rcp_f32_e32 v163, v163
	v_pk_mul_f32 v[138:139], v[138:139], v[102:103]
	v_pk_mul_f32 v[140:141], v[140:141], v[104:105]
	v_pk_mul_f32 v[134:135], v[134:135], v[98:99]
	v_mul_f32_e32 v162, v163, v162
	v_and_b32_e32 v163, 0xffff0000, v174
	v_mul_f32_e32 v174, 0xbfb8aa3b, v163
	v_exp_f32_e32 v174, v174
	v_mul_f32_e32 v162, v184, v162
	v_pk_mul_f32 v[136:137], v[136:137], v[100:101]
	v_pk_mul_f32 v[126:127], v[126:127], v[102:103]
	v_add_f32_e32 v174, 1.0, v174
	v_rcp_f32_e32 v174, v174
	v_pk_mul_f32 v[128:129], v[128:129], v[104:105]
	v_pk_mul_f32 v[122:123], v[122:123], v[98:99]
	v_pk_mul_f32 v[124:125], v[124:125], v[100:101]
	v_mul_f32_e32 v163, v174, v163
	v_mul_f32_e32 v163, v185, v163
	v_cvt_pk_bf16_f32 v162, v162, v163
	v_lshlrev_b32_e32 v163, 16, v175
	v_mul_f32_e32 v174, 0xbfb8aa3b, v163
	v_exp_f32_e32 v174, v174
	v_pk_mul_f32 v[114:115], v[114:115], v[102:103]
	v_pk_mul_f32 v[116:117], v[116:117], v[104:105]
	v_pk_mul_f32 v[110:111], v[110:111], v[98:99]
	v_add_f32_e32 v174, 1.0, v174
	v_rcp_f32_e32 v174, v174
	v_pk_mul_f32 v[112:113], v[112:113], v[100:101]
	v_pk_mul_f32 v[94:95], v[94:95], v[102:103]
	v_pk_mul_f32 v[96:97], v[96:97], v[104:105]
	v_mul_f32_e32 v163, v174, v163
	v_mul_f32_e32 v163, v168, v163
	v_and_b32_e32 v168, 0xffff0000, v175
	v_mul_f32_e32 v174, 0xbfb8aa3b, v168
	v_exp_f32_e32 v174, v174
	v_pk_mul_f32 v[90:91], v[90:91], v[98:99]
	v_pk_mul_f32 v[92:93], v[92:93], v[100:101]
	v_pk_mul_f32 v[86:87], v[86:87], v[102:103]
	v_add_f32_e32 v174, 1.0, v174
	v_rcp_f32_e32 v174, v174
	v_pk_mul_f32 v[88:89], v[88:89], v[104:105]
	v_pk_mul_f32 v[82:83], v[82:83], v[98:99]
	v_pk_mul_f32 v[84:85], v[84:85], v[100:101]
	v_mul_f32_e32 v168, v174, v168
	v_mul_f32_e32 v168, v169, v168
	v_cvt_pk_bf16_f32 v163, v163, v168
	v_lshlrev_b32_e32 v168, 16, v176
	v_mul_f32_e32 v169, 0xbfb8aa3b, v168
	v_exp_f32_e32 v169, v169
	v_pk_mul_f32 v[78:79], v[78:79], v[102:103]
	v_pk_mul_f32 v[80:81], v[80:81], v[104:105]
	v_pk_mul_f32 v[74:75], v[74:75], v[98:99]
	v_add_f32_e32 v169, 1.0, v169
	v_rcp_f32_e32 v169, v169
	v_pk_mul_f32 v[76:77], v[76:77], v[100:101]
	v_pk_mul_f32 v[70:71], v[70:71], v[38:39]
	v_pk_mul_f32 v[72:73], v[72:73], v[40:41]
	v_mul_f32_e32 v168, v169, v168
	v_mul_f32_e32 v164, v164, v168
	v_and_b32_e32 v168, 0xffff0000, v176
	v_mul_f32_e32 v169, 0xbfb8aa3b, v168
	v_exp_f32_e32 v169, v169
	v_pk_mul_f32 v[66:67], v[66:67], v[34:35]
	v_pk_mul_f32 v[68:69], v[68:69], v[36:37]
	v_pk_mul_f32 v[62:63], v[62:63], v[38:39]
	v_add_f32_e32 v169, 1.0, v169
	v_rcp_f32_e32 v169, v169
	v_pk_mul_f32 v[64:65], v[64:65], v[40:41]
	v_pk_mul_f32 v[58:59], v[58:59], v[34:35]
	v_pk_mul_f32 v[60:61], v[60:61], v[36:37]
	v_mul_f32_e32 v168, v169, v168
	v_mul_f32_e32 v165, v165, v168
	v_cvt_pk_bf16_f32 v164, v164, v165
	v_lshlrev_b32_e32 v165, 16, v177
	v_mul_f32_e32 v168, 0xbfb8aa3b, v165
	v_exp_f32_e32 v168, v168
	v_pk_mul_f32 v[54:55], v[54:55], v[38:39]
	v_pk_mul_f32 v[56:57], v[56:57], v[40:41]
	v_pk_mul_f32 v[50:51], v[50:51], v[34:35]
	v_add_f32_e32 v168, 1.0, v168
	v_rcp_f32_e32 v168, v168
	v_pk_mul_f32 v[52:53], v[52:53], v[36:37]
	v_pk_mul_f32 v[46:47], v[46:47], v[38:39]
	v_pk_mul_f32 v[48:49], v[48:49], v[40:41]
	v_mul_f32_e32 v165, v168, v165
	v_mul_f32_e32 v165, v166, v165
	v_and_b32_e32 v166, 0xffff0000, v177
	v_mul_f32_e32 v168, 0xbfb8aa3b, v166
	v_exp_f32_e32 v168, v168
	v_pk_mul_f32 v[42:43], v[42:43], v[34:35]
	v_pk_mul_f32 v[44:45], v[44:45], v[36:37]
	v_pk_mul_f32 v[30:31], v[30:31], v[38:39]
	v_add_f32_e32 v168, 1.0, v168
	v_rcp_f32_e32 v168, v168
	v_pk_mul_f32 v[32:33], v[32:33], v[40:41]
	v_pk_mul_f32 v[26:27], v[26:27], v[34:35]
	v_pk_mul_f32 v[28:29], v[28:29], v[36:37]
	v_mul_f32_e32 v166, v168, v166
	v_mul_f32_e32 v166, v167, v166
	v_cvt_pk_bf16_f32 v165, v165, v166
	v_lshlrev_b64 v[166:167], 13, v[226:227]
	v_lshl_add_u64 v[166:167], s[44:45], 0, v[166:167]
	v_lshl_add_u64 v[166:167], v[166:167], 0, v[216:217]
	global_store_dwordx4 v[166:167], v[162:165], off
	v_pk_mul_f32 v[22:23], v[22:23], v[38:39]
	v_pk_mul_f32 v[24:25], v[24:25], v[40:41]
	v_lshlrev_b32_e32 v162, 16, v170
	v_mul_f32_e32 v163, 0xbfb8aa3b, v162
	v_exp_f32_e32 v163, v163
	v_pk_mul_f32 v[18:19], v[18:19], v[34:35]
	v_pk_mul_f32 v[20:21], v[20:21], v[36:37]
	v_pk_mul_f32 v[14:15], v[14:15], v[38:39]
	v_add_f32_e32 v163, 1.0, v163
	v_rcp_f32_e32 v163, v163
	v_pk_mul_f32 v[16:17], v[16:17], v[40:41]
	v_pk_mul_f32 v[10:11], v[10:11], v[34:35]
	v_pk_mul_f32 v[12:13], v[12:13], v[36:37]
	v_mul_f32_e32 v162, v163, v162
	v_mul_f32_e32 v150, v150, v162
	v_and_b32_e32 v162, 0xffff0000, v170
	v_mul_f32_e32 v163, 0xbfb8aa3b, v162
	v_exp_f32_e32 v163, v163
	v_pk_mul_f32 v[6:7], v[6:7], v[38:39]
	v_pk_mul_f32 v[8:9], v[8:9], v[40:41]
	v_pk_mul_f32 v[2:3], v[2:3], v[34:35]
	v_add_f32_e32 v163, 1.0, v163
	v_rcp_f32_e32 v163, v163
	v_pk_mul_f32 v[4:5], v[4:5], v[36:37]
	v_mul_f32_e32 v162, v163, v162
	v_mul_f32_e32 v151, v151, v162
	v_cvt_pk_bf16_f32 v150, v150, v151
	v_lshlrev_b32_e32 v151, 16, v171
	v_mul_f32_e32 v162, 0xbfb8aa3b, v151
	v_exp_f32_e32 v162, v162
	s_nop 0
	v_add_f32_e32 v162, 1.0, v162
	v_rcp_f32_e32 v162, v162
	s_nop 0
; __device__ __forceinline__ unsigned cvt_pk_bf16(float lo, float hi) { unsigned r; asm volatile("v_cvt_pk_bf16_f32 %0, %1, %2" : "=v"(r) : "v"(lo), "v"(hi)); return r; }
; __device__ __forceinline__ float bf_lo(unsigned w) { return __uint_as_float(w << 16); }
; __device__ __forceinline__ float bf_hi(unsigned w) { return __uint_as_float(w & 0xffff0000u); }
; __device__ __forceinline__ float silu_f(float z) { return z * fast_rcp(1.0f + __builtin_amdgcn_exp2f(z * -1.44269504f)); }
;     __device__ __forceinline__ void operator()(const f32x4 (&acc)[2][2][4][2], const Unit& u, int wr, int wc, int fr, int fq, const Pre&) const {
;     ...
;             for (int ai = 0; ai < 2; ++ai)
; #pragma unroll
;                 for (int m = 0; m < 4; ++m) { const int r = row0 + ai * HALF + m * 16;
;                     const u32x4 zw = zv[ai * 4 + m];
;                     const f32x4 a0 = acc[ai][bj][m][0] * sc[bj][0], a1 = acc[ai][bj][m][1] * sc[bj][1];
;                     u32x4 w;
;                     w.x = cvt_pk_bf16(a0[0] * silu_f(bf_lo(zw.x)), a0[1] * silu_f(bf_hi(zw.x)));
;                     w.y = cvt_pk_bf16(a0[2] * silu_f(bf_lo(zw.y)), a0[3] * silu_f(bf_hi(zw.y)));
;                     w.z = cvt_pk_bf16(a1[0] * silu_f(bf_lo(zw.z)), a1[1] * silu_f(bf_hi(zw.z)));
;                     w.w = cvt_pk_bf16(a1[2] * silu_f(bf_lo(zw.w)), a1[3] * silu_f(bf_hi(zw.w)));
;                     *(u32x4*)(O + (size_t)r * DE + c) = w; } }
	v_mul_f32_e32 v151, v162, v151
	v_mul_f32_e32 v151, v152, v151
	v_and_b32_e32 v152, 0xffff0000, v171
	v_mul_f32_e32 v162, 0xbfb8aa3b, v152
	v_exp_f32_e32 v162, v162
	s_nop 0
	v_add_f32_e32 v162, 1.0, v162
	v_rcp_f32_e32 v162, v162
	s_nop 0
	v_mul_f32_e32 v152, v162, v152
	v_mul_f32_e32 v152, v153, v152
	v_cvt_pk_bf16_f32 v151, v151, v152
	v_lshlrev_b32_e32 v152, 16, v172
	v_mul_f32_e32 v153, 0xbfb8aa3b, v152
	v_exp_f32_e32 v153, v153
	s_nop 0
	v_add_f32_e32 v153, 1.0, v153
	v_rcp_f32_e32 v153, v153
	s_nop 0
	v_mul_f32_e32 v152, v153, v152
	v_mul_f32_e32 v146, v146, v152
	v_and_b32_e32 v152, 0xffff0000, v172
	v_mul_f32_e32 v153, 0xbfb8aa3b, v152
	v_exp_f32_e32 v153, v153
	s_nop 0
	v_add_f32_e32 v153, 1.0, v153
	v_rcp_f32_e32 v153, v153
	s_nop 0
	v_mul_f32_e32 v152, v153, v152
	v_mul_f32_e32 v147, v147, v152
	v_cvt_pk_bf16_f32 v152, v146, v147
	v_lshlrev_b32_e32 v146, 16, v173
	v_mul_f32_e32 v147, 0xbfb8aa3b, v146
	v_exp_f32_e32 v147, v147
	s_nop 0
	v_add_f32_e32 v147, 1.0, v147
	v_rcp_f32_e32 v147, v147
	s_nop 0
	v_mul_f32_e32 v146, v147, v146
	v_and_b32_e32 v147, 0xffff0000, v173
	v_mul_f32_e32 v146, v148, v146
	v_mul_f32_e32 v148, 0xbfb8aa3b, v147
	v_exp_f32_e32 v148, v148
	s_nop 0
	v_add_f32_e32 v148, 1.0, v148
	v_rcp_f32_e32 v148, v148
	s_nop 0
	v_mul_f32_e32 v147, v148, v147
	v_lshlrev_b32_e32 v148, 16, v158
	v_mul_f32_e32 v147, v149, v147
	v_mul_f32_e32 v149, 0xbfb8aa3b, v148
	v_exp_f32_e32 v149, v149
	v_cvt_pk_bf16_f32 v153, v146, v147
	v_lshlrev_b64 v[146:147], 13, v[224:225]
	v_lshl_add_u64 v[146:147], s[44:45], 0, v[146:147]
	v_add_f32_e32 v149, 1.0, v149
	v_rcp_f32_e32 v149, v149
	v_lshl_add_u64 v[146:147], v[146:147], 0, v[216:217]
	global_store_dwordx4 v[146:147], v[150:153], off
	v_mul_f32_e32 v148, v149, v148
	v_mul_f32_e32 v138, v138, v148
	v_and_b32_e32 v148, 0xffff0000, v158
	v_mul_f32_e32 v149, 0xbfb8aa3b, v148
	v_exp_f32_e32 v149, v149
	s_nop 0
	v_add_f32_e32 v149, 1.0, v149
	v_rcp_f32_e32 v149, v149
	s_nop 0
	v_mul_f32_e32 v148, v149, v148
	v_mul_f32_e32 v139, v139, v148
	v_cvt_pk_bf16_f32 v138, v138, v139
	v_lshlrev_b32_e32 v139, 16, v159
	v_mul_f32_e32 v148, 0xbfb8aa3b, v139
	v_exp_f32_e32 v148, v148
	s_nop 0
	v_add_f32_e32 v148, 1.0, v148
	v_rcp_f32_e32 v148, v148
	s_nop 0
	v_mul_f32_e32 v139, v148, v139
	v_mul_f32_e32 v139, v140, v139
	v_and_b32_e32 v140, 0xffff0000, v159
	v_mul_f32_e32 v148, 0xbfb8aa3b, v140
	v_exp_f32_e32 v148, v148
	s_nop 0
	v_add_f32_e32 v148, 1.0, v148
	v_rcp_f32_e32 v148, v148
	s_nop 0
	v_mul_f32_e32 v140, v148, v140
	v_mul_f32_e32 v140, v141, v140
	v_cvt_pk_bf16_f32 v139, v139, v140
	v_lshlrev_b32_e32 v140, 16, v160
	v_mul_f32_e32 v141, 0xbfb8aa3b, v140
	v_exp_f32_e32 v141, v141
	s_nop 0
	v_add_f32_e32 v141, 1.0, v141
	v_rcp_f32_e32 v141, v141
	s_nop 0
	v_mul_f32_e32 v140, v141, v140
	v_mul_f32_e32 v134, v134, v140
	v_and_b32_e32 v140, 0xffff0000, v160
	v_mul_f32_e32 v141, 0xbfb8aa3b, v140
	v_exp_f32_e32 v141, v141
	s_nop 0
	v_add_f32_e32 v141, 1.0, v141
	v_rcp_f32_e32 v141, v141
	s_nop 0
	v_mul_f32_e32 v140, v141, v140
	v_mul_f32_e32 v135, v135, v140
	v_cvt_pk_bf16_f32 v140, v134, v135
	v_lshlrev_b32_e32 v134, 16, v161
	v_mul_f32_e32 v135, 0xbfb8aa3b, v134
	v_exp_f32_e32 v135, v135
	s_nop 0
	v_add_f32_e32 v135, 1.0, v135
	v_rcp_f32_e32 v135, v135
	s_nop 0
	v_mul_f32_e32 v134, v135, v134
	v_and_b32_e32 v135, 0xffff0000, v161
	v_mul_f32_e32 v134, v136, v134
	v_mul_f32_e32 v136, 0xbfb8aa3b, v135
	v_exp_f32_e32 v136, v136
	s_nop 0
	v_add_f32_e32 v136, 1.0, v136
	v_rcp_f32_e32 v136, v136
	s_nop 0
	v_mul_f32_e32 v135, v136, v135
	v_lshlrev_b32_e32 v136, 16, v154
	v_mul_f32_e32 v135, v137, v135
	v_mul_f32_e32 v137, 0xbfb8aa3b, v136
	v_exp_f32_e32 v137, v137
	v_cvt_pk_bf16_f32 v141, v134, v135
	v_lshlrev_b64 v[134:135], 13, v[222:223]
	v_lshl_add_u64 v[134:135], s[44:45], 0, v[134:135]
	v_add_f32_e32 v137, 1.0, v137
	v_rcp_f32_e32 v137, v137
	v_lshl_add_u64 v[134:135], v[134:135], 0, v[216:217]
	global_store_dwordx4 v[134:135], v[138:141], off
	v_mul_f32_e32 v136, v137, v136
	v_mul_f32_e32 v126, v126, v136
	v_and_b32_e32 v136, 0xffff0000, v154
	v_mul_f32_e32 v137, 0xbfb8aa3b, v136
	v_exp_f32_e32 v137, v137
	s_nop 0
	v_add_f32_e32 v137, 1.0, v137
	v_rcp_f32_e32 v137, v137
	s_nop 0
	v_mul_f32_e32 v136, v137, v136
	v_mul_f32_e32 v127, v127, v136
	v_cvt_pk_bf16_f32 v126, v126, v127
	v_lshlrev_b32_e32 v127, 16, v155
	v_mul_f32_e32 v136, 0xbfb8aa3b, v127
	v_exp_f32_e32 v136, v136
	s_nop 0
	v_add_f32_e32 v136, 1.0, v136
	v_rcp_f32_e32 v136, v136
	s_nop 0
	v_mul_f32_e32 v127, v136, v127
	v_mul_f32_e32 v127, v128, v127
	v_and_b32_e32 v128, 0xffff0000, v155
	v_mul_f32_e32 v136, 0xbfb8aa3b, v128
	v_exp_f32_e32 v136, v136
	s_nop 0
	v_add_f32_e32 v136, 1.0, v136
	v_rcp_f32_e32 v136, v136
	s_nop 0
	v_mul_f32_e32 v128, v136, v128
	v_mul_f32_e32 v128, v129, v128
	v_cvt_pk_bf16_f32 v127, v127, v128
	v_lshlrev_b32_e32 v128, 16, v156
	v_mul_f32_e32 v129, 0xbfb8aa3b, v128
	v_exp_f32_e32 v129, v129
	s_nop 0
	v_add_f32_e32 v129, 1.0, v129
	v_rcp_f32_e32 v129, v129
	s_nop 0
	v_mul_f32_e32 v128, v129, v128
	v_mul_f32_e32 v122, v122, v128
	v_and_b32_e32 v128, 0xffff0000, v156
	v_mul_f32_e32 v129, 0xbfb8aa3b, v128
	v_exp_f32_e32 v129, v129
	s_nop 0
	v_add_f32_e32 v129, 1.0, v129
	v_rcp_f32_e32 v129, v129
	s_nop 0
	v_mul_f32_e32 v128, v129, v128
	v_mul_f32_e32 v123, v123, v128
	v_cvt_pk_bf16_f32 v128, v122, v123
	v_lshlrev_b32_e32 v122, 16, v157
	v_mul_f32_e32 v123, 0xbfb8aa3b, v122
	v_exp_f32_e32 v123, v123
	s_nop 0
	v_add_f32_e32 v123, 1.0, v123
	v_rcp_f32_e32 v123, v123
	s_nop 0
	v_mul_f32_e32 v122, v123, v122
	v_and_b32_e32 v123, 0xffff0000, v157
	v_mul_f32_e32 v122, v124, v122
	v_mul_f32_e32 v124, 0xbfb8aa3b, v123
; __device__ __forceinline__ unsigned cvt_pk_bf16(float lo, float hi) { unsigned r; asm volatile("v_cvt_pk_bf16_f32 %0, %1, %2" : "=v"(r) : "v"(lo), "v"(hi)); return r; }
; __device__ __forceinline__ float bf_lo(unsigned w) { return __uint_as_float(w << 16); }
; __device__ __forceinline__ float bf_hi(unsigned w) { return __uint_as_float(w & 0xffff0000u); }
; __device__ __forceinline__ float silu_f(float z) { return z * fast_rcp(1.0f + __builtin_amdgcn_exp2f(z * -1.44269504f)); }
;     __device__ __forceinline__ void operator()(const f32x4 (&acc)[2][2][4][2], const Unit& u, int wr, int wc, int fr, int fq, const Pre&) const {
;     ...
;             for (int ai = 0; ai < 2; ++ai)
; #pragma unroll
;                 for (int m = 0; m < 4; ++m) { const int r = row0 + ai * HALF + m * 16;
;                     const u32x4 zw = zv[ai * 4 + m];
;                     const f32x4 a0 = acc[ai][bj][m][0] * sc[bj][0], a1 = acc[ai][bj][m][1] * sc[bj][1];
;                     u32x4 w;
;                     w.x = cvt_pk_bf16(a0[0] * silu_f(bf_lo(zw.x)), a0[1] * silu_f(bf_hi(zw.x)));
;                     w.y = cvt_pk_bf16(a0[2] * silu_f(bf_lo(zw.y)), a0[3] * silu_f(bf_hi(zw.y)));
;                     w.z = cvt_pk_bf16(a1[0] * silu_f(bf_lo(zw.z)), a1[1] * silu_f(bf_hi(zw.z)));
;                     w.w = cvt_pk_bf16(a1[2] * silu_f(bf_lo(zw.w)), a1[3] * silu_f(bf_hi(zw.w)));
;                     *(u32x4*)(O + (size_t)r * DE + c) = w; } }
	v_exp_f32_e32 v124, v124
	s_nop 0
	v_add_f32_e32 v124, 1.0, v124
	v_rcp_f32_e32 v124, v124
	s_nop 0
	v_mul_f32_e32 v123, v124, v123
	v_lshlrev_b32_e32 v124, 16, v142
	v_mul_f32_e32 v123, v125, v123
	v_mul_f32_e32 v125, 0xbfb8aa3b, v124
	v_exp_f32_e32 v125, v125
	v_cvt_pk_bf16_f32 v129, v122, v123
	v_lshlrev_b64 v[122:123], 13, v[220:221]
	v_lshl_add_u64 v[122:123], s[44:45], 0, v[122:123]
	v_add_f32_e32 v125, 1.0, v125
	v_rcp_f32_e32 v125, v125
	v_lshl_add_u64 v[122:123], v[122:123], 0, v[216:217]
	global_store_dwordx4 v[122:123], v[126:129], off
	v_mul_f32_e32 v124, v125, v124
	v_mul_f32_e32 v114, v114, v124
	v_and_b32_e32 v124, 0xffff0000, v142
	v_mul_f32_e32 v125, 0xbfb8aa3b, v124
	v_exp_f32_e32 v125, v125
	s_nop 0
	v_add_f32_e32 v125, 1.0, v125
	v_rcp_f32_e32 v125, v125
	s_nop 0
	v_mul_f32_e32 v124, v125, v124
	v_mul_f32_e32 v115, v115, v124
	v_cvt_pk_bf16_f32 v114, v114, v115
	v_lshlrev_b32_e32 v115, 16, v143
	v_mul_f32_e32 v124, 0xbfb8aa3b, v115
	v_exp_f32_e32 v124, v124
	s_nop 0
	v_add_f32_e32 v124, 1.0, v124
	v_rcp_f32_e32 v124, v124
	s_nop 0
	v_mul_f32_e32 v115, v124, v115
	v_mul_f32_e32 v115, v116, v115
	v_and_b32_e32 v116, 0xffff0000, v143
	v_mul_f32_e32 v124, 0xbfb8aa3b, v116
	v_exp_f32_e32 v124, v124
	s_nop 0
	v_add_f32_e32 v124, 1.0, v124
	v_rcp_f32_e32 v124, v124
	s_nop 0
	v_mul_f32_e32 v116, v124, v116
	v_mul_f32_e32 v116, v117, v116
	v_cvt_pk_bf16_f32 v115, v115, v116
	v_lshlrev_b32_e32 v116, 16, v144
	v_mul_f32_e32 v117, 0xbfb8aa3b, v116
	v_exp_f32_e32 v117, v117
	s_nop 0
	v_add_f32_e32 v117, 1.0, v117
	v_rcp_f32_e32 v117, v117
	s_nop 0
	v_mul_f32_e32 v116, v117, v116
	v_mul_f32_e32 v110, v110, v116
	v_and_b32_e32 v116, 0xffff0000, v144
	v_mul_f32_e32 v117, 0xbfb8aa3b, v116
	v_exp_f32_e32 v117, v117
	s_nop 0
	v_add_f32_e32 v117, 1.0, v117
	v_rcp_f32_e32 v117, v117
	s_nop 0
	v_mul_f32_e32 v116, v117, v116
	v_mul_f32_e32 v111, v111, v116
	v_cvt_pk_bf16_f32 v116, v110, v111
	v_lshlrev_b32_e32 v110, 16, v145
	v_mul_f32_e32 v111, 0xbfb8aa3b, v110
	v_exp_f32_e32 v111, v111
	s_nop 0
	v_add_f32_e32 v111, 1.0, v111
	v_rcp_f32_e32 v111, v111
	s_nop 0
	v_mul_f32_e32 v110, v111, v110
	v_and_b32_e32 v111, 0xffff0000, v145
	v_mul_f32_e32 v110, v112, v110
	v_mul_f32_e32 v112, 0xbfb8aa3b, v111
	v_exp_f32_e32 v112, v112
	s_nop 0
	v_add_f32_e32 v112, 1.0, v112
	v_rcp_f32_e32 v112, v112
	s_nop 0
	v_mul_f32_e32 v111, v112, v111
	v_mul_f32_e32 v111, v113, v111
	v_cvt_pk_bf16_f32 v117, v110, v111
	v_lshlrev_b64 v[110:111], 13, v[218:219]
	v_lshl_add_u64 v[110:111], s[44:45], 0, v[110:111]
	v_lshl_add_u64 v[112:113], v[110:111], 0, v[216:217]
	v_lshlrev_b32_e32 v110, 16, v130
	v_mul_f32_e32 v111, 0xbfb8aa3b, v110
	v_exp_f32_e32 v111, v111
	global_store_dwordx4 v[112:113], v[114:117], off
	v_add_f32_e32 v111, 1.0, v111
	v_rcp_f32_e32 v111, v111
	s_nop 0
	v_mul_f32_e32 v110, v111, v110
	v_mul_f32_e32 v94, v94, v110
	v_and_b32_e32 v110, 0xffff0000, v130
	v_mul_f32_e32 v111, 0xbfb8aa3b, v110
	v_exp_f32_e32 v111, v111
	s_nop 0
	v_add_f32_e32 v111, 1.0, v111
	v_rcp_f32_e32 v111, v111
	s_nop 0
	v_mul_f32_e32 v110, v111, v110
	v_mul_f32_e32 v95, v95, v110
	v_cvt_pk_bf16_f32 v94, v94, v95
	v_lshlrev_b32_e32 v95, 16, v131
	v_mul_f32_e32 v110, 0xbfb8aa3b, v95
	v_exp_f32_e32 v110, v110
	s_nop 0
	v_add_f32_e32 v110, 1.0, v110
	v_rcp_f32_e32 v110, v110
	s_nop 0
	v_mul_f32_e32 v95, v110, v95
	v_mul_f32_e32 v95, v96, v95
	v_and_b32_e32 v96, 0xffff0000, v131
	v_mul_f32_e32 v110, 0xbfb8aa3b, v96
	v_exp_f32_e32 v110, v110
	s_nop 0
	v_add_f32_e32 v110, 1.0, v110
	v_rcp_f32_e32 v110, v110
	s_nop 0
	v_mul_f32_e32 v96, v110, v96
	v_mul_f32_e32 v96, v97, v96
	v_cvt_pk_bf16_f32 v95, v95, v96
	v_lshlrev_b32_e32 v96, 16, v132
	v_mul_f32_e32 v97, 0xbfb8aa3b, v96
	v_exp_f32_e32 v97, v97
	v_lshl_add_u64 v[110:111], v[166:167], 0, s[0:1]
	s_mov_b64 s[0:1], 0x140000
	v_lshl_add_u64 v[114:115], v[166:167], 0, s[0:1]
	v_add_f32_e32 v97, 1.0, v97
	v_rcp_f32_e32 v97, v97
	s_mov_b64 s[0:1], 0x160000
	v_mul_f32_e32 v96, v97, v96
	v_mul_f32_e32 v90, v90, v96
	v_and_b32_e32 v96, 0xffff0000, v132
	v_mul_f32_e32 v97, 0xbfb8aa3b, v96
	v_exp_f32_e32 v97, v97
	s_nop 0
	v_add_f32_e32 v97, 1.0, v97
	v_rcp_f32_e32 v97, v97
	s_nop 0
	v_mul_f32_e32 v96, v97, v96
	v_mul_f32_e32 v91, v91, v96
	v_cvt_pk_bf16_f32 v96, v90, v91
	v_lshlrev_b32_e32 v90, 16, v133
	v_mul_f32_e32 v91, 0xbfb8aa3b, v90
	v_exp_f32_e32 v91, v91
	s_nop 0
	v_add_f32_e32 v91, 1.0, v91
	v_rcp_f32_e32 v91, v91
	s_nop 0
	v_mul_f32_e32 v90, v91, v90
	v_and_b32_e32 v91, 0xffff0000, v133
	v_mul_f32_e32 v90, v92, v90
	v_mul_f32_e32 v92, 0xbfb8aa3b, v91
	v_exp_f32_e32 v92, v92
	s_nop 0
	v_add_f32_e32 v92, 1.0, v92
	v_rcp_f32_e32 v92, v92
	s_nop 0
	v_mul_f32_e32 v91, v92, v91
	v_mul_f32_e32 v91, v93, v91
	v_cvt_pk_bf16_f32 v97, v90, v91
	v_add_co_u32_e32 v90, vcc, s41, v166
	s_nop 1
	v_addc_co_u32_e32 v91, vcc, 0, v167, vcc
	global_store_dwordx4 v[90:91], v[94:97], off
	v_lshlrev_b32_e32 v90, 16, v118
	v_mul_f32_e32 v91, 0xbfb8aa3b, v90
	v_exp_f32_e32 v91, v91
	s_nop 0
	v_add_f32_e32 v91, 1.0, v91
	v_rcp_f32_e32 v91, v91
	s_nop 0
	v_mul_f32_e32 v90, v91, v90
	v_mul_f32_e32 v86, v86, v90
	v_and_b32_e32 v90, 0xffff0000, v118
	v_mul_f32_e32 v91, 0xbfb8aa3b, v90
	v_exp_f32_e32 v91, v91
	s_nop 0
	v_add_f32_e32 v91, 1.0, v91
	v_rcp_f32_e32 v91, v91
	s_nop 0
	v_mul_f32_e32 v90, v91, v90
	v_mul_f32_e32 v87, v87, v90
	v_cvt_pk_bf16_f32 v86, v86, v87
	v_lshlrev_b32_e32 v87, 16, v119
	v_mul_f32_e32 v90, 0xbfb8aa3b, v87
	v_exp_f32_e32 v90, v90
	s_nop 0
	v_add_f32_e32 v90, 1.0, v90
	v_rcp_f32_e32 v90, v90
	s_nop 0
	v_mul_f32_e32 v87, v90, v87
	v_mul_f32_e32 v87, v88, v87
	v_and_b32_e32 v88, 0xffff0000, v119
	v_mul_f32_e32 v90, 0xbfb8aa3b, v88
; __device__ __forceinline__ unsigned cvt_pk_bf16(float lo, float hi) { unsigned r; asm volatile("v_cvt_pk_bf16_f32 %0, %1, %2" : "=v"(r) : "v"(lo), "v"(hi)); return r; }
; __device__ __forceinline__ float bf_lo(unsigned w) { return __uint_as_float(w << 16); }
; __device__ __forceinline__ float bf_hi(unsigned w) { return __uint_as_float(w & 0xffff0000u); }
; __device__ __forceinline__ float silu_f(float z) { return z * fast_rcp(1.0f + __builtin_amdgcn_exp2f(z * -1.44269504f)); }
;     __device__ __forceinline__ void operator()(const f32x4 (&acc)[2][2][4][2], const Unit& u, int wr, int wc, int fr, int fq, const Pre&) const {
;     ...
;             for (int g8 = 0; g8 < 8; ++g8) zv[g8] = *(const u32x4*)(Z + (size_t)(row0 + (g8 >> 2) * HALF + (g8 & 3) * 16) * DE2 + c);
; #pragma unroll
;             for (int ai = 0; ai < 2; ++ai)
; #pragma unroll
;                 for (int m = 0; m < 4; ++m) { const int r = row0 + ai * HALF + m * 16;
;                     const u32x4 zw = zv[ai * 4 + m];
;                     const f32x4 a0 = acc[ai][bj][m][0] * sc[bj][0], a1 = acc[ai][bj][m][1] * sc[bj][1];
;                     u32x4 w;
;                     w.x = cvt_pk_bf16(a0[0] * silu_f(bf_lo(zw.x)), a0[1] * silu_f(bf_hi(zw.x)));
;                     w.y = cvt_pk_bf16(a0[2] * silu_f(bf_lo(zw.y)), a0[3] * silu_f(bf_hi(zw.y)));
;                     w.z = cvt_pk_bf16(a1[0] * silu_f(bf_lo(zw.z)), a1[1] * silu_f(bf_hi(zw.z)));
;                     w.w = cvt_pk_bf16(a1[2] * silu_f(bf_lo(zw.w)), a1[3] * silu_f(bf_hi(zw.w)));
;                     *(u32x4*)(O + (size_t)r * DE + c) = w; } }
	v_exp_f32_e32 v90, v90
	s_nop 0
	v_add_f32_e32 v90, 1.0, v90
	v_rcp_f32_e32 v90, v90
	s_nop 0
	v_mul_f32_e32 v88, v90, v88
	v_mul_f32_e32 v88, v89, v88
	v_cvt_pk_bf16_f32 v87, v87, v88
	v_lshlrev_b32_e32 v88, 16, v120
	v_mul_f32_e32 v89, 0xbfb8aa3b, v88
	v_exp_f32_e32 v89, v89
	s_nop 0
	v_add_f32_e32 v89, 1.0, v89
	v_rcp_f32_e32 v89, v89
	s_nop 0
	v_mul_f32_e32 v88, v89, v88
	v_mul_f32_e32 v82, v82, v88
	v_and_b32_e32 v88, 0xffff0000, v120
	v_mul_f32_e32 v89, 0xbfb8aa3b, v88
	v_exp_f32_e32 v89, v89
	s_nop 0
	v_add_f32_e32 v89, 1.0, v89
	v_rcp_f32_e32 v89, v89
	s_nop 0
	v_mul_f32_e32 v88, v89, v88
	v_mul_f32_e32 v83, v83, v88
	v_cvt_pk_bf16_f32 v88, v82, v83
	v_lshlrev_b32_e32 v82, 16, v121
	v_mul_f32_e32 v83, 0xbfb8aa3b, v82
	v_exp_f32_e32 v83, v83
	s_nop 0
	v_add_f32_e32 v83, 1.0, v83
	v_rcp_f32_e32 v83, v83
	s_nop 0
	v_mul_f32_e32 v82, v83, v82
	v_and_b32_e32 v83, 0xffff0000, v121
	v_mul_f32_e32 v82, v84, v82
	v_mul_f32_e32 v84, 0xbfb8aa3b, v83
	v_exp_f32_e32 v84, v84
	s_nop 0
	v_add_f32_e32 v84, 1.0, v84
	v_rcp_f32_e32 v84, v84
	s_nop 0
	v_mul_f32_e32 v83, v84, v83
	v_mul_f32_e32 v83, v85, v83
	v_cvt_pk_bf16_f32 v89, v82, v83
	v_add_co_u32_e32 v82, vcc, s65, v166
	s_nop 1
	v_addc_co_u32_e32 v83, vcc, 0, v167, vcc
	global_store_dwordx4 v[82:83], v[86:89], off
	v_lshlrev_b32_e32 v82, 16, v106
	v_mul_f32_e32 v83, 0xbfb8aa3b, v82
	v_exp_f32_e32 v83, v83
	s_nop 0
	v_add_f32_e32 v83, 1.0, v83
	v_rcp_f32_e32 v83, v83
	s_nop 0
	v_mul_f32_e32 v82, v83, v82
	v_mul_f32_e32 v78, v78, v82
	v_and_b32_e32 v82, 0xffff0000, v106
	v_mul_f32_e32 v83, 0xbfb8aa3b, v82
	v_exp_f32_e32 v83, v83
	s_nop 0
	v_add_f32_e32 v83, 1.0, v83
	v_rcp_f32_e32 v83, v83
	s_nop 0
	v_mul_f32_e32 v82, v83, v82
	v_mul_f32_e32 v79, v79, v82
	v_cvt_pk_bf16_f32 v78, v78, v79
	v_lshlrev_b32_e32 v79, 16, v107
	v_mul_f32_e32 v82, 0xbfb8aa3b, v79
	v_exp_f32_e32 v82, v82
	s_nop 0
	v_add_f32_e32 v82, 1.0, v82
	v_rcp_f32_e32 v82, v82
	s_nop 0
	v_mul_f32_e32 v79, v82, v79
	v_mul_f32_e32 v79, v80, v79
	v_and_b32_e32 v80, 0xffff0000, v107
	v_mul_f32_e32 v82, 0xbfb8aa3b, v80
	v_exp_f32_e32 v82, v82
	v_lshl_add_u64 v[106:107], v[166:167], 0, s[0:1]
	s_mov_b64 s[0:1], s[54:55]
	v_add_f32_e32 v82, 1.0, v82
	v_rcp_f32_e32 v82, v82
	s_nop 0
	v_mul_f32_e32 v80, v82, v80
	v_mul_f32_e32 v80, v81, v80
	v_cvt_pk_bf16_f32 v79, v79, v80
	v_lshlrev_b32_e32 v80, 16, v108
	v_mul_f32_e32 v81, 0xbfb8aa3b, v80
	v_exp_f32_e32 v81, v81
	s_nop 0
	v_add_f32_e32 v81, 1.0, v81
	v_rcp_f32_e32 v81, v81
	s_nop 0
	v_mul_f32_e32 v80, v81, v80
	v_mul_f32_e32 v74, v74, v80
	v_and_b32_e32 v80, 0xffff0000, v108
	v_mul_f32_e32 v81, 0xbfb8aa3b, v80
	v_exp_f32_e32 v81, v81
	s_nop 0
	v_add_f32_e32 v81, 1.0, v81
	v_rcp_f32_e32 v81, v81
	s_nop 0
	v_mul_f32_e32 v80, v81, v80
	v_mul_f32_e32 v75, v75, v80
	v_cvt_pk_bf16_f32 v80, v74, v75
	v_lshlrev_b32_e32 v74, 16, v109
	v_mul_f32_e32 v75, 0xbfb8aa3b, v74
	v_exp_f32_e32 v75, v75
	s_nop 0
	v_add_f32_e32 v75, 1.0, v75
	v_rcp_f32_e32 v75, v75
	s_nop 0
	v_mul_f32_e32 v74, v75, v74
	v_and_b32_e32 v75, 0xffff0000, v109
	v_mul_f32_e32 v74, v76, v74
	v_mul_f32_e32 v76, 0xbfb8aa3b, v75
	v_exp_f32_e32 v76, v76
	s_nop 0
	v_add_f32_e32 v76, 1.0, v76
	v_rcp_f32_e32 v76, v76
	s_nop 0
	v_mul_f32_e32 v75, v76, v75
	v_mul_f32_e32 v75, v77, v75
	v_cvt_pk_bf16_f32 v81, v74, v75
	v_add_co_u32_e32 v74, vcc, s70, v166
	v_lshl_add_u64 v[76:77], s[46:47], 0, v[204:205]
	s_nop 0
	v_addc_co_u32_e32 v75, vcc, 0, v167, vcc
	global_store_dwordx4 v[74:75], v[78:81], off
	v_or_b32_e32 v74, 0x80, v200
	v_ashrrev_i32_e32 v75, 31, v74
	v_lshlrev_b64 v[74:75], 1, v[74:75]
	v_lshl_add_u64 v[76:77], v[76:77], 0, v[74:75]
	global_load_dwordx4 v[102:105], v[76:77], off
	v_lshl_add_u64 v[76:77], s[46:47], 0, v[198:199]
	v_lshl_add_u64 v[76:77], v[76:77], 0, v[74:75]
	global_load_dwordx4 v[98:101], v[76:77], off
	v_lshl_add_u64 v[76:77], s[46:47], 0, v[202:203]
	v_lshl_add_u64 v[76:77], v[76:77], 0, v[74:75]
	global_load_dwordx4 v[94:97], v[76:77], off
	v_lshl_add_u64 v[76:77], s[46:47], 0, v[206:207]
	v_lshl_add_u64 v[76:77], v[76:77], 0, v[74:75]
	global_load_dwordx4 v[90:93], v[76:77], off
	v_lshl_add_u64 v[76:77], s[46:47], 0, v[208:209]
	v_lshl_add_u64 v[76:77], v[76:77], 0, v[74:75]
	global_load_dwordx4 v[86:89], v[76:77], off
	v_lshl_add_u64 v[76:77], s[46:47], 0, v[210:211]
	v_lshl_add_u64 v[76:77], v[76:77], 0, v[74:75]
	global_load_dwordx4 v[82:85], v[76:77], off
	v_lshl_add_u64 v[76:77], s[46:47], 0, v[212:213]
	v_lshl_add_u64 v[76:77], v[76:77], 0, v[74:75]
	global_load_dwordx4 v[78:81], v[76:77], off
	v_lshl_add_u64 v[76:77], s[46:47], 0, v[214:215]
	v_lshl_add_u64 v[74:75], v[76:77], 0, v[74:75]
	global_load_dwordx4 v[74:77], v[74:75], off
	s_and_b64 vcc, exec, s[42:43]
	s_waitcnt vmcnt(0)
; __device__ __forceinline__ unsigned cvt_pk_bf16(float lo, float hi) { unsigned r; asm volatile("v_cvt_pk_bf16_f32 %0, %1, %2" : "=v"(r) : "v"(lo), "v"(hi)); return r; }
; __device__ __forceinline__ float bf_lo(unsigned w) { return __uint_as_float(w << 16); }
; __device__ __forceinline__ float bf_hi(unsigned w) { return __uint_as_float(w & 0xffff0000u); }
; __device__ __forceinline__ float silu_f(float z) { return z * fast_rcp(1.0f + __builtin_amdgcn_exp2f(z * -1.44269504f)); }
;     __device__ __forceinline__ void operator()(const f32x4 (&acc)[2][2][4][2], const Unit& u, int wr, int wc, int fr, int fq, const Pre&) const {
;     ...
;             for (int ai = 0; ai < 2; ++ai)
; #pragma unroll
;                 for (int m = 0; m < 4; ++m) { const int r = row0 + ai * HALF + m * 16;
;                     const u32x4 zw = zv[ai * 4 + m];
;                     const f32x4 a0 = acc[ai][bj][m][0] * sc[bj][0], a1 = acc[ai][bj][m][1] * sc[bj][1];
;                     u32x4 w;
;                     w.x = cvt_pk_bf16(a0[0] * silu_f(bf_lo(zw.x)), a0[1] * silu_f(bf_hi(zw.x)));
;                     w.y = cvt_pk_bf16(a0[2] * silu_f(bf_lo(zw.y)), a0[3] * silu_f(bf_hi(zw.y)));
;                     w.z = cvt_pk_bf16(a1[0] * silu_f(bf_lo(zw.z)), a1[1] * silu_f(bf_hi(zw.z)));
;                     w.w = cvt_pk_bf16(a1[2] * silu_f(bf_lo(zw.w)), a1[3] * silu_f(bf_hi(zw.w)));
;                     *(u32x4*)(O + (size_t)r * DE + c) = w; } }
	v_lshlrev_b32_e32 v108, 16, v102
	v_mul_f32_e32 v109, 0xbfb8aa3b, v108
	v_exp_f32_e32 v109, v109
	v_and_b32_e32 v102, 0xffff0000, v102
	v_add_f32_e32 v109, 1.0, v109
	v_rcp_f32_e32 v109, v109
	s_nop 0
	v_mul_f32_e32 v108, v109, v108
	v_mul_f32_e32 v70, v70, v108
	v_mul_f32_e32 v108, 0xbfb8aa3b, v102
	v_exp_f32_e32 v108, v108
	s_nop 0
	v_add_f32_e32 v108, 1.0, v108
	v_rcp_f32_e32 v108, v108
	s_nop 0
	v_mul_f32_e32 v102, v108, v102
	v_mul_f32_e32 v71, v71, v102
	v_cvt_pk_bf16_f32 v70, v70, v71
	v_lshlrev_b32_e32 v71, 16, v103
	v_mul_f32_e32 v102, 0xbfb8aa3b, v71
	v_exp_f32_e32 v102, v102
	s_nop 0
	v_add_f32_e32 v102, 1.0, v102
	v_rcp_f32_e32 v102, v102
	s_nop 0
	v_mul_f32_e32 v71, v102, v71
	v_mul_f32_e32 v71, v72, v71
	v_and_b32_e32 v72, 0xffff0000, v103
	v_mul_f32_e32 v102, 0xbfb8aa3b, v72
	v_exp_f32_e32 v102, v102
	s_nop 0
	v_add_f32_e32 v102, 1.0, v102
	v_rcp_f32_e32 v102, v102
	s_nop 0
	v_mul_f32_e32 v72, v102, v72
	v_mul_f32_e32 v72, v73, v72
	v_cvt_pk_bf16_f32 v71, v71, v72
	v_lshlrev_b32_e32 v72, 16, v104
	v_mul_f32_e32 v73, 0xbfb8aa3b, v72
	v_exp_f32_e32 v73, v73
	s_nop 0
	v_add_f32_e32 v73, 1.0, v73
	v_rcp_f32_e32 v73, v73
	s_nop 0
	v_mul_f32_e32 v72, v73, v72
	v_mul_f32_e32 v66, v66, v72
	v_and_b32_e32 v72, 0xffff0000, v104
	v_mul_f32_e32 v73, 0xbfb8aa3b, v72
	v_exp_f32_e32 v73, v73
	s_nop 0
	v_add_f32_e32 v73, 1.0, v73
	v_rcp_f32_e32 v73, v73
	s_nop 0
	v_mul_f32_e32 v72, v73, v72
	v_mul_f32_e32 v67, v67, v72
	v_cvt_pk_bf16_f32 v72, v66, v67
	v_lshlrev_b32_e32 v66, 16, v105
	v_mul_f32_e32 v67, 0xbfb8aa3b, v66
	v_exp_f32_e32 v67, v67
	s_nop 0
	v_add_f32_e32 v67, 1.0, v67
	v_rcp_f32_e32 v67, v67
	s_nop 0
	v_mul_f32_e32 v66, v67, v66
	v_and_b32_e32 v67, 0xffff0000, v105
	v_mul_f32_e32 v66, v68, v66
	v_mul_f32_e32 v68, 0xbfb8aa3b, v67
	v_exp_f32_e32 v68, v68
	s_nop 0
	v_add_f32_e32 v68, 1.0, v68
	v_rcp_f32_e32 v68, v68
	s_nop 0
	v_mul_f32_e32 v67, v68, v67
	v_mul_f32_e32 v67, v69, v67
	v_cvt_pk_bf16_f32 v73, v66, v67
	v_lshlrev_b32_e32 v66, 16, v98
	v_mul_f32_e32 v67, 0xbfb8aa3b, v66
	v_exp_f32_e32 v67, v67
	global_store_dwordx4 v[166:167], v[70:73], off offset:256
	v_add_f32_e32 v67, 1.0, v67
	v_rcp_f32_e32 v67, v67
	s_nop 0
	v_mul_f32_e32 v66, v67, v66
	v_mul_f32_e32 v62, v62, v66
	v_and_b32_e32 v66, 0xffff0000, v98
	v_mul_f32_e32 v67, 0xbfb8aa3b, v66
	v_exp_f32_e32 v67, v67
	s_nop 0
	v_add_f32_e32 v67, 1.0, v67
	v_rcp_f32_e32 v67, v67
	s_nop 0
	v_mul_f32_e32 v66, v67, v66
	v_mul_f32_e32 v63, v63, v66
	v_cvt_pk_bf16_f32 v62, v62, v63
	v_lshlrev_b32_e32 v63, 16, v99
	v_mul_f32_e32 v66, 0xbfb8aa3b, v63
	v_exp_f32_e32 v66, v66
	s_nop 0
	v_add_f32_e32 v66, 1.0, v66
	v_rcp_f32_e32 v66, v66
	s_nop 0
	v_mul_f32_e32 v63, v66, v63
	v_mul_f32_e32 v63, v64, v63
	v_and_b32_e32 v64, 0xffff0000, v99
	v_mul_f32_e32 v66, 0xbfb8aa3b, v64
	v_exp_f32_e32 v66, v66
	s_nop 0
	v_add_f32_e32 v66, 1.0, v66
	v_rcp_f32_e32 v66, v66
	s_nop 0
	v_mul_f32_e32 v64, v66, v64
	v_mul_f32_e32 v64, v65, v64
	v_cvt_pk_bf16_f32 v63, v63, v64
	v_lshlrev_b32_e32 v64, 16, v100
	v_mul_f32_e32 v65, 0xbfb8aa3b, v64
	v_exp_f32_e32 v65, v65
	s_nop 0
	v_add_f32_e32 v65, 1.0, v65
	v_rcp_f32_e32 v65, v65
	s_nop 0
	v_mul_f32_e32 v64, v65, v64
	v_mul_f32_e32 v58, v58, v64
	v_and_b32_e32 v64, 0xffff0000, v100
	v_mul_f32_e32 v65, 0xbfb8aa3b, v64
	v_exp_f32_e32 v65, v65
	s_nop 0
	v_add_f32_e32 v65, 1.0, v65
	v_rcp_f32_e32 v65, v65
	s_nop 0
	v_mul_f32_e32 v64, v65, v64
	v_mul_f32_e32 v59, v59, v64
	v_cvt_pk_bf16_f32 v64, v58, v59
	v_lshlrev_b32_e32 v58, 16, v101
	v_mul_f32_e32 v59, 0xbfb8aa3b, v58
	v_exp_f32_e32 v59, v59
	s_nop 0
	v_add_f32_e32 v59, 1.0, v59
	v_rcp_f32_e32 v59, v59
	s_nop 0
	v_mul_f32_e32 v58, v59, v58
	v_and_b32_e32 v59, 0xffff0000, v101
	v_mul_f32_e32 v58, v60, v58
	v_mul_f32_e32 v60, 0xbfb8aa3b, v59
	v_exp_f32_e32 v60, v60
	s_nop 0
	v_add_f32_e32 v60, 1.0, v60
	v_rcp_f32_e32 v60, v60
	s_nop 0
	v_mul_f32_e32 v59, v60, v59
	v_mul_f32_e32 v59, v61, v59
	v_cvt_pk_bf16_f32 v65, v58, v59
	v_lshlrev_b32_e32 v58, 16, v94
	v_mul_f32_e32 v59, 0xbfb8aa3b, v58
	v_exp_f32_e32 v59, v59
	global_store_dwordx4 v[146:147], v[62:65], off offset:256
	v_add_f32_e32 v59, 1.0, v59
	v_rcp_f32_e32 v59, v59
	s_nop 0
	v_mul_f32_e32 v58, v59, v58
	v_mul_f32_e32 v54, v54, v58
	v_and_b32_e32 v58, 0xffff0000, v94
	v_mul_f32_e32 v59, 0xbfb8aa3b, v58
	v_exp_f32_e32 v59, v59
	s_nop 0
	v_add_f32_e32 v59, 1.0, v59
	v_rcp_f32_e32 v59, v59
	s_nop 0
	v_mul_f32_e32 v58, v59, v58
	v_mul_f32_e32 v55, v55, v58
	v_cvt_pk_bf16_f32 v54, v54, v55
	v_lshlrev_b32_e32 v55, 16, v95
	v_mul_f32_e32 v58, 0xbfb8aa3b, v55
	v_exp_f32_e32 v58, v58
	s_nop 0
	v_add_f32_e32 v58, 1.0, v58
	v_rcp_f32_e32 v58, v58
	s_nop 0
	v_mul_f32_e32 v55, v58, v55
	v_mul_f32_e32 v55, v56, v55
	v_and_b32_e32 v56, 0xffff0000, v95
	v_mul_f32_e32 v58, 0xbfb8aa3b, v56
	v_exp_f32_e32 v58, v58
	s_nop 0
	v_add_f32_e32 v58, 1.0, v58
	v_rcp_f32_e32 v58, v58
	s_nop 0
	v_mul_f32_e32 v56, v58, v56
	v_mul_f32_e32 v56, v57, v56
	v_cvt_pk_bf16_f32 v55, v55, v56
	v_lshlrev_b32_e32 v56, 16, v96
	v_mul_f32_e32 v57, 0xbfb8aa3b, v56
	v_exp_f32_e32 v57, v57
	s_nop 0
	v_add_f32_e32 v57, 1.0, v57
	v_rcp_f32_e32 v57, v57
	s_nop 0
	v_mul_f32_e32 v56, v57, v56
	v_mul_f32_e32 v50, v50, v56
	v_and_b32_e32 v56, 0xffff0000, v96
	v_mul_f32_e32 v57, 0xbfb8aa3b, v56
	v_exp_f32_e32 v57, v57
	s_nop 0
	v_add_f32_e32 v57, 1.0, v57
	v_rcp_f32_e32 v57, v57
	s_nop 0
	v_mul_f32_e32 v56, v57, v56
	v_mul_f32_e32 v51, v51, v56
	v_cvt_pk_bf16_f32 v56, v50, v51
	v_lshlrev_b32_e32 v50, 16, v97
	v_mul_f32_e32 v51, 0xbfb8aa3b, v50
	v_exp_f32_e32 v51, v51
	s_nop 0
	v_add_f32_e32 v51, 1.0, v51
	v_rcp_f32_e32 v51, v51
	s_nop 0
	v_mul_f32_e32 v50, v51, v50
	v_and_b32_e32 v51, 0xffff0000, v97
; __device__ __forceinline__ unsigned cvt_pk_bf16(float lo, float hi) { unsigned r; asm volatile("v_cvt_pk_bf16_f32 %0, %1, %2" : "=v"(r) : "v"(lo), "v"(hi)); return r; }
; __device__ __forceinline__ float bf_lo(unsigned w) { return __uint_as_float(w << 16); }
; __device__ __forceinline__ float bf_hi(unsigned w) { return __uint_as_float(w & 0xffff0000u); }
; __device__ __forceinline__ float silu_f(float z) { return z * fast_rcp(1.0f + __builtin_amdgcn_exp2f(z * -1.44269504f)); }
;     __device__ __forceinline__ void operator()(const f32x4 (&acc)[2][2][4][2], const Unit& u, int wr, int wc, int fr, int fq, const Pre&) const {
;     ...
;             for (int ai = 0; ai < 2; ++ai)
; #pragma unroll
;                 for (int m = 0; m < 4; ++m) { const int r = row0 + ai * HALF + m * 16;
;                     const u32x4 zw = zv[ai * 4 + m];
;                     const f32x4 a0 = acc[ai][bj][m][0] * sc[bj][0], a1 = acc[ai][bj][m][1] * sc[bj][1];
;                     u32x4 w;
;                     w.x = cvt_pk_bf16(a0[0] * silu_f(bf_lo(zw.x)), a0[1] * silu_f(bf_hi(zw.x)));
;                     w.y = cvt_pk_bf16(a0[2] * silu_f(bf_lo(zw.y)), a0[3] * silu_f(bf_hi(zw.y)));
;                     w.z = cvt_pk_bf16(a1[0] * silu_f(bf_lo(zw.z)), a1[1] * silu_f(bf_hi(zw.z)));
;                     w.w = cvt_pk_bf16(a1[2] * silu_f(bf_lo(zw.w)), a1[3] * silu_f(bf_hi(zw.w)));
;                     *(u32x4*)(O + (size_t)r * DE + c) = w; } }
	v_mul_f32_e32 v50, v52, v50
	v_mul_f32_e32 v52, 0xbfb8aa3b, v51
	v_exp_f32_e32 v52, v52
	s_nop 0
	v_add_f32_e32 v52, 1.0, v52
	v_rcp_f32_e32 v52, v52
	s_nop 0
	v_mul_f32_e32 v51, v52, v51
	v_mul_f32_e32 v51, v53, v51
	v_cvt_pk_bf16_f32 v57, v50, v51
	v_lshlrev_b32_e32 v50, 16, v90
	v_mul_f32_e32 v51, 0xbfb8aa3b, v50
	v_exp_f32_e32 v51, v51
	global_store_dwordx4 v[134:135], v[54:57], off offset:256
	v_add_f32_e32 v51, 1.0, v51
	v_rcp_f32_e32 v51, v51
	s_nop 0
	v_mul_f32_e32 v50, v51, v50
	v_mul_f32_e32 v46, v46, v50
	v_and_b32_e32 v50, 0xffff0000, v90
	v_mul_f32_e32 v51, 0xbfb8aa3b, v50
	v_exp_f32_e32 v51, v51
	s_nop 0
	v_add_f32_e32 v51, 1.0, v51
	v_rcp_f32_e32 v51, v51
	s_nop 0
	v_mul_f32_e32 v50, v51, v50
	v_mul_f32_e32 v47, v47, v50
	v_cvt_pk_bf16_f32 v46, v46, v47
	v_lshlrev_b32_e32 v47, 16, v91
	v_mul_f32_e32 v50, 0xbfb8aa3b, v47
	v_exp_f32_e32 v50, v50
	s_nop 0
	v_add_f32_e32 v50, 1.0, v50
	v_rcp_f32_e32 v50, v50
	s_nop 0
	v_mul_f32_e32 v47, v50, v47
	v_mul_f32_e32 v47, v48, v47
	v_and_b32_e32 v48, 0xffff0000, v91
	v_mul_f32_e32 v50, 0xbfb8aa3b, v48
	v_exp_f32_e32 v50, v50
	s_nop 0
	v_add_f32_e32 v50, 1.0, v50
	v_rcp_f32_e32 v50, v50
	s_nop 0
	v_mul_f32_e32 v48, v50, v48
	v_mul_f32_e32 v48, v49, v48
	v_cvt_pk_bf16_f32 v47, v47, v48
	v_lshlrev_b32_e32 v48, 16, v92
	v_mul_f32_e32 v49, 0xbfb8aa3b, v48
	v_exp_f32_e32 v49, v49
	s_nop 0
	v_add_f32_e32 v49, 1.0, v49
	v_rcp_f32_e32 v49, v49
	s_nop 0
	v_mul_f32_e32 v48, v49, v48
	v_mul_f32_e32 v42, v42, v48
	v_and_b32_e32 v48, 0xffff0000, v92
	v_mul_f32_e32 v49, 0xbfb8aa3b, v48
	v_exp_f32_e32 v49, v49
	s_nop 0
	v_add_f32_e32 v49, 1.0, v49
	v_rcp_f32_e32 v49, v49
	s_nop 0
	v_mul_f32_e32 v48, v49, v48
	v_mul_f32_e32 v43, v43, v48
	v_cvt_pk_bf16_f32 v48, v42, v43
	v_lshlrev_b32_e32 v42, 16, v93
	v_mul_f32_e32 v43, 0xbfb8aa3b, v42
	v_exp_f32_e32 v43, v43
	s_nop 0
	v_add_f32_e32 v43, 1.0, v43
	v_rcp_f32_e32 v43, v43
	s_nop 0
	v_mul_f32_e32 v42, v43, v42
	v_and_b32_e32 v43, 0xffff0000, v93
	v_mul_f32_e32 v42, v44, v42
	v_mul_f32_e32 v44, 0xbfb8aa3b, v43
	v_exp_f32_e32 v44, v44
	s_nop 0
	v_add_f32_e32 v44, 1.0, v44
	v_rcp_f32_e32 v44, v44
	s_nop 0
	v_mul_f32_e32 v43, v44, v43
	v_mul_f32_e32 v43, v45, v43
	v_cvt_pk_bf16_f32 v49, v42, v43
	v_lshlrev_b32_e32 v42, 16, v86
	v_mul_f32_e32 v43, 0xbfb8aa3b, v42
	v_exp_f32_e32 v43, v43
	global_store_dwordx4 v[122:123], v[46:49], off offset:256
	v_add_f32_e32 v43, 1.0, v43
	v_rcp_f32_e32 v43, v43
	s_nop 0
	v_mul_f32_e32 v42, v43, v42
	v_mul_f32_e32 v30, v30, v42
	v_and_b32_e32 v42, 0xffff0000, v86
	v_mul_f32_e32 v43, 0xbfb8aa3b, v42
	v_exp_f32_e32 v43, v43
	s_nop 0
	v_add_f32_e32 v43, 1.0, v43
	v_rcp_f32_e32 v43, v43
	s_nop 0
	v_mul_f32_e32 v42, v43, v42
	v_mul_f32_e32 v31, v31, v42
	v_cvt_pk_bf16_f32 v30, v30, v31
	v_lshlrev_b32_e32 v31, 16, v87
	v_mul_f32_e32 v42, 0xbfb8aa3b, v31
	v_exp_f32_e32 v42, v42
	s_nop 0
	v_add_f32_e32 v42, 1.0, v42
	v_rcp_f32_e32 v42, v42
	s_nop 0
	v_mul_f32_e32 v31, v42, v31
	v_mul_f32_e32 v31, v32, v31
	v_and_b32_e32 v32, 0xffff0000, v87
	v_mul_f32_e32 v42, 0xbfb8aa3b, v32
	v_exp_f32_e32 v42, v42
	s_nop 0
	v_add_f32_e32 v42, 1.0, v42
	v_rcp_f32_e32 v42, v42
	s_nop 0
	v_mul_f32_e32 v32, v42, v32
	v_mul_f32_e32 v32, v33, v32
	v_cvt_pk_bf16_f32 v31, v31, v32
	v_lshlrev_b32_e32 v32, 16, v88
	v_mul_f32_e32 v33, 0xbfb8aa3b, v32
	v_exp_f32_e32 v33, v33
	s_nop 0
	v_add_f32_e32 v33, 1.0, v33
	v_rcp_f32_e32 v33, v33
	s_nop 0
	v_mul_f32_e32 v32, v33, v32
	v_mul_f32_e32 v26, v26, v32
	v_and_b32_e32 v32, 0xffff0000, v88
	v_mul_f32_e32 v33, 0xbfb8aa3b, v32
	v_exp_f32_e32 v33, v33
	s_nop 0
	v_add_f32_e32 v33, 1.0, v33
	v_rcp_f32_e32 v33, v33
	s_nop 0
	v_mul_f32_e32 v32, v33, v32
	v_mul_f32_e32 v27, v27, v32
	v_cvt_pk_bf16_f32 v32, v26, v27
	v_lshlrev_b32_e32 v26, 16, v89
	v_mul_f32_e32 v27, 0xbfb8aa3b, v26
	v_exp_f32_e32 v27, v27
	s_nop 0
	v_add_f32_e32 v27, 1.0, v27
	v_rcp_f32_e32 v27, v27
	s_nop 0
	v_mul_f32_e32 v26, v27, v26
	v_and_b32_e32 v27, 0xffff0000, v89
	v_mul_f32_e32 v26, v28, v26
	v_mul_f32_e32 v28, 0xbfb8aa3b, v27
	v_exp_f32_e32 v28, v28
	s_nop 0
	v_add_f32_e32 v28, 1.0, v28
	v_rcp_f32_e32 v28, v28
	s_nop 0
	v_mul_f32_e32 v27, v28, v27
	v_mul_f32_e32 v27, v29, v27
	v_cvt_pk_bf16_f32 v33, v26, v27
	v_lshlrev_b32_e32 v26, 16, v82
	v_mul_f32_e32 v27, 0xbfb8aa3b, v26
	v_exp_f32_e32 v27, v27
	global_store_dwordx4 v[112:113], v[30:33], off offset:256
	v_add_f32_e32 v27, 1.0, v27
	v_rcp_f32_e32 v27, v27
	s_nop 0
	v_mul_f32_e32 v26, v27, v26
	v_mul_f32_e32 v22, v22, v26
	v_and_b32_e32 v26, 0xffff0000, v82
	v_mul_f32_e32 v27, 0xbfb8aa3b, v26
	v_exp_f32_e32 v27, v27
	s_nop 0
	v_add_f32_e32 v27, 1.0, v27
	v_rcp_f32_e32 v27, v27
	s_nop 0
	v_mul_f32_e32 v26, v27, v26
	v_mul_f32_e32 v23, v23, v26
	v_cvt_pk_bf16_f32 v22, v22, v23
	v_lshlrev_b32_e32 v23, 16, v83
	v_mul_f32_e32 v26, 0xbfb8aa3b, v23
	v_exp_f32_e32 v26, v26
	s_nop 0
	v_add_f32_e32 v26, 1.0, v26
	v_rcp_f32_e32 v26, v26
	s_nop 0
	v_mul_f32_e32 v23, v26, v23
	v_mul_f32_e32 v23, v24, v23
	v_and_b32_e32 v24, 0xffff0000, v83
	v_mul_f32_e32 v26, 0xbfb8aa3b, v24
	v_exp_f32_e32 v26, v26
	s_nop 0
	v_add_f32_e32 v26, 1.0, v26
	v_rcp_f32_e32 v26, v26
; __device__ __forceinline__ unsigned cvt_pk_bf16(float lo, float hi) { unsigned r; asm volatile("v_cvt_pk_bf16_f32 %0, %1, %2" : "=v"(r) : "v"(lo), "v"(hi)); return r; }
; __device__ __forceinline__ float bf_lo(unsigned w) { return __uint_as_float(w << 16); }
; __device__ __forceinline__ float bf_hi(unsigned w) { return __uint_as_float(w & 0xffff0000u); }
; __device__ __forceinline__ float silu_f(float z) { return z * fast_rcp(1.0f + __builtin_amdgcn_exp2f(z * -1.44269504f)); }
; #define PG8_WAIT_V(n) asm volatile("s_waitcnt vmcnt(" #n ")" ::: "memory")
; #define PG8_BAR __builtin_amdgcn_s_barrier()
; template <class Epi>
; __device__ __forceinline__ void gemm_phase(LAS unsigned char* lds, const Gemm g, const StaticOrder& S, const Epi& E) {
;     ...
;         if (!has_next) break;
; #pragma unroll
;         for (int a = 0; a < 2; ++a)
; #pragma unroll
;             for (int b = 0; b < 2; ++b)
; #pragma unroll
;                 for (int m = 0; m < 4; ++m)
; #pragma unroll
;                     for (int n = 0; n < 2; ++n) acc[a][b][m][n] = (f32x4){0.f, 0.f, 0.f, 0.f};
;         cur = nxt; cA = nA; cB = nB; ++ui;
;         pre = E.pre(cur, wr, fr);
;     }
;     PG8_WAIT_V(0);
;     if (wr == 0) PG8_BAR;
;     PG8_BAR;
;     __device__ __forceinline__ void operator()(const f32x4 (&acc)[2][2][4][2], const Unit& u, int wr, int wc, int fr, int fq, const Pre&) const {
;     ...
;             for (int ai = 0; ai < 2; ++ai)
; #pragma unroll
;                 for (int m = 0; m < 4; ++m) { const int r = row0 + ai * HALF + m * 16;
;                     const u32x4 zw = zv[ai * 4 + m];
;                     const f32x4 a0 = acc[ai][bj][m][0] * sc[bj][0], a1 = acc[ai][bj][m][1] * sc[bj][1];
;                     u32x4 w;
;                     w.x = cvt_pk_bf16(a0[0] * silu_f(bf_lo(zw.x)), a0[1] * silu_f(bf_hi(zw.x)));
;                     w.y = cvt_pk_bf16(a0[2] * silu_f(bf_lo(zw.y)), a0[3] * silu_f(bf_hi(zw.y)));
;                     w.z = cvt_pk_bf16(a1[0] * silu_f(bf_lo(zw.z)), a1[1] * silu_f(bf_hi(zw.z)));
;                     w.w = cvt_pk_bf16(a1[2] * silu_f(bf_lo(zw.w)), a1[3] * silu_f(bf_hi(zw.w)));
;                     *(u32x4*)(O + (size_t)r * DE + c) = w; } }
	s_nop 0
	v_mul_f32_e32 v24, v26, v24
	v_mul_f32_e32 v24, v25, v24
	v_cvt_pk_bf16_f32 v23, v23, v24
	v_lshlrev_b32_e32 v24, 16, v84
	v_mul_f32_e32 v25, 0xbfb8aa3b, v24
	v_exp_f32_e32 v25, v25
	s_nop 0
	v_add_f32_e32 v25, 1.0, v25
	v_rcp_f32_e32 v25, v25
	s_nop 0
	v_mul_f32_e32 v24, v25, v24
	v_mul_f32_e32 v18, v18, v24
	v_and_b32_e32 v24, 0xffff0000, v84
	v_mul_f32_e32 v25, 0xbfb8aa3b, v24
	v_exp_f32_e32 v25, v25
	s_nop 0
	v_add_f32_e32 v25, 1.0, v25
	v_rcp_f32_e32 v25, v25
	s_nop 0
	v_mul_f32_e32 v24, v25, v24
	v_mul_f32_e32 v19, v19, v24
	v_cvt_pk_bf16_f32 v24, v18, v19
	v_lshlrev_b32_e32 v18, 16, v85
	v_mul_f32_e32 v19, 0xbfb8aa3b, v18
	v_exp_f32_e32 v19, v19
	s_nop 0
	v_add_f32_e32 v19, 1.0, v19
	v_rcp_f32_e32 v19, v19
	s_nop 0
	v_mul_f32_e32 v18, v19, v18
	v_and_b32_e32 v19, 0xffff0000, v85
	v_mul_f32_e32 v18, v20, v18
	v_mul_f32_e32 v20, 0xbfb8aa3b, v19
	v_exp_f32_e32 v20, v20
	s_nop 0
	v_add_f32_e32 v20, 1.0, v20
	v_rcp_f32_e32 v20, v20
	s_nop 0
	v_mul_f32_e32 v19, v20, v19
	v_mul_f32_e32 v19, v21, v19
	v_cvt_pk_bf16_f32 v25, v18, v19
	v_lshlrev_b32_e32 v18, 16, v78
	v_mul_f32_e32 v19, 0xbfb8aa3b, v18
	v_exp_f32_e32 v19, v19
	global_store_dwordx4 v[110:111], v[22:25], off offset:256
	v_add_f32_e32 v19, 1.0, v19
	v_rcp_f32_e32 v19, v19
	s_nop 0
	v_mul_f32_e32 v18, v19, v18
	v_mul_f32_e32 v14, v14, v18
	v_and_b32_e32 v18, 0xffff0000, v78
	v_mul_f32_e32 v19, 0xbfb8aa3b, v18
	v_exp_f32_e32 v19, v19
	s_nop 0
	v_add_f32_e32 v19, 1.0, v19
	v_rcp_f32_e32 v19, v19
	s_nop 0
	v_mul_f32_e32 v18, v19, v18
	v_mul_f32_e32 v15, v15, v18
	v_cvt_pk_bf16_f32 v14, v14, v15
	v_lshlrev_b32_e32 v15, 16, v79
	v_mul_f32_e32 v18, 0xbfb8aa3b, v15
	v_exp_f32_e32 v18, v18
	s_nop 0
	v_add_f32_e32 v18, 1.0, v18
	v_rcp_f32_e32 v18, v18
	s_nop 0
	v_mul_f32_e32 v15, v18, v15
	v_mul_f32_e32 v15, v16, v15
	v_and_b32_e32 v16, 0xffff0000, v79
	v_mul_f32_e32 v18, 0xbfb8aa3b, v16
	v_exp_f32_e32 v18, v18
	s_nop 0
	v_add_f32_e32 v18, 1.0, v18
	v_rcp_f32_e32 v18, v18
	s_nop 0
	v_mul_f32_e32 v16, v18, v16
	v_mul_f32_e32 v16, v17, v16
	v_cvt_pk_bf16_f32 v15, v15, v16
	v_lshlrev_b32_e32 v16, 16, v80
	v_mul_f32_e32 v17, 0xbfb8aa3b, v16
	v_exp_f32_e32 v17, v17
	s_nop 0
	v_add_f32_e32 v17, 1.0, v17
	v_rcp_f32_e32 v17, v17
	s_nop 0
	v_mul_f32_e32 v16, v17, v16
	v_mul_f32_e32 v10, v10, v16
	v_and_b32_e32 v16, 0xffff0000, v80
	v_mul_f32_e32 v17, 0xbfb8aa3b, v16
	v_exp_f32_e32 v17, v17
	s_nop 0
	v_add_f32_e32 v17, 1.0, v17
	v_rcp_f32_e32 v17, v17
	s_nop 0
	v_mul_f32_e32 v16, v17, v16
	v_mul_f32_e32 v11, v11, v16
	v_cvt_pk_bf16_f32 v16, v10, v11
	v_lshlrev_b32_e32 v10, 16, v81
	v_mul_f32_e32 v11, 0xbfb8aa3b, v10
	v_exp_f32_e32 v11, v11
	s_nop 0
	v_add_f32_e32 v11, 1.0, v11
	v_rcp_f32_e32 v11, v11
	s_nop 0
	v_mul_f32_e32 v10, v11, v10
	v_and_b32_e32 v11, 0xffff0000, v81
	v_mul_f32_e32 v10, v12, v10
	v_mul_f32_e32 v12, 0xbfb8aa3b, v11
	v_exp_f32_e32 v12, v12
	s_nop 0
	v_add_f32_e32 v12, 1.0, v12
	v_rcp_f32_e32 v12, v12
	s_nop 0
	v_mul_f32_e32 v11, v12, v11
	v_mul_f32_e32 v11, v13, v11
	v_cvt_pk_bf16_f32 v17, v10, v11
	v_lshlrev_b32_e32 v10, 16, v74
	v_mul_f32_e32 v11, 0xbfb8aa3b, v10
	v_exp_f32_e32 v11, v11
	global_store_dwordx4 v[114:115], v[14:17], off offset:256
	v_add_f32_e32 v11, 1.0, v11
	v_rcp_f32_e32 v11, v11
	s_nop 0
	v_mul_f32_e32 v10, v11, v10
	v_mul_f32_e32 v6, v6, v10
	v_and_b32_e32 v10, 0xffff0000, v74
	v_mul_f32_e32 v11, 0xbfb8aa3b, v10
	v_exp_f32_e32 v11, v11
	s_nop 0
	v_add_f32_e32 v11, 1.0, v11
	v_rcp_f32_e32 v11, v11
	s_nop 0
	v_mul_f32_e32 v10, v11, v10
	v_mul_f32_e32 v7, v7, v10
	v_cvt_pk_bf16_f32 v6, v6, v7
	v_lshlrev_b32_e32 v7, 16, v75
	v_mul_f32_e32 v10, 0xbfb8aa3b, v7
	v_exp_f32_e32 v10, v10
	s_nop 0
	v_add_f32_e32 v10, 1.0, v10
	v_rcp_f32_e32 v10, v10
	s_nop 0
	v_mul_f32_e32 v7, v10, v7
	v_mul_f32_e32 v7, v8, v7
	v_and_b32_e32 v8, 0xffff0000, v75
	v_mul_f32_e32 v10, 0xbfb8aa3b, v8
	v_exp_f32_e32 v10, v10
	s_nop 0
	v_add_f32_e32 v10, 1.0, v10
	v_rcp_f32_e32 v10, v10
	s_nop 0
	v_mul_f32_e32 v8, v10, v8
	v_mul_f32_e32 v8, v9, v8
	v_cvt_pk_bf16_f32 v7, v7, v8
	v_lshlrev_b32_e32 v8, 16, v76
	v_mul_f32_e32 v9, 0xbfb8aa3b, v8
	v_exp_f32_e32 v9, v9
	s_nop 0
	v_add_f32_e32 v9, 1.0, v9
	v_rcp_f32_e32 v9, v9
	s_nop 0
	v_mul_f32_e32 v8, v9, v8
	v_mul_f32_e32 v2, v2, v8
	v_and_b32_e32 v8, 0xffff0000, v76
	v_mul_f32_e32 v9, 0xbfb8aa3b, v8
	v_exp_f32_e32 v9, v9
	s_nop 0
	v_add_f32_e32 v9, 1.0, v9
	v_rcp_f32_e32 v9, v9
	s_nop 0
	v_mul_f32_e32 v8, v9, v8
	v_mul_f32_e32 v3, v3, v8
	v_cvt_pk_bf16_f32 v8, v2, v3
	v_lshlrev_b32_e32 v2, 16, v77
	v_mul_f32_e32 v3, 0xbfb8aa3b, v2
	v_exp_f32_e32 v3, v3
	s_nop 0
	v_add_f32_e32 v3, 1.0, v3
	v_rcp_f32_e32 v3, v3
	s_nop 0
	v_mul_f32_e32 v2, v3, v2
	v_and_b32_e32 v3, 0xffff0000, v77
	v_mul_f32_e32 v2, v4, v2
	v_mul_f32_e32 v4, 0xbfb8aa3b, v3
	v_exp_f32_e32 v4, v4
	s_nop 0
	v_add_f32_e32 v4, 1.0, v4
	v_rcp_f32_e32 v4, v4
	s_nop 0
	v_mul_f32_e32 v3, v4, v3
	v_mul_f32_e32 v3, v5, v3
	v_cvt_pk_bf16_f32 v9, v2, v3
	global_store_dwordx4 v[106:107], v[6:9], off offset:256
	s_cbranch_vccz .LBB0_596
	s_waitcnt vmcnt(0)
	s_cmpk_gt_u32 s14, 0xff
	s_mov_b64 s[36:37], s[96:97]
	s_cbranch_scc1 .LBB0_607
	s_barrier

; #define PG8_STAGE(bufoff, gbase, voff) do { _Pragma("unroll") for (int _i = 0; _i < 2; ++_i) \
;         __builtin_amdgcn_global_load_lds((const unsigned*)((const char*)(gbase) + (voff)[_i]), (LAS unsigned*)(lds + (bufoff) + ldsw + _i * 8192), 16, 0, 0); } while (0)
; #define PG8_LDA(dst, b, h) do { _Pragma("unroll") for (int m = 0; m < 4; ++m) _Pragma("unroll") for (int k = 0; k < 2; ++k) dst[m][k] = *(const LAS bf16x8*)(lds + PG8_SA(b, h) + aoff + m * 2048 + k * 1024); } while (0)
; #define PG8_LDB(dst, b, h) do { _Pragma("unroll") for (int n = 0; n < 2; ++n) _Pragma("unroll") for (int k = 0; k < 2; ++k) dst[n][k] = *(const LAS bf16x8*)(lds + PG8_SB(b, h) + boff + n * 2048 + k * 1024); } while (0)
; #define PG8_MMA(ai, bj, At, Bt) do { __builtin_amdgcn_s_setprio(1); _Pragma("unroll") for (int m = 0; m < 4; ++m) _Pragma("unroll") for (int n = 0; n < 2; ++n) _Pragma("unroll") for (int k = 0; k < 2; ++k) \
;         acc[ai][bj][m][n] = __builtin_amdgcn_mfma_f32_16x16x32_bf16(Bt[n][k], At[m][k], acc[ai][bj][m][n], 0, 0, 0); __builtin_amdgcn_s_setprio(0); } while (0)
; #define PG8_WAIT_V(n) asm volatile("s_waitcnt vmcnt(" #n ")" ::: "memory")
; #define PG8_WAIT_L(n) asm volatile("s_waitcnt lgkmcnt(" #n ")" ::: "memory")
; #define PG8_BAR __builtin_amdgcn_s_barrier()
; #define PG8_SCHED __builtin_amdgcn_sched_barrier(0)
; template <class Epi>
; __device__ __forceinline__ void gemm_phase(LAS unsigned char* lds, const Gemm g, const StaticOrder& S, const Epi& E) {
;     ...
;             PG8_LDB(B0, 0, 0); PG8_SCHED; PG8_LDA(At, 0, 0); PG8_STAGE(PG8_SA(1, 1), a1 + hstepA, voffA);
;             PG8_WAIT_L(8); PG8_BAR; PG8_WAIT_L(0); PG8_MMA(0, 0, At, B0); PG8_BAR; PG8_SCHED;
;             PG8_LDB(B1, 0, 1); PG8_STAGE(PG8_SB(0, 0), b2, voffB);
;             PG8_BAR; PG8_WAIT_L(0); PG8_MMA(0, 1, At, B1); PG8_BAR;
;             PG8_LDA(At, 0, 1); PG8_STAGE(PG8_SA(0, 0), a2, voffA);
;             PG8_BAR; PG8_WAIT_L(0); PG8_MMA(1, 0, At, B0); PG8_BAR; PG8_SCHED;
;             PG8_STAGE(PG8_SB(0, 1), b2 + hstepB, voffB);
;             PG8_WAIT_V(6); PG8_BAR; PG8_MMA(1, 1, At, B1); PG8_BAR;
.LBB0_796:
	s_add_u32 s4, s8, 0x103400
	s_addc_u32 s5, s9, 0
	s_cmp_eq_u32 s57, 60
	s_cselect_b32 s16, s38, s4
	s_cselect_b32 s17, s37, s5
	s_cselect_b32 s4, s49, s51
	s_cselect_b32 s5, s39, s56
	s_add_u32 s14, s16, 0x104400
	s_addc_u32 s15, s17, 0
	s_add_i32 s58, 0, 0x10000
	ds_read_b128 v[26:29], v250
	ds_read_b128 v[30:33], v250 offset:1024
	ds_read_b128 v[98:101], v250 offset:2048
	ds_read_b128 v[102:105], v250 offset:3072
	s_add_i32 m0, s22, 0xc000
	ds_read_b128 v[130:133], v247
	ds_read_b128 v[146:149], v247 offset:2048
	ds_read_b128 v[154:157], v247 offset:4096
	ds_read_b128 v[170:173], v247 offset:6144
	ds_read_b128 v[142:145], v247 offset:1024
	ds_read_b128 v[150:153], v247 offset:3072
	ds_read_b128 v[166:169], v247 offset:5120
	ds_read_b128 v[174:177], v247 offset:7168
	global_load_lds_dwordx4 v196, s[8:9]
	s_add_i32 m0, s22, 0xe000
	s_nop 0
	global_load_lds_dwordx4 v198, s[8:9]
	s_waitcnt lgkmcnt(8)
	s_barrier
	s_waitcnt lgkmcnt(4)
	v_mfma_f32_16x16x32_bf16 v[162:165], v[26:29], v[130:133], v[162:165]
	v_mfma_f32_16x16x32_bf16 v[158:161], v[98:101], v[130:133], v[158:161]
	v_mfma_f32_16x16x32_bf16 v[138:141], v[26:29], v[146:149], v[138:141]
	v_mfma_f32_16x16x32_bf16 v[134:137], v[98:101], v[146:149], v[134:137]
	v_mfma_f32_16x16x32_bf16 v[126:129], v[26:29], v[154:157], v[126:129]
	v_mfma_f32_16x16x32_bf16 v[122:125], v[98:101], v[154:157], v[122:125]
	v_mfma_f32_16x16x32_bf16 v[118:121], v[26:29], v[170:173], v[118:121]
	v_mfma_f32_16x16x32_bf16 v[114:117], v[98:101], v[170:173], v[114:117]
	s_waitcnt lgkmcnt(0)
	v_mfma_f32_16x16x32_bf16 v[162:165], v[30:33], v[142:145], v[162:165]
	v_mfma_f32_16x16x32_bf16 v[158:161], v[102:105], v[142:145], v[158:161]
	v_mfma_f32_16x16x32_bf16 v[138:141], v[30:33], v[150:153], v[138:141]
	v_mfma_f32_16x16x32_bf16 v[134:137], v[102:105], v[150:153], v[134:137]
	v_mfma_f32_16x16x32_bf16 v[126:129], v[30:33], v[166:169], v[126:129]
	v_mfma_f32_16x16x32_bf16 v[122:125], v[102:105], v[166:169], v[122:125]
	v_mfma_f32_16x16x32_bf16 v[118:121], v[30:33], v[174:177], v[118:121]
	v_mfma_f32_16x16x32_bf16 v[114:117], v[102:105], v[174:177], v[114:117]
	s_barrier
	s_add_i32 s60, 0, 0x14000
	s_add_i32 s58, s58, s21
	s_add_u32 s100, s4, s6
	s_addc_u32 s101, s5, s7
	s_mov_b32 m0, s58
	ds_read_b128 v[184:187], v250 offset:16384
	ds_read_b128 v[204:207], v250 offset:18432
	ds_read_b128 v[200:203], v250 offset:17408
	ds_read_b128 v[208:211], v250 offset:19456
	global_load_lds_dwordx4 v0, s[4:5]
	s_add_i32 m0, s58, 0x2000
	s_nop 0
	global_load_lds_dwordx4 v188, s[4:5]
	s_barrier
	s_waitcnt lgkmcnt(2)
	v_mfma_f32_16x16x32_bf16 v[70:73], v[184:187], v[130:133], v[70:73]
	v_mfma_f32_16x16x32_bf16 v[66:69], v[204:207], v[130:133], v[66:69]
	v_mfma_f32_16x16x32_bf16 v[62:65], v[184:187], v[146:149], v[62:65]
	v_mfma_f32_16x16x32_bf16 v[58:61], v[204:207], v[146:149], v[58:61]
	v_mfma_f32_16x16x32_bf16 v[54:57], v[184:187], v[154:157], v[54:57]
	v_mfma_f32_16x16x32_bf16 v[50:53], v[204:207], v[154:157], v[50:53]
	v_mfma_f32_16x16x32_bf16 v[46:49], v[184:187], v[170:173], v[46:49]
	v_mfma_f32_16x16x32_bf16 v[42:45], v[204:207], v[170:173], v[42:45]
	s_waitcnt lgkmcnt(0)
	v_mfma_f32_16x16x32_bf16 v[70:73], v[200:203], v[142:145], v[70:73]
	v_mfma_f32_16x16x32_bf16 v[66:69], v[208:211], v[142:145], v[66:69]
	v_mfma_f32_16x16x32_bf16 v[62:65], v[200:203], v[150:153], v[62:65]
	v_mfma_f32_16x16x32_bf16 v[58:61], v[208:211], v[150:153], v[58:61]
	v_mfma_f32_16x16x32_bf16 v[54:57], v[200:203], v[166:169], v[54:57]
	v_mfma_f32_16x16x32_bf16 v[50:53], v[208:211], v[166:169], v[50:53]
	v_mfma_f32_16x16x32_bf16 v[46:49], v[200:203], v[174:177], v[46:49]
	v_mfma_f32_16x16x32_bf16 v[42:45], v[208:211], v[174:177], v[42:45]
	s_mov_b32 m0, s22
	s_barrier
	ds_read_b128 v[130:133], v247 offset:16384
	ds_read_b128 v[142:145], v247 offset:17408
	ds_read_b128 v[146:149], v247 offset:18432
	ds_read_b128 v[154:157], v247 offset:20480
	ds_read_b128 v[170:173], v247 offset:22528
	ds_read_b128 v[150:153], v247 offset:19456
	ds_read_b128 v[166:169], v247 offset:21504
	ds_read_b128 v[174:177], v247 offset:23552
	global_load_lds_dwordx4 v192, s[16:17]
	s_mov_b32 m0, s23
	s_nop 0
	global_load_lds_dwordx4 v190, s[16:17]
	s_barrier
	s_waitcnt lgkmcnt(3)
	v_mfma_f32_16x16x32_bf16 v[110:113], v[26:29], v[130:133], v[110:113]
	v_mfma_f32_16x16x32_bf16 v[106:109], v[98:101], v[130:133], v[106:109]
	v_mfma_f32_16x16x32_bf16 v[94:97], v[26:29], v[146:149], v[94:97]
	v_mfma_f32_16x16x32_bf16 v[90:93], v[98:101], v[146:149], v[90:93]
	v_mfma_f32_16x16x32_bf16 v[86:89], v[26:29], v[154:157], v[86:89]
	v_mfma_f32_16x16x32_bf16 v[82:85], v[98:101], v[154:157], v[82:85]
	v_mfma_f32_16x16x32_bf16 v[26:29], v[26:29], v[170:173], v[78:81]
	v_mfma_f32_16x16x32_bf16 v[110:113], v[30:33], v[142:145], v[110:113]
	s_waitcnt lgkmcnt(0)
	v_mfma_f32_16x16x32_bf16 v[106:109], v[102:105], v[142:145], v[106:109]
	v_mfma_f32_16x16x32_bf16 v[94:97], v[30:33], v[150:153], v[94:97]
	v_mfma_f32_16x16x32_bf16 v[90:93], v[102:105], v[150:153], v[90:93]
	v_mfma_f32_16x16x32_bf16 v[86:89], v[30:33], v[166:169], v[86:89]
	v_mfma_f32_16x16x32_bf16 v[82:85], v[102:105], v[166:169], v[82:85]
	v_mfma_f32_16x16x32_bf16 v[26:29], v[30:33], v[174:177], v[26:29]
	v_mfma_f32_16x16x32_bf16 v[30:33], v[98:101], v[170:173], v[74:77]
	v_mfma_f32_16x16x32_bf16 v[30:33], v[102:105], v[174:177], v[30:33]
	s_barrier
	s_add_u32 s58, s4, 0x100000
	s_addc_u32 s59, s5, 0
	s_add_i32 s60, s60, s21
	s_mov_b32 m0, s60
	s_nop 0
	global_load_lds_dwordx4 v0, s[58:59]
	s_add_i32 m0, s60, 0x2000
	s_nop 0
	global_load_lds_dwordx4 v188, s[58:59]
	s_waitcnt vmcnt(6)
	s_barrier
; #define PG8_STAGE(bufoff, gbase, voff) do { _Pragma("unroll") for (int _i = 0; _i < 2; ++_i) \
;         __builtin_amdgcn_global_load_lds((const unsigned*)((const char*)(gbase) + (voff)[_i]), (LAS unsigned*)(lds + (bufoff) + ldsw + _i * 8192), 16, 0, 0); } while (0)
; #define PG8_LDA(dst, b, h) do { _Pragma("unroll") for (int m = 0; m < 4; ++m) _Pragma("unroll") for (int k = 0; k < 2; ++k) dst[m][k] = *(const LAS bf16x8*)(lds + PG8_SA(b, h) + aoff + m * 2048 + k * 1024); } while (0)
; #define PG8_LDB(dst, b, h) do { _Pragma("unroll") for (int n = 0; n < 2; ++n) _Pragma("unroll") for (int k = 0; k < 2; ++k) dst[n][k] = *(const LAS bf16x8*)(lds + PG8_SB(b, h) + boff + n * 2048 + k * 1024); } while (0)
; #define PG8_MMA(ai, bj, At, Bt) do { __builtin_amdgcn_s_setprio(1); _Pragma("unroll") for (int m = 0; m < 4; ++m) _Pragma("unroll") for (int n = 0; n < 2; ++n) _Pragma("unroll") for (int k = 0; k < 2; ++k) \
;         acc[ai][bj][m][n] = __builtin_amdgcn_mfma_f32_16x16x32_bf16(Bt[n][k], At[m][k], acc[ai][bj][m][n], 0, 0, 0); __builtin_amdgcn_s_setprio(0); } while (0)
; #define PG8_WAIT_V(n) asm volatile("s_waitcnt vmcnt(" #n ")" ::: "memory")
; #define PG8_WAIT_L(n) asm volatile("s_waitcnt lgkmcnt(" #n ")" ::: "memory")
; #define PG8_BAR __builtin_amdgcn_s_barrier()
; #define PG8_SCHED __builtin_amdgcn_sched_barrier(0)
; template <class Epi>
; __device__ __forceinline__ void gemm_phase(LAS unsigned char* lds, const Gemm g, const StaticOrder& S, const Epi& E) {
;     ...
;             PG8_WAIT_V(6); PG8_BAR; PG8_MMA(1, 1, At, B1); PG8_BAR;
;             PG8_LDB(B0, 1, 0); PG8_SCHED; PG8_LDA(At, 1, 0); PG8_STAGE(PG8_SA(0, 1), a2 + hstepA, voffA);
;             PG8_WAIT_L(8); PG8_BAR; PG8_WAIT_L(0); PG8_MMA(0, 0, At, B0); PG8_BAR; PG8_SCHED;
;             PG8_LDB(B1, 1, 1); PG8_STAGE(PG8_SB(1, 0), b3, voffB);
;             PG8_BAR; PG8_WAIT_L(0); PG8_MMA(0, 1, At, B1); PG8_BAR;
;             PG8_LDA(At, 1, 1); PG8_STAGE(PG8_SA(1, 0), a3, voffA);
;             PG8_BAR; PG8_WAIT_L(0); PG8_MMA(1, 0, At, B0); PG8_BAR; PG8_SCHED;
	v_mfma_f32_16x16x32_bf16 v[38:41], v[184:187], v[130:133], v[38:41]
	v_mfma_f32_16x16x32_bf16 v[34:37], v[204:207], v[130:133], v[34:37]
	v_mfma_f32_16x16x32_bf16 v[22:25], v[184:187], v[146:149], v[22:25]
	v_mfma_f32_16x16x32_bf16 v[18:21], v[204:207], v[146:149], v[18:21]
	v_mfma_f32_16x16x32_bf16 v[14:17], v[184:187], v[154:157], v[14:17]
	v_mfma_f32_16x16x32_bf16 v[10:13], v[204:207], v[154:157], v[10:13]
	v_mfma_f32_16x16x32_bf16 v[6:9], v[184:187], v[170:173], v[6:9]
	v_mfma_f32_16x16x32_bf16 v[2:5], v[204:207], v[170:173], v[2:5]
	v_mfma_f32_16x16x32_bf16 v[38:41], v[200:203], v[142:145], v[38:41]
	v_mfma_f32_16x16x32_bf16 v[34:37], v[208:211], v[142:145], v[34:37]
	v_mfma_f32_16x16x32_bf16 v[22:25], v[200:203], v[150:153], v[22:25]
	v_mfma_f32_16x16x32_bf16 v[18:21], v[208:211], v[150:153], v[18:21]
	v_mfma_f32_16x16x32_bf16 v[14:17], v[200:203], v[166:169], v[14:17]
	v_mfma_f32_16x16x32_bf16 v[10:13], v[208:211], v[166:169], v[10:13]
	v_mfma_f32_16x16x32_bf16 v[6:9], v[200:203], v[174:177], v[6:9]
	v_mfma_f32_16x16x32_bf16 v[2:5], v[208:211], v[174:177], v[2:5]
	s_add_i32 s58, 0, 0x18000
	s_barrier
	ds_read_b128 v[74:77], v250 offset:32768
	ds_read_b128 v[78:81], v250 offset:33792
	ds_read_b128 v[98:101], v250 offset:34816
	ds_read_b128 v[102:105], v250 offset:35840
	s_add_u32 s16, s16, 0x1000
	s_addc_u32 s17, s17, 0
	s_mov_b32 m0, s24
	ds_read_b128 v[130:133], v247 offset:32768
	ds_read_b128 v[146:149], v247 offset:34816
	ds_read_b128 v[154:157], v247 offset:36864
	ds_read_b128 v[170:173], v247 offset:38912
	ds_read_b128 v[142:145], v247 offset:33792
	ds_read_b128 v[150:153], v247 offset:35840
	ds_read_b128 v[166:169], v247 offset:37888
	ds_read_b128 v[174:177], v247 offset:39936
	global_load_lds_dwordx4 v192, s[16:17]
	s_mov_b32 m0, s25
	s_nop 0
	global_load_lds_dwordx4 v190, s[16:17]
	s_waitcnt lgkmcnt(8)
	s_barrier
	s_waitcnt lgkmcnt(4)
	v_mfma_f32_16x16x32_bf16 v[162:165], v[74:77], v[130:133], v[162:165]
	v_mfma_f32_16x16x32_bf16 v[158:161], v[98:101], v[130:133], v[158:161]
	v_mfma_f32_16x16x32_bf16 v[138:141], v[74:77], v[146:149], v[138:141]
	v_mfma_f32_16x16x32_bf16 v[134:137], v[98:101], v[146:149], v[134:137]
	v_mfma_f32_16x16x32_bf16 v[126:129], v[74:77], v[154:157], v[126:129]
	v_mfma_f32_16x16x32_bf16 v[122:125], v[98:101], v[154:157], v[122:125]
	v_mfma_f32_16x16x32_bf16 v[118:121], v[74:77], v[170:173], v[118:121]
	v_mfma_f32_16x16x32_bf16 v[114:117], v[98:101], v[170:173], v[114:117]
	s_waitcnt lgkmcnt(0)
	v_mfma_f32_16x16x32_bf16 v[162:165], v[78:81], v[142:145], v[162:165]
	v_mfma_f32_16x16x32_bf16 v[158:161], v[102:105], v[142:145], v[158:161]
	v_mfma_f32_16x16x32_bf16 v[138:141], v[78:81], v[150:153], v[138:141]
	v_mfma_f32_16x16x32_bf16 v[134:137], v[102:105], v[150:153], v[134:137]
	v_mfma_f32_16x16x32_bf16 v[126:129], v[78:81], v[166:169], v[126:129]
	v_mfma_f32_16x16x32_bf16 v[122:125], v[102:105], v[166:169], v[122:125]
	v_mfma_f32_16x16x32_bf16 v[118:121], v[78:81], v[174:177], v[118:121]
	v_mfma_f32_16x16x32_bf16 v[114:117], v[102:105], v[174:177], v[114:117]
	s_barrier
	s_add_i32 s16, 0, 0x1c000
	s_add_i32 s17, s58, s21
	s_mov_b32 m0, s17
	ds_read_b128 v[184:187], v250 offset:49152
	ds_read_b128 v[204:207], v250 offset:51200
	ds_read_b128 v[200:203], v250 offset:50176
	ds_read_b128 v[208:211], v250 offset:52224
	global_load_lds_dwordx4 v0, s[100:101]
	s_add_i32 m0, s17, 0x2000
	s_nop 0
	global_load_lds_dwordx4 v188, s[100:101]
	s_barrier
	s_waitcnt lgkmcnt(2)
	v_mfma_f32_16x16x32_bf16 v[70:73], v[184:187], v[130:133], v[70:73]
	v_mfma_f32_16x16x32_bf16 v[66:69], v[204:207], v[130:133], v[66:69]
	v_mfma_f32_16x16x32_bf16 v[62:65], v[184:187], v[146:149], v[62:65]
	v_mfma_f32_16x16x32_bf16 v[58:61], v[204:207], v[146:149], v[58:61]
	v_mfma_f32_16x16x32_bf16 v[54:57], v[184:187], v[154:157], v[54:57]
	v_mfma_f32_16x16x32_bf16 v[50:53], v[204:207], v[154:157], v[50:53]
	v_mfma_f32_16x16x32_bf16 v[46:49], v[184:187], v[170:173], v[46:49]
	v_mfma_f32_16x16x32_bf16 v[42:45], v[204:207], v[170:173], v[42:45]
	s_waitcnt lgkmcnt(0)
	v_mfma_f32_16x16x32_bf16 v[70:73], v[200:203], v[142:145], v[70:73]
	v_mfma_f32_16x16x32_bf16 v[66:69], v[208:211], v[142:145], v[66:69]
	v_mfma_f32_16x16x32_bf16 v[62:65], v[200:203], v[150:153], v[62:65]
	v_mfma_f32_16x16x32_bf16 v[58:61], v[208:211], v[150:153], v[58:61]
	v_mfma_f32_16x16x32_bf16 v[54:57], v[200:203], v[166:169], v[54:57]
	v_mfma_f32_16x16x32_bf16 v[50:53], v[208:211], v[166:169], v[50:53]
	v_mfma_f32_16x16x32_bf16 v[46:49], v[200:203], v[174:177], v[46:49]
	v_mfma_f32_16x16x32_bf16 v[42:45], v[208:211], v[174:177], v[42:45]
	s_mov_b32 m0, s26
	s_barrier
	ds_read_b128 v[130:133], v247 offset:49152
	ds_read_b128 v[142:145], v247 offset:50176
	ds_read_b128 v[146:149], v247 offset:51200
	ds_read_b128 v[150:153], v247 offset:52224
	ds_read_b128 v[154:157], v247 offset:53248
	ds_read_b128 v[170:173], v247 offset:55296
	ds_read_b128 v[166:169], v247 offset:54272
	ds_read_b128 v[174:177], v247 offset:56320
	global_load_lds_dwordx4 v192, s[14:15]
	s_mov_b32 m0, s27
	s_nop 0
	global_load_lds_dwordx4 v190, s[14:15]
	s_barrier
; #define PG8_STAGE(bufoff, gbase, voff) do { _Pragma("unroll") for (int _i = 0; _i < 2; ++_i) \
;         __builtin_amdgcn_global_load_lds((const unsigned*)((const char*)(gbase) + (voff)[_i]), (LAS unsigned*)(lds + (bufoff) + ldsw + _i * 8192), 16, 0, 0); } while (0)
; #define PG8_MMA(ai, bj, At, Bt) do { __builtin_amdgcn_s_setprio(1); _Pragma("unroll") for (int m = 0; m < 4; ++m) _Pragma("unroll") for (int n = 0; n < 2; ++n) _Pragma("unroll") for (int k = 0; k < 2; ++k) \
;         acc[ai][bj][m][n] = __builtin_amdgcn_mfma_f32_16x16x32_bf16(Bt[n][k], At[m][k], acc[ai][bj][m][n], 0, 0, 0); __builtin_amdgcn_s_setprio(0); } while (0)
; #define PG8_WAIT_V(n) asm volatile("s_waitcnt vmcnt(" #n ")" ::: "memory")
; #define PG8_WAIT_L(n) asm volatile("s_waitcnt lgkmcnt(" #n ")" ::: "memory")
; #define PG8_BAR __builtin_amdgcn_s_barrier()
; #define PG8_SCHED __builtin_amdgcn_sched_barrier(0)
; template <class Epi>
; __device__ __forceinline__ void gemm_phase(LAS unsigned char* lds, const Gemm g, const StaticOrder& S, const Epi& E) {
;     ...
;             PG8_BAR; PG8_WAIT_L(0); PG8_MMA(1, 0, At, B0); PG8_BAR; PG8_SCHED;
;             PG8_STAGE(PG8_SB(1, 1), b3 + hstepB, voffB);
;             PG8_WAIT_V(6); PG8_BAR; PG8_MMA(1, 1, At, B1); PG8_BAR;
;     __device__ __forceinline__ void operator()(const f32x4 (&acc)[2][2][4][2], const Unit& u, int wr, int wc, int fr, int fq, const Pre&) const {
;         const int row0 = u.pm * BM + wr * 64 + fr, col0 = u.pn * BM + wc * 32 + 8 * fq;
;         f32x4 bs[2][2];
; #pragma unroll
;         for (int bj = 0; bj < 2; ++bj) { bs[bj][0] = *(const f32x4*)(bias + col0 + bj * HALF); bs[bj][1] = *(const f32x4*)(bias + col0 + bj * HALF + 4); }
; #pragma unroll
;         for (int bj = 0; bj < 2; ++bj) { const int c = col0 + bj * HALF;
; #pragma unroll
;             for (int ai = 0; ai < 2; ++ai) { u32x4 zv[4], gv[4];
; #pragma unroll
;                 for (int m = 0; m < 4; ++m) { const int r = row0 + ai * HALF + m * 16; zv[m] = *(const u32x4*)(Z + (size_t)r * DE2 + c); gv[m] = *(const u32x4*)(Gm + (size_t)(c >> 4) * GSTR + r * 16 + (c & 15)); }
	s_waitcnt lgkmcnt(2)
	v_mfma_f32_16x16x32_bf16 v[110:113], v[74:77], v[130:133], v[110:113]
	v_mfma_f32_16x16x32_bf16 v[94:97], v[74:77], v[146:149], v[94:97]
	v_mfma_f32_16x16x32_bf16 v[86:89], v[74:77], v[154:157], v[86:89]
	v_mfma_f32_16x16x32_bf16 v[26:29], v[74:77], v[170:173], v[26:29]
	v_mfma_f32_16x16x32_bf16 v[110:113], v[78:81], v[142:145], v[110:113]
	v_mfma_f32_16x16x32_bf16 v[106:109], v[98:101], v[130:133], v[106:109]
	v_mfma_f32_16x16x32_bf16 v[94:97], v[78:81], v[150:153], v[94:97]
	v_mfma_f32_16x16x32_bf16 v[90:93], v[98:101], v[146:149], v[90:93]
	s_waitcnt lgkmcnt(0)
	v_mfma_f32_16x16x32_bf16 v[86:89], v[78:81], v[166:169], v[86:89]
	v_mfma_f32_16x16x32_bf16 v[82:85], v[98:101], v[154:157], v[82:85]
	v_mfma_f32_16x16x32_bf16 v[78:81], v[78:81], v[174:177], v[26:29]
	v_mfma_f32_16x16x32_bf16 v[26:29], v[98:101], v[170:173], v[30:33]
	v_mfma_f32_16x16x32_bf16 v[106:109], v[102:105], v[142:145], v[106:109]
	v_mfma_f32_16x16x32_bf16 v[90:93], v[102:105], v[150:153], v[90:93]
	v_mfma_f32_16x16x32_bf16 v[82:85], v[102:105], v[166:169], v[82:85]
	v_mfma_f32_16x16x32_bf16 v[74:77], v[102:105], v[174:177], v[26:29]
	s_barrier
	s_add_u32 s4, s4, 0x100080
	s_addc_u32 s5, s5, 0
	s_add_i32 s14, s16, s21
	s_mov_b32 m0, s14
	s_nop 0
	global_load_lds_dwordx4 v0, s[4:5]
	s_add_i32 m0, s14, 0x2000
	s_nop 0
	global_load_lds_dwordx4 v188, s[4:5]
	s_waitcnt vmcnt(6)
	s_barrier
	v_mfma_f32_16x16x32_bf16 v[26:29], v[184:187], v[130:133], v[38:41]
	v_mfma_f32_16x16x32_bf16 v[38:41], v[200:203], v[142:145], v[26:29]
	v_mfma_f32_16x16x32_bf16 v[26:29], v[204:207], v[130:133], v[34:37]
	v_mfma_f32_16x16x32_bf16 v[22:25], v[184:187], v[146:149], v[22:25]
	v_mfma_f32_16x16x32_bf16 v[18:21], v[204:207], v[146:149], v[18:21]
	v_mfma_f32_16x16x32_bf16 v[14:17], v[184:187], v[154:157], v[14:17]
	v_mfma_f32_16x16x32_bf16 v[10:13], v[204:207], v[154:157], v[10:13]
	v_mfma_f32_16x16x32_bf16 v[6:9], v[184:187], v[170:173], v[6:9]
	v_mfma_f32_16x16x32_bf16 v[2:5], v[204:207], v[170:173], v[2:5]
	v_mfma_f32_16x16x32_bf16 v[34:37], v[208:211], v[142:145], v[26:29]
	v_mfma_f32_16x16x32_bf16 v[22:25], v[200:203], v[150:153], v[22:25]
	v_mfma_f32_16x16x32_bf16 v[18:21], v[208:211], v[150:153], v[18:21]
	v_mfma_f32_16x16x32_bf16 v[14:17], v[200:203], v[166:169], v[14:17]
	v_mfma_f32_16x16x32_bf16 v[10:13], v[208:211], v[166:169], v[10:13]
	v_mfma_f32_16x16x32_bf16 v[6:9], v[200:203], v[174:177], v[6:9]
	v_mfma_f32_16x16x32_bf16 v[2:5], v[208:211], v[174:177], v[2:5]
	s_add_i32 s57, s57, 2
	s_add_u32 s51, s51, 0x100
	s_addc_u32 s56, s56, 0
	s_add_u32 s8, s8, 0x208800
	s_addc_u32 s9, s9, 0
	s_cmp_gt_u32 s57, 61
	s_barrier
	s_cbranch_scc0 .LBB0_796
	v_lshl_or_b32 v200, s36, 8, v246
	v_ashrrev_i32_e32 v201, 31, v200
	v_lshl_add_u32 v224, s35, 8, v244
	v_lshlrev_b64 v[204:205], 1, v[200:201]
	v_ashrrev_i32_e32 v225, 31, v224
	v_ashrrev_i32_e32 v130, 4, v200
	v_lshl_add_u64 v[222:223], s[46:47], 0, v[204:205]
	v_lshlrev_b64 v[202:203], 14, v[224:225]
	v_lshl_add_u64 v[30:31], v[200:201], 2, s[10:11]
	v_mad_i64_i32 v[220:221], s[4:5], v130, s94, v[194:195]
	v_lshl_add_u64 v[130:131], v[222:223], 0, v[202:203]
	global_load_dwordx4 v[98:101], v[30:31], off offset:16
	global_load_dwordx4 v[102:105], v[30:31], off
	global_load_dwordx4 v[26:29], v[30:31], off offset:528
	s_nop 0
	global_load_dwordx4 v[30:33], v[30:31], off offset:512
	v_or_b32_e32 v226, 48, v224
	global_load_dwordx4 v[170:173], v[130:131], off
	v_lshlrev_b32_e32 v142, 4, v226
	v_ashrrev_i32_e32 v143, 31, v142
	v_lshlrev_b64 v[218:219], 1, v[142:143]
	v_lshl_add_u64 v[142:143], v[220:221], 0, v[218:219]
	global_load_dwordx4 v[142:145], v[142:143], off
	v_lshlrev_b32_e32 v130, 4, v224
	v_ashrrev_i32_e32 v131, 31, v130
	v_lshlrev_b64 v[206:207], 1, v[130:131]
	v_lshl_add_u64 v[130:131], v[220:221], 0, v[206:207]
	global_load_dwordx4 v[174:177], v[130:131], off
	v_or_b32_e32 v230, 16, v224
	v_ashrrev_i32_e32 v231, 31, v230
	v_lshlrev_b64 v[210:211], 14, v[230:231]
	v_lshl_add_u64 v[130:131], v[222:223], 0, v[210:211]
	global_load_dwordx4 v[154:157], v[130:131], off
	v_lshlrev_b32_e32 v130, 4, v230
	v_ashrrev_i32_e32 v131, 31, v130
	v_or_b32_e32 v228, 32, v224
	v_lshlrev_b64 v[208:209], 1, v[130:131]
	v_ashrrev_i32_e32 v229, 31, v228
	v_lshl_add_u64 v[130:131], v[220:221], 0, v[208:209]
	v_lshlrev_b64 v[214:215], 14, v[228:229]
	global_load_dwordx4 v[166:169], v[130:131], off
	v_lshl_add_u64 v[130:131], v[222:223], 0, v[214:215]
	global_load_dwordx4 v[146:149], v[130:131], off
	v_lshlrev_b32_e32 v130, 4, v228
	v_ashrrev_i32_e32 v131, 31, v130
	v_lshlrev_b64 v[212:213], 1, v[130:131]
	v_ashrrev_i32_e32 v227, 31, v226
	v_lshl_add_u64 v[130:131], v[220:221], 0, v[212:213]
	v_lshlrev_b64 v[216:217], 14, v[226:227]
	global_load_dwordx4 v[150:153], v[130:131], off
	v_lshl_add_u64 v[130:131], v[222:223], 0, v[216:217]
	global_load_dwordx4 v[130:133], v[130:131], off
	s_and_b64 vcc, exec, s[40:41]
	s_mov_b32 s35, s50
	s_mov_b32 s36, s48
	s_mov_b64 s[8:9], s[54:55]
	s_mov_b64 s[14:15], s[52:53]
	s_waitcnt vmcnt(0)
; __device__ __forceinline__ unsigned cvt_pk_bf16(float lo, float hi) { unsigned r; asm volatile("v_cvt_pk_bf16_f32 %0, %1, %2" : "=v"(r) : "v"(lo), "v"(hi)); return r; }
; __device__ __forceinline__ float bf_lo(unsigned w) { return __uint_as_float(w << 16); }
; __device__ __forceinline__ float bf_hi(unsigned w) { return __uint_as_float(w & 0xffff0000u); }
;     __device__ __forceinline__ void operator()(const f32x4 (&acc)[2][2][4][2], const Unit& u, int wr, int wc, int fr, int fq, const Pre&) const {
;     ...
;                 for (int m = 0; m < 4; ++m) { const int r = row0 + ai * HALF + m * 16;
;                     const u32x4 zw = zv[m], gw = gv[m];
;                     const f32x4 a0 = acc[ai][bj][m][0] + bs[bj][0], a1 = acc[ai][bj][m][1] + bs[bj][1];
;                     u32x4 w;
;                     w.x = cvt_pk_bf16(glu_gate_f(bf_lo(gw.x), a0[0], bf_lo(zw.x)), glu_gate_f(bf_hi(gw.x), a0[1], bf_hi(zw.x)));
;                     w.y = cvt_pk_bf16(glu_gate_f(bf_lo(gw.y), a0[2], bf_lo(zw.y)), glu_gate_f(bf_hi(gw.y), a0[3], bf_hi(zw.y)));
;                     w.z = cvt_pk_bf16(glu_gate_f(bf_lo(gw.z), a1[0], bf_lo(zw.z)), glu_gate_f(bf_hi(gw.z), a1[1], bf_hi(zw.z)));
;                     w.w = cvt_pk_bf16(glu_gate_f(bf_lo(gw.w), a1[2], bf_lo(zw.w)), glu_gate_f(bf_hi(gw.w), a1[3], bf_hi(zw.w)));
;                     *(u32x4*)(O + (size_t)r * DE + c) = w; } } }
	v_pk_add_f32 v[134:135], v[134:135], v[98:99]
	v_pk_add_f32 v[184:185], v[162:163], v[102:103]
	v_pk_add_f32 v[162:163], v[160:161], v[100:101]
	v_pk_add_f32 v[160:161], v[158:159], v[98:99]
	v_mul_f32_e32 v158, 0xbfb8aa3b, v184
	v_lshlrev_b32_e32 v186, 16, v170
	v_mul_f32_e32 v159, 0xbfb8aa3b, v186
	v_exp_f32_e32 v158, v158
	v_exp_f32_e32 v159, v159
	v_and_b32_e32 v170, 0xffff0000, v170
	v_pk_add_f32 v[164:165], v[164:165], v[104:105]
	v_mul_f32_e32 v160, 0xbfb8aa3b, v160
	v_pk_add_f32 v[158:159], v[158:159], 1.0 op_sel_hi:[1,0]
	v_mul_f32_e32 v164, 0xbfb8aa3b, v164
	v_mul_f32_e32 v158, v158, v159
	v_rcp_f32_e32 v158, v158
	v_lshlrev_b32_e32 v187, 16, v174
	v_mul_f32_e32 v184, v187, v186
	v_mul_f32_e32 v159, 0xbfb8aa3b, v170
	v_mul_f32_e32 v184, v184, v158
	v_mul_f32_e32 v158, 0xbfb8aa3b, v185
	v_exp_f32_e32 v158, v158
	v_exp_f32_e32 v159, v159
	v_and_b32_e32 v174, 0xffff0000, v174
	v_mul_f32_e32 v170, v174, v170
	v_mul_f32_e32 v162, 0xbfb8aa3b, v162
	v_pk_add_f32 v[158:159], v[158:159], 1.0 op_sel_hi:[1,0]
	v_pk_add_f32 v[138:139], v[138:139], v[102:103]
	v_mul_f32_e32 v158, v158, v159
	v_rcp_f32_e32 v158, v158
	v_lshlrev_b32_e32 v159, 16, v171
	v_and_b32_e32 v171, 0xffff0000, v171
	v_mul_f32_e32 v138, 0xbfb8aa3b, v138
	v_mul_f32_e32 v158, v170, v158
	v_cvt_pk_bf16_f32 v158, v184, v158
	v_exp_f32_e32 v184, v164
	v_mul_f32_e32 v164, 0xbfb8aa3b, v159
	v_exp_f32_e32 v185, v164
	v_lshlrev_b32_e32 v170, 16, v175
	v_mul_f32_e32 v159, v170, v159
	v_and_b32_e32 v170, 0xffff0000, v175
	v_pk_add_f32 v[184:185], v[184:185], 1.0 op_sel_hi:[1,0]
	v_mul_f32_e32 v170, v170, v171
	v_mul_f32_e32 v164, v184, v185
	v_rcp_f32_e32 v164, v164
	v_pk_add_f32 v[140:141], v[140:141], v[104:105]
	v_mul_f32_e32 v134, 0xbfb8aa3b, v134
	v_mul_f32_e32 v140, 0xbfb8aa3b, v140
	v_mul_f32_e32 v159, v159, v164
	v_mul_f32_e32 v164, 0xbfb8aa3b, v165
	v_mul_f32_e32 v165, 0xbfb8aa3b, v171
	v_exp_f32_e32 v164, v164
	v_exp_f32_e32 v165, v165
	v_lshlrev_b32_e32 v171, 16, v176
	v_pk_add_f32 v[136:137], v[136:137], v[100:101]
	v_pk_add_f32 v[126:127], v[126:127], v[102:103]
	v_pk_add_f32 v[164:165], v[164:165], 1.0 op_sel_hi:[1,0]
	v_mul_f32_e32 v126, 0xbfb8aa3b, v126
	v_mul_f32_e32 v164, v164, v165
	v_rcp_f32_e32 v164, v164
	v_pk_add_f32 v[128:129], v[128:129], v[104:105]
	v_pk_add_f32 v[122:123], v[122:123], v[98:99]
	v_mul_f32_e32 v128, 0xbfb8aa3b, v128
	v_mul_f32_e32 v164, v170, v164
	v_lshlrev_b32_e32 v170, 16, v172
	v_cvt_pk_bf16_f32 v159, v159, v164
	v_exp_f32_e32 v164, v160
	v_mul_f32_e32 v160, 0xbfb8aa3b, v170
	v_exp_f32_e32 v165, v160
	v_mul_f32_e32 v160, v171, v170
	v_and_b32_e32 v170, 0xffff0000, v172
	v_mul_f32_e32 v122, 0xbfb8aa3b, v122
	v_pk_add_f32 v[164:165], v[164:165], 1.0 op_sel_hi:[1,0]
	v_pk_add_f32 v[124:125], v[124:125], v[100:101]
	v_mul_f32_e32 v164, v164, v165
	v_rcp_f32_e32 v164, v164
	v_and_b32_e32 v165, 0xffff0000, v176
	v_mul_f32_e32 v165, v165, v170
	v_pk_add_f32 v[118:119], v[118:119], v[102:103]
	v_mul_f32_e32 v164, v160, v164
	v_mul_f32_e32 v160, 0xbfb8aa3b, v161
	v_mul_f32_e32 v161, 0xbfb8aa3b, v170
	v_exp_f32_e32 v160, v160
	v_exp_f32_e32 v161, v161
	v_lshlrev_b32_e32 v170, 16, v177
	v_mul_f32_e32 v118, 0xbfb8aa3b, v118
	v_pk_add_f32 v[120:121], v[120:121], v[104:105]
	v_pk_add_f32 v[160:161], v[160:161], 1.0 op_sel_hi:[1,0]
	v_mul_f32_e32 v120, 0xbfb8aa3b, v120
	v_mul_f32_e32 v160, v160, v161
	v_rcp_f32_e32 v160, v160
	v_lshlrev_b32_e32 v161, 16, v173
	v_pk_add_f32 v[114:115], v[114:115], v[98:99]
	v_pk_add_f32 v[116:117], v[116:117], v[100:101]
	v_mul_f32_e32 v160, v165, v160
	v_cvt_pk_bf16_f32 v160, v164, v160
	v_exp_f32_e32 v164, v162
	v_mul_f32_e32 v162, 0xbfb8aa3b, v161
	v_exp_f32_e32 v165, v162
	v_mul_f32_e32 v161, v170, v161
	v_mul_f32_e32 v114, 0xbfb8aa3b, v114
	v_add_u32_e32 v176, 0x80, v224
	v_pk_add_f32 v[164:165], v[164:165], 1.0 op_sel_hi:[1,0]
	v_add_u32_e32 v170, 0xb0, v224
	v_mul_f32_e32 v162, v164, v165
	v_rcp_f32_e32 v162, v162
	v_and_b32_e32 v165, 0xffff0000, v173
	v_and_b32_e32 v164, 0xffff0000, v177
	v_mul_f32_e32 v164, v164, v165
	v_mul_f32_e32 v161, v161, v162
	v_mul_f32_e32 v162, 0xbfb8aa3b, v163
	v_mul_f32_e32 v163, 0xbfb8aa3b, v165
	v_exp_f32_e32 v162, v162
	v_exp_f32_e32 v163, v163
	v_ashrrev_i32_e32 v177, 31, v176
	v_pk_add_f32 v[110:111], v[110:111], v[102:103]
	v_add_u32_e32 v174, 0x90, v224
	v_pk_add_f32 v[162:163], v[162:163], 1.0 op_sel_hi:[1,0]
	v_mul_f32_e32 v110, 0xbfb8aa3b, v110
	v_mul_f32_e32 v162, v162, v163
	v_rcp_f32_e32 v162, v162
	v_exp_f32_e32 v184, v110
	v_ashrrev_i32_e32 v175, 31, v174
	v_add_u32_e32 v172, 0xa0, v224
	v_mul_f32_e32 v162, v164, v162
	v_cvt_pk_bf16_f32 v161, v161, v162
	v_lshlrev_b64 v[162:163], 13, v[224:225]
	v_lshl_add_u64 v[162:163], s[44:45], 0, v[162:163]
	v_lshl_add_u64 v[162:163], v[162:163], 0, v[204:205]
	global_store_dwordx4 v[162:163], v[158:161], off
	v_ashrrev_i32_e32 v173, 31, v172
	v_ashrrev_i32_e32 v171, 31, v170
	v_lshlrev_b32_e32 v160, 16, v154
	v_exp_f32_e32 v158, v138
	v_mul_f32_e32 v138, 0xbfb8aa3b, v160
	v_exp_f32_e32 v159, v138
	v_lshlrev_b32_e32 v161, 16, v166
	v_mul_f32_e32 v138, v161, v160
	v_and_b32_e32 v154, 0xffff0000, v154
	v_pk_add_f32 v[158:159], v[158:159], 1.0 op_sel_hi:[1,0]
	v_lshlrev_b64 v[160:161], 14, v[172:173]
	v_mul_f32_e32 v158, v158, v159
	v_rcp_f32_e32 v158, v158
	v_and_b32_e32 v159, 0xffff0000, v166
	v_pk_add_f32 v[112:113], v[112:113], v[104:105]
	v_pk_add_f32 v[106:107], v[106:107], v[98:99]
	v_mul_f32_e32 v158, v138, v158
	v_mul_f32_e32 v138, 0xbfb8aa3b, v139
	v_mul_f32_e32 v139, 0xbfb8aa3b, v154
	v_exp_f32_e32 v138, v138
	v_exp_f32_e32 v139, v139
	v_mul_f32_e32 v154, v159, v154
	v_mul_f32_e32 v112, 0xbfb8aa3b, v112
; __device__ __forceinline__ unsigned cvt_pk_bf16(float lo, float hi) { unsigned r; asm volatile("v_cvt_pk_bf16_f32 %0, %1, %2" : "=v"(r) : "v"(lo), "v"(hi)); return r; }
; __device__ __forceinline__ float bf_lo(unsigned w) { return __uint_as_float(w << 16); }
; __device__ __forceinline__ float bf_hi(unsigned w) { return __uint_as_float(w & 0xffff0000u); }
;     __device__ __forceinline__ void operator()(const f32x4 (&acc)[2][2][4][2], const Unit& u, int wr, int wc, int fr, int fq, const Pre&) const {
;     ...
;                 for (int m = 0; m < 4; ++m) { const int r = row0 + ai * HALF + m * 16;
;                     const u32x4 zw = zv[m], gw = gv[m];
;                     const f32x4 a0 = acc[ai][bj][m][0] + bs[bj][0], a1 = acc[ai][bj][m][1] + bs[bj][1];
;                     u32x4 w;
;                     w.x = cvt_pk_bf16(glu_gate_f(bf_lo(gw.x), a0[0], bf_lo(zw.x)), glu_gate_f(bf_hi(gw.x), a0[1], bf_hi(zw.x)));
;                     w.y = cvt_pk_bf16(glu_gate_f(bf_lo(gw.y), a0[2], bf_lo(zw.y)), glu_gate_f(bf_hi(gw.y), a0[3], bf_hi(zw.y)));
;                     w.z = cvt_pk_bf16(glu_gate_f(bf_lo(gw.z), a1[0], bf_lo(zw.z)), glu_gate_f(bf_hi(gw.z), a1[1], bf_hi(zw.z)));
;                     w.w = cvt_pk_bf16(glu_gate_f(bf_lo(gw.w), a1[2], bf_lo(zw.w)), glu_gate_f(bf_hi(gw.w), a1[3], bf_hi(zw.w)));
;                     *(u32x4*)(O + (size_t)r * DE + c) = w; } } }
	v_mul_f32_e32 v106, 0xbfb8aa3b, v106
	v_pk_add_f32 v[138:139], v[138:139], 1.0 op_sel_hi:[1,0]
	v_pk_add_f32 v[108:109], v[108:109], v[100:101]
	v_mul_f32_e32 v138, v138, v139
	v_rcp_f32_e32 v138, v138
	v_lshlrev_b32_e32 v139, 16, v155
	v_and_b32_e32 v155, 0xffff0000, v155
	v_pk_add_f32 v[94:95], v[94:95], v[102:103]
	v_mul_f32_e32 v138, v154, v138
	v_cvt_pk_bf16_f32 v138, v158, v138
	v_exp_f32_e32 v158, v140
	v_mul_f32_e32 v140, 0xbfb8aa3b, v139
	v_exp_f32_e32 v159, v140
	v_lshlrev_b32_e32 v154, 16, v167
	v_mul_f32_e32 v139, v154, v139
	v_and_b32_e32 v154, 0xffff0000, v167
	v_pk_add_f32 v[158:159], v[158:159], 1.0 op_sel_hi:[1,0]
	v_mul_f32_e32 v154, v154, v155
	v_mul_f32_e32 v140, v158, v159
	v_rcp_f32_e32 v140, v140
	v_lshlrev_b64 v[166:167], 14, v[170:171]
	v_mul_f32_e32 v94, 0xbfb8aa3b, v94
	v_pk_add_f32 v[96:97], v[96:97], v[104:105]
	v_mul_f32_e32 v139, v139, v140
	v_mul_f32_e32 v140, 0xbfb8aa3b, v141
	v_mul_f32_e32 v141, 0xbfb8aa3b, v155
	v_exp_f32_e32 v140, v140
	v_exp_f32_e32 v141, v141
	v_lshlrev_b32_e32 v155, 16, v168
	v_mul_f32_e32 v96, 0xbfb8aa3b, v96
	v_pk_add_f32 v[90:91], v[90:91], v[98:99]
	v_pk_add_f32 v[140:141], v[140:141], 1.0 op_sel_hi:[1,0]
	v_mul_f32_e32 v90, 0xbfb8aa3b, v90
	v_mul_f32_e32 v140, v140, v141
	v_rcp_f32_e32 v140, v140
	v_pk_add_f32 v[92:93], v[92:93], v[100:101]
	v_pk_add_f32 v[86:87], v[86:87], v[102:103]
	v_pk_add_f32 v[88:89], v[88:89], v[104:105]
	v_mul_f32_e32 v140, v154, v140
	v_lshlrev_b32_e32 v154, 16, v156
	v_cvt_pk_bf16_f32 v139, v139, v140
	v_exp_f32_e32 v140, v134
	v_mul_f32_e32 v134, 0xbfb8aa3b, v154
	v_exp_f32_e32 v141, v134
	v_mul_f32_e32 v134, v155, v154
	v_and_b32_e32 v154, 0xffff0000, v156
	v_mul_f32_e32 v86, 0xbfb8aa3b, v86
	v_pk_add_f32 v[140:141], v[140:141], 1.0 op_sel_hi:[1,0]
	v_mul_f32_e32 v88, 0xbfb8aa3b, v88
	v_mul_f32_e32 v140, v140, v141
	v_rcp_f32_e32 v140, v140
	v_and_b32_e32 v141, 0xffff0000, v168
	v_mul_f32_e32 v141, v141, v154
	v_pk_add_f32 v[82:83], v[82:83], v[98:99]
	v_mul_f32_e32 v140, v134, v140
	v_mul_f32_e32 v134, 0xbfb8aa3b, v135
	v_mul_f32_e32 v135, 0xbfb8aa3b, v154
	v_exp_f32_e32 v134, v134
	v_exp_f32_e32 v135, v135
	v_lshlrev_b32_e32 v154, 16, v169
	v_mul_f32_e32 v82, 0xbfb8aa3b, v82
	v_pk_add_f32 v[84:85], v[84:85], v[100:101]
	v_pk_add_f32 v[134:135], v[134:135], 1.0 op_sel_hi:[1,0]
	v_pk_add_f32 v[78:79], v[78:79], v[102:103]
	v_mul_f32_e32 v134, v134, v135
	v_rcp_f32_e32 v134, v134
	v_mul_f32_e32 v78, 0xbfb8aa3b, v78
	v_pk_add_f32 v[80:81], v[80:81], v[104:105]
	v_pk_add_f32 v[74:75], v[74:75], v[98:99]
	v_mul_f32_e32 v134, v141, v134
	v_lshlrev_b32_e32 v141, 16, v157
	v_cvt_pk_bf16_f32 v140, v140, v134
	v_mul_f32_e32 v134, 0xbfb8aa3b, v136
	v_mul_f32_e32 v135, 0xbfb8aa3b, v141
	v_exp_f32_e32 v134, v134
	v_exp_f32_e32 v135, v135
	v_mul_f32_e32 v136, v154, v141
	v_and_b32_e32 v154, 0xffff0000, v157
	v_and_b32_e32 v141, 0xffff0000, v169
	v_pk_add_f32 v[134:135], v[134:135], 1.0 op_sel_hi:[1,0]
	v_lshlrev_b64 v[156:157], 14, v[174:175]
	v_mul_f32_e32 v134, v134, v135
	v_rcp_f32_e32 v134, v134
	v_mul_f32_e32 v135, 0xbfb8aa3b, v154
	v_exp_f32_e32 v135, v135
	v_mul_f32_e32 v80, 0xbfb8aa3b, v80
	v_mul_f32_e32 v136, v136, v134
	v_mul_f32_e32 v134, 0xbfb8aa3b, v137
	v_exp_f32_e32 v134, v134
	v_mul_f32_e32 v137, v141, v154
	v_mul_f32_e32 v74, 0xbfb8aa3b, v74
	v_pk_add_f32 v[76:77], v[76:77], v[100:101]
	v_pk_add_f32 v[134:135], v[134:135], 1.0 op_sel_hi:[1,0]
	v_pk_add_f32 v[70:71], v[70:71], v[30:31]
	v_mul_f32_e32 v134, v134, v135
	v_rcp_f32_e32 v134, v134
	v_mul_f32_e32 v70, 0xbfb8aa3b, v70
	v_pk_add_f32 v[72:73], v[72:73], v[32:33]
	v_pk_add_f32 v[66:67], v[66:67], v[26:27]
	v_mul_f32_e32 v134, v137, v134
	v_cvt_pk_bf16_f32 v141, v136, v134
	v_lshlrev_b64 v[134:135], 13, v[230:231]
	v_lshl_add_u64 v[134:135], s[44:45], 0, v[134:135]
	v_lshlrev_b32_e32 v136, 16, v146
	v_lshl_add_u64 v[154:155], v[134:135], 0, v[204:205]
	v_exp_f32_e32 v134, v126
	v_mul_f32_e32 v126, 0xbfb8aa3b, v136
	v_exp_f32_e32 v135, v126
	v_lshlrev_b32_e32 v137, 16, v150
	v_mul_f32_e32 v126, v137, v136
	v_and_b32_e32 v136, 0xffff0000, v146
	v_pk_add_f32 v[134:135], v[134:135], 1.0 op_sel_hi:[1,0]
	global_store_dwordx4 v[154:155], v[138:141], off
	v_mul_f32_e32 v134, v134, v135
	v_rcp_f32_e32 v134, v134
	v_and_b32_e32 v135, 0xffff0000, v150
	v_mul_f32_e32 v135, v135, v136
	v_mul_f32_e32 v72, 0xbfb8aa3b, v72
	v_mul_f32_e32 v134, v126, v134
	v_mul_f32_e32 v126, 0xbfb8aa3b, v127
	v_mul_f32_e32 v127, 0xbfb8aa3b, v136
	v_exp_f32_e32 v126, v126
	v_exp_f32_e32 v127, v127
	v_lshlrev_b32_e32 v136, 16, v151
	v_mul_f32_e32 v66, 0xbfb8aa3b, v66
	v_pk_add_f32 v[68:69], v[68:69], v[28:29]
	v_pk_add_f32 v[126:127], v[126:127], 1.0 op_sel_hi:[1,0]
	v_pk_add_f32 v[62:63], v[62:63], v[30:31]
	v_mul_f32_e32 v126, v126, v127
	v_rcp_f32_e32 v126, v126
	v_lshlrev_b32_e32 v127, 16, v147
	v_mul_f32_e32 v62, 0xbfb8aa3b, v62
	v_pk_add_f32 v[64:65], v[64:65], v[32:33]
	v_mul_f32_e32 v126, v135, v126
	v_cvt_pk_bf16_f32 v126, v134, v126
	v_exp_f32_e32 v134, v128
	v_mul_f32_e32 v128, 0xbfb8aa3b, v127
	v_exp_f32_e32 v135, v128
	v_mul_f32_e32 v127, v136, v127
	v_mul_f32_e32 v64, 0xbfb8aa3b, v64
	v_pk_add_f32 v[58:59], v[58:59], v[26:27]
	v_pk_add_f32 v[134:135], v[134:135], 1.0 op_sel_hi:[1,0]
	v_mul_f32_e32 v58, 0xbfb8aa3b, v58
	v_mul_f32_e32 v128, v134, v135
	v_rcp_f32_e32 v128, v128
	v_and_b32_e32 v135, 0xffff0000, v147
	v_and_b32_e32 v134, 0xffff0000, v151
	v_mul_f32_e32 v134, v134, v135
	v_mul_f32_e32 v127, v127, v128
	v_mul_f32_e32 v128, 0xbfb8aa3b, v129
	v_mul_f32_e32 v129, 0xbfb8aa3b, v135
	v_exp_f32_e32 v128, v128
	v_exp_f32_e32 v129, v129
	v_lshlrev_b32_e32 v135, 16, v152
	v_lshlrev_b64 v[150:151], 14, v[176:177]
; __device__ __forceinline__ unsigned cvt_pk_bf16(float lo, float hi) { unsigned r; asm volatile("v_cvt_pk_bf16_f32 %0, %1, %2" : "=v"(r) : "v"(lo), "v"(hi)); return r; }
; __device__ __forceinline__ float bf_lo(unsigned w) { return __uint_as_float(w << 16); }
; __device__ __forceinline__ float bf_hi(unsigned w) { return __uint_as_float(w & 0xffff0000u); }
;     __device__ __forceinline__ void operator()(const f32x4 (&acc)[2][2][4][2], const Unit& u, int wr, int wc, int fr, int fq, const Pre&) const {
;     ...
;                 for (int m = 0; m < 4; ++m) { const int r = row0 + ai * HALF + m * 16;
;                     const u32x4 zw = zv[m], gw = gv[m];
;                     const f32x4 a0 = acc[ai][bj][m][0] + bs[bj][0], a1 = acc[ai][bj][m][1] + bs[bj][1];
;                     u32x4 w;
;                     w.x = cvt_pk_bf16(glu_gate_f(bf_lo(gw.x), a0[0], bf_lo(zw.x)), glu_gate_f(bf_hi(gw.x), a0[1], bf_hi(zw.x)));
;                     w.y = cvt_pk_bf16(glu_gate_f(bf_lo(gw.y), a0[2], bf_lo(zw.y)), glu_gate_f(bf_hi(gw.y), a0[3], bf_hi(zw.y)));
;                     w.z = cvt_pk_bf16(glu_gate_f(bf_lo(gw.z), a1[0], bf_lo(zw.z)), glu_gate_f(bf_hi(gw.z), a1[1], bf_hi(zw.z)));
;                     w.w = cvt_pk_bf16(glu_gate_f(bf_lo(gw.w), a1[2], bf_lo(zw.w)), glu_gate_f(bf_hi(gw.w), a1[3], bf_hi(zw.w)));
;                     *(u32x4*)(O + (size_t)r * DE + c) = w; } } }
	v_pk_add_f32 v[60:61], v[60:61], v[28:29]
	v_pk_add_f32 v[128:129], v[128:129], 1.0 op_sel_hi:[1,0]
	v_pk_add_f32 v[54:55], v[54:55], v[30:31]
	v_mul_f32_e32 v128, v128, v129
	v_rcp_f32_e32 v128, v128
	v_mul_f32_e32 v54, 0xbfb8aa3b, v54
	v_pk_add_f32 v[56:57], v[56:57], v[32:33]
	v_pk_add_f32 v[50:51], v[50:51], v[26:27]
	v_mul_f32_e32 v128, v134, v128
	v_lshlrev_b32_e32 v134, 16, v148
	v_cvt_pk_bf16_f32 v127, v127, v128
	v_exp_f32_e32 v128, v122
	v_mul_f32_e32 v122, 0xbfb8aa3b, v134
	v_exp_f32_e32 v129, v122
	v_mul_f32_e32 v122, v135, v134
	v_and_b32_e32 v134, 0xffff0000, v148
	v_mul_f32_e32 v56, 0xbfb8aa3b, v56
	v_pk_add_f32 v[128:129], v[128:129], 1.0 op_sel_hi:[1,0]
	v_mul_f32_e32 v50, 0xbfb8aa3b, v50
	v_mul_f32_e32 v128, v128, v129
	v_rcp_f32_e32 v128, v128
	v_and_b32_e32 v129, 0xffff0000, v152
	v_mul_f32_e32 v129, v129, v134
	v_pk_add_f32 v[52:53], v[52:53], v[28:29]
	v_mul_f32_e32 v128, v122, v128
	v_mul_f32_e32 v122, 0xbfb8aa3b, v123
	v_mul_f32_e32 v123, 0xbfb8aa3b, v134
	v_exp_f32_e32 v122, v122
	v_exp_f32_e32 v123, v123
	v_lshlrev_b32_e32 v134, 16, v153
	v_pk_add_f32 v[46:47], v[46:47], v[30:31]
	v_pk_add_f32 v[48:49], v[48:49], v[32:33]
	v_pk_add_f32 v[122:123], v[122:123], 1.0 op_sel_hi:[1,0]
	v_mul_f32_e32 v46, 0xbfb8aa3b, v46
	v_mul_f32_e32 v122, v122, v123
	v_rcp_f32_e32 v122, v122
	v_mul_f32_e32 v48, 0xbfb8aa3b, v48
	v_pk_add_f32 v[42:43], v[42:43], v[26:27]
	v_pk_add_f32 v[44:45], v[44:45], v[28:29]
	v_mul_f32_e32 v122, v129, v122
	v_lshlrev_b32_e32 v129, 16, v149
	v_cvt_pk_bf16_f32 v128, v128, v122
	v_mul_f32_e32 v122, 0xbfb8aa3b, v124
	v_mul_f32_e32 v123, 0xbfb8aa3b, v129
	v_exp_f32_e32 v122, v122
	v_exp_f32_e32 v123, v123
	v_mul_f32_e32 v124, v134, v129
	v_and_b32_e32 v134, 0xffff0000, v149
	v_and_b32_e32 v129, 0xffff0000, v153
	v_pk_add_f32 v[122:123], v[122:123], 1.0 op_sel_hi:[1,0]
	v_mul_f32_e32 v42, 0xbfb8aa3b, v42
	v_mul_f32_e32 v122, v122, v123
	v_rcp_f32_e32 v122, v122
	v_mul_f32_e32 v123, 0xbfb8aa3b, v134
	v_exp_f32_e32 v123, v123
	v_pk_add_f32 v[38:39], v[38:39], v[30:31]
	v_mul_f32_e32 v124, v124, v122
	v_mul_f32_e32 v122, 0xbfb8aa3b, v125
	v_exp_f32_e32 v122, v122
	v_mul_f32_e32 v125, v129, v134
	v_mul_f32_e32 v38, 0xbfb8aa3b, v38
	v_pk_add_f32 v[40:41], v[40:41], v[32:33]
	v_pk_add_f32 v[122:123], v[122:123], 1.0 op_sel_hi:[1,0]
	v_mul_f32_e32 v40, 0xbfb8aa3b, v40
	v_mul_f32_e32 v122, v122, v123
	v_rcp_f32_e32 v122, v122
	v_pk_add_f32 v[34:35], v[34:35], v[26:27]
	v_pk_add_f32 v[36:37], v[36:37], v[28:29]
	v_mul_f32_e32 v34, 0xbfb8aa3b, v34
	v_mul_f32_e32 v122, v125, v122
	v_cvt_pk_bf16_f32 v129, v124, v122
	v_lshlrev_b64 v[122:123], 13, v[228:229]
	v_lshl_add_u64 v[122:123], s[44:45], 0, v[122:123]
	v_lshlrev_b32_e32 v124, 16, v130
	v_lshl_add_u64 v[146:147], v[122:123], 0, v[204:205]
	v_exp_f32_e32 v122, v118
	v_mul_f32_e32 v118, 0xbfb8aa3b, v124
	v_exp_f32_e32 v123, v118
	v_lshlrev_b32_e32 v125, 16, v142
	v_mul_f32_e32 v118, v125, v124
	v_and_b32_e32 v124, 0xffff0000, v130
	v_pk_add_f32 v[122:123], v[122:123], 1.0 op_sel_hi:[1,0]
	global_store_dwordx4 v[146:147], v[126:129], off
	v_mul_f32_e32 v122, v122, v123
	v_rcp_f32_e32 v122, v122
	v_and_b32_e32 v123, 0xffff0000, v142
	v_mul_f32_e32 v123, v123, v124
	v_pk_add_f32 v[22:23], v[22:23], v[30:31]
	v_mul_f32_e32 v122, v118, v122
	v_mul_f32_e32 v118, 0xbfb8aa3b, v119
	v_mul_f32_e32 v119, 0xbfb8aa3b, v124
	v_exp_f32_e32 v118, v118
	v_exp_f32_e32 v119, v119
	v_lshlrev_b32_e32 v124, 16, v143
	v_mul_f32_e32 v22, 0xbfb8aa3b, v22
	v_pk_add_f32 v[24:25], v[24:25], v[32:33]
	v_pk_add_f32 v[118:119], v[118:119], 1.0 op_sel_hi:[1,0]
	v_mul_f32_e32 v24, 0xbfb8aa3b, v24
	v_mul_f32_e32 v118, v118, v119
	v_rcp_f32_e32 v118, v118
	v_lshlrev_b32_e32 v119, 16, v131
	v_pk_add_f32 v[18:19], v[18:19], v[26:27]
	v_pk_add_f32 v[20:21], v[20:21], v[28:29]
	v_mul_f32_e32 v118, v123, v118
	v_cvt_pk_bf16_f32 v118, v122, v118
	v_exp_f32_e32 v122, v120
	v_mul_f32_e32 v120, 0xbfb8aa3b, v119
	v_exp_f32_e32 v123, v120
	v_mul_f32_e32 v119, v124, v119
	v_mul_f32_e32 v18, 0xbfb8aa3b, v18
	v_pk_add_f32 v[14:15], v[14:15], v[30:31]
	v_pk_add_f32 v[122:123], v[122:123], 1.0 op_sel_hi:[1,0]
	v_mul_f32_e32 v14, 0xbfb8aa3b, v14
	v_mul_f32_e32 v120, v122, v123
	v_rcp_f32_e32 v120, v120
	v_and_b32_e32 v123, 0xffff0000, v131
	v_and_b32_e32 v122, 0xffff0000, v143
	v_mul_f32_e32 v122, v122, v123
	v_mul_f32_e32 v119, v119, v120
	v_mul_f32_e32 v120, 0xbfb8aa3b, v121
	v_mul_f32_e32 v121, 0xbfb8aa3b, v123
	v_exp_f32_e32 v120, v120
	v_exp_f32_e32 v121, v121
	v_lshlrev_b32_e32 v123, 16, v144
	v_pk_add_f32 v[16:17], v[16:17], v[32:33]
	v_pk_add_f32 v[10:11], v[10:11], v[26:27]
	v_pk_add_f32 v[120:121], v[120:121], 1.0 op_sel_hi:[1,0]
	v_mul_f32_e32 v16, 0xbfb8aa3b, v16
	v_mul_f32_e32 v120, v120, v121
	v_rcp_f32_e32 v120, v120
	v_mul_f32_e32 v10, 0xbfb8aa3b, v10
	v_pk_add_f32 v[12:13], v[12:13], v[28:29]
	v_pk_add_f32 v[6:7], v[6:7], v[30:31]
	v_mul_f32_e32 v120, v122, v120
	v_lshlrev_b32_e32 v122, 16, v132
	v_cvt_pk_bf16_f32 v119, v119, v120
	v_exp_f32_e32 v120, v114
	v_mul_f32_e32 v114, 0xbfb8aa3b, v122
	v_exp_f32_e32 v121, v114
	v_mul_f32_e32 v114, v123, v122
	v_and_b32_e32 v122, 0xffff0000, v132
	v_mul_f32_e32 v6, 0xbfb8aa3b, v6
	v_pk_add_f32 v[120:121], v[120:121], 1.0 op_sel_hi:[1,0]
	v_pk_add_f32 v[8:9], v[8:9], v[32:33]
	v_mul_f32_e32 v120, v120, v121
	v_rcp_f32_e32 v120, v120
	v_and_b32_e32 v121, 0xffff0000, v144
	v_mul_f32_e32 v121, v121, v122
	v_mul_f32_e32 v8, 0xbfb8aa3b, v8
	v_mul_f32_e32 v120, v114, v120
	v_mul_f32_e32 v114, 0xbfb8aa3b, v115
	v_mul_f32_e32 v115, 0xbfb8aa3b, v122
	v_exp_f32_e32 v114, v114
	v_exp_f32_e32 v115, v115
	v_lshlrev_b32_e32 v122, 16, v145
	v_pk_add_f32 v[2:3], v[2:3], v[26:27]
; __device__ __forceinline__ unsigned cvt_pk_bf16(float lo, float hi) { unsigned r; asm volatile("v_cvt_pk_bf16_f32 %0, %1, %2" : "=v"(r) : "v"(lo), "v"(hi)); return r; }
; __device__ __forceinline__ float bf_lo(unsigned w) { return __uint_as_float(w << 16); }
; __device__ __forceinline__ float bf_hi(unsigned w) { return __uint_as_float(w & 0xffff0000u); }
;     __device__ __forceinline__ void operator()(const f32x4 (&acc)[2][2][4][2], const Unit& u, int wr, int wc, int fr, int fq, const Pre&) const {
;     ...
;             for (int ai = 0; ai < 2; ++ai) { u32x4 zv[4], gv[4];
; #pragma unroll
;                 for (int m = 0; m < 4; ++m) { const int r = row0 + ai * HALF + m * 16; zv[m] = *(const u32x4*)(Z + (size_t)r * DE2 + c); gv[m] = *(const u32x4*)(Gm + (size_t)(c >> 4) * GSTR + r * 16 + (c & 15)); }
; #pragma unroll
;                 for (int m = 0; m < 4; ++m) { const int r = row0 + ai * HALF + m * 16;
;                     const u32x4 zw = zv[m], gw = gv[m];
;                     const f32x4 a0 = acc[ai][bj][m][0] + bs[bj][0], a1 = acc[ai][bj][m][1] + bs[bj][1];
;                     u32x4 w;
;                     w.x = cvt_pk_bf16(glu_gate_f(bf_lo(gw.x), a0[0], bf_lo(zw.x)), glu_gate_f(bf_hi(gw.x), a0[1], bf_hi(zw.x)));
;                     w.y = cvt_pk_bf16(glu_gate_f(bf_lo(gw.y), a0[2], bf_lo(zw.y)), glu_gate_f(bf_hi(gw.y), a0[3], bf_hi(zw.y)));
;                     w.z = cvt_pk_bf16(glu_gate_f(bf_lo(gw.z), a1[0], bf_lo(zw.z)), glu_gate_f(bf_hi(gw.z), a1[1], bf_hi(zw.z)));
;                     w.w = cvt_pk_bf16(glu_gate_f(bf_lo(gw.w), a1[2], bf_lo(zw.w)), glu_gate_f(bf_hi(gw.w), a1[3], bf_hi(zw.w)));
;                     *(u32x4*)(O + (size_t)r * DE + c) = w; } } }
	v_pk_add_f32 v[4:5], v[4:5], v[28:29]
	v_pk_add_f32 v[114:115], v[114:115], 1.0 op_sel_hi:[1,0]
	v_mul_f32_e32 v2, 0xbfb8aa3b, v2
	v_mul_f32_e32 v114, v114, v115
	v_rcp_f32_e32 v114, v114
	s_nop 0
	v_mul_f32_e32 v114, v121, v114
	v_lshlrev_b32_e32 v121, 16, v133
	v_cvt_pk_bf16_f32 v120, v120, v114
	v_mul_f32_e32 v114, 0xbfb8aa3b, v116
	v_mul_f32_e32 v115, 0xbfb8aa3b, v121
	v_exp_f32_e32 v114, v114
	v_exp_f32_e32 v115, v115
	v_mul_f32_e32 v116, v122, v121
	v_and_b32_e32 v122, 0xffff0000, v133
	v_and_b32_e32 v121, 0xffff0000, v145
	v_pk_add_f32 v[114:115], v[114:115], 1.0 op_sel_hi:[1,0]
	s_nop 0
	v_mul_f32_e32 v114, v114, v115
	v_rcp_f32_e32 v114, v114
	v_mul_f32_e32 v115, 0xbfb8aa3b, v122
	v_exp_f32_e32 v115, v115
	v_mul_f32_e32 v116, v116, v114
	v_mul_f32_e32 v114, 0xbfb8aa3b, v117
	v_exp_f32_e32 v114, v114
	v_mul_f32_e32 v117, v121, v122
	v_pk_add_f32 v[114:115], v[114:115], 1.0 op_sel_hi:[1,0]
	s_nop 0
	v_mul_f32_e32 v114, v114, v115
	v_rcp_f32_e32 v114, v114
	s_nop 0
	v_mul_f32_e32 v114, v117, v114
	v_cvt_pk_bf16_f32 v121, v116, v114
	v_lshlrev_b64 v[114:115], 13, v[226:227]
	v_lshl_add_u64 v[114:115], s[44:45], 0, v[114:115]
	v_lshl_add_u64 v[148:149], v[114:115], 0, v[204:205]
	global_store_dwordx4 v[148:149], v[118:121], off
	v_lshl_add_u64 v[114:115], v[222:223], 0, v[150:151]
	global_load_dwordx4 v[138:141], v[114:115], off
	v_lshlrev_b32_e32 v118, 4, v170
	v_ashrrev_i32_e32 v119, 31, v118
	v_lshlrev_b64 v[168:169], 1, v[118:119]
	v_lshl_add_u64 v[118:119], v[220:221], 0, v[168:169]
	global_load_dwordx4 v[118:121], v[118:119], off
	v_lshlrev_b32_e32 v114, 4, v176
	v_ashrrev_i32_e32 v115, 31, v114
	v_lshlrev_b64 v[152:153], 1, v[114:115]
	v_lshl_add_u64 v[114:115], v[220:221], 0, v[152:153]
	global_load_dwordx4 v[142:145], v[114:115], off
	v_lshl_add_u64 v[114:115], v[222:223], 0, v[156:157]
	global_load_dwordx4 v[130:133], v[114:115], off
	v_lshlrev_b32_e32 v114, 4, v174
	v_ashrrev_i32_e32 v115, 31, v114
	v_lshlrev_b64 v[158:159], 1, v[114:115]
	v_lshl_add_u64 v[114:115], v[220:221], 0, v[158:159]
	global_load_dwordx4 v[134:137], v[114:115], off
	v_lshl_add_u64 v[114:115], v[222:223], 0, v[160:161]
	global_load_dwordx4 v[122:125], v[114:115], off
	v_lshlrev_b32_e32 v114, 4, v172
	v_ashrrev_i32_e32 v115, 31, v114
	v_lshlrev_b64 v[164:165], 1, v[114:115]
	v_lshl_add_u64 v[114:115], v[220:221], 0, v[164:165]
	global_load_dwordx4 v[126:129], v[114:115], off
	v_lshl_add_u64 v[114:115], v[222:223], 0, v[166:167]
	global_load_dwordx4 v[114:117], v[114:115], off
	s_waitcnt vmcnt(0)
	v_lshlrev_b32_e32 v186, 16, v138
	v_mul_f32_e32 v110, 0xbfb8aa3b, v186
	v_exp_f32_e32 v185, v110
	v_and_b32_e32 v138, 0xffff0000, v138
	v_pk_add_f32 v[184:185], v[184:185], 1.0 op_sel_hi:[1,0]
	s_nop 0
	v_mul_f32_e32 v184, v184, v185
	v_rcp_f32_e32 v184, v184
	v_lshlrev_b32_e32 v187, 16, v142
	v_mul_f32_e32 v110, v187, v186
	v_mul_f32_e32 v184, v110, v184
	v_mul_f32_e32 v110, 0xbfb8aa3b, v111
	v_mul_f32_e32 v111, 0xbfb8aa3b, v138
	v_exp_f32_e32 v110, v110
	v_exp_f32_e32 v111, v111
	v_and_b32_e32 v142, 0xffff0000, v142
	v_mul_f32_e32 v138, v142, v138
	v_pk_add_f32 v[110:111], v[110:111], 1.0 op_sel_hi:[1,0]
	s_nop 0
	v_mul_f32_e32 v110, v110, v111
	v_rcp_f32_e32 v110, v110
	v_lshlrev_b32_e32 v111, 16, v139
	v_and_b32_e32 v139, 0xffff0000, v139
	v_mul_f32_e32 v110, v138, v110
	v_cvt_pk_bf16_f32 v110, v184, v110
	v_exp_f32_e32 v184, v112
	v_mul_f32_e32 v112, 0xbfb8aa3b, v111
	v_exp_f32_e32 v185, v112
	v_lshlrev_b32_e32 v138, 16, v143
	v_mul_f32_e32 v111, v138, v111
	v_and_b32_e32 v138, 0xffff0000, v143
	v_pk_add_f32 v[184:185], v[184:185], 1.0 op_sel_hi:[1,0]
	v_mul_f32_e32 v138, v138, v139
	v_mul_f32_e32 v112, v184, v185
	v_rcp_f32_e32 v112, v112
	s_nop 0
	v_mul_f32_e32 v111, v111, v112
	v_mul_f32_e32 v112, 0xbfb8aa3b, v113
	v_mul_f32_e32 v113, 0xbfb8aa3b, v139
	v_exp_f32_e32 v112, v112
	v_exp_f32_e32 v113, v113
	v_lshlrev_b32_e32 v139, 16, v144
	v_pk_add_f32 v[112:113], v[112:113], 1.0 op_sel_hi:[1,0]
	s_nop 0
	v_mul_f32_e32 v112, v112, v113
	v_rcp_f32_e32 v112, v112
	s_nop 0
	v_mul_f32_e32 v112, v138, v112
	v_lshlrev_b32_e32 v138, 16, v140
	v_cvt_pk_bf16_f32 v111, v111, v112
	v_exp_f32_e32 v112, v106
	v_mul_f32_e32 v106, 0xbfb8aa3b, v138
	v_exp_f32_e32 v113, v106
	v_mul_f32_e32 v106, v139, v138
	v_and_b32_e32 v138, 0xffff0000, v140
	v_pk_add_f32 v[112:113], v[112:113], 1.0 op_sel_hi:[1,0]
	s_nop 0
	v_mul_f32_e32 v112, v112, v113
	v_rcp_f32_e32 v112, v112
	v_and_b32_e32 v113, 0xffff0000, v144
	v_mul_f32_e32 v113, v113, v138
	v_mul_f32_e32 v112, v106, v112
	v_mul_f32_e32 v106, 0xbfb8aa3b, v107
	v_mul_f32_e32 v107, 0xbfb8aa3b, v138
	v_exp_f32_e32 v106, v106
	v_exp_f32_e32 v107, v107
	v_lshlrev_b32_e32 v138, 16, v145
	v_pk_add_f32 v[106:107], v[106:107], 1.0 op_sel_hi:[1,0]
	s_nop 0
	v_mul_f32_e32 v106, v106, v107
	v_rcp_f32_e32 v106, v106
	s_nop 0
	v_mul_f32_e32 v106, v113, v106
	v_lshlrev_b32_e32 v113, 16, v141
	v_cvt_pk_bf16_f32 v112, v112, v106
	v_mul_f32_e32 v106, 0xbfb8aa3b, v108
	v_mul_f32_e32 v107, 0xbfb8aa3b, v113
	v_exp_f32_e32 v106, v106
	v_exp_f32_e32 v107, v107
	v_mul_f32_e32 v108, v138, v113
	v_and_b32_e32 v138, 0xffff0000, v141
	v_and_b32_e32 v113, 0xffff0000, v145
	v_pk_add_f32 v[106:107], v[106:107], 1.0 op_sel_hi:[1,0]
	s_nop 0
	v_mul_f32_e32 v106, v106, v107
	v_rcp_f32_e32 v106, v106
	v_mul_f32_e32 v107, 0xbfb8aa3b, v138
	v_exp_f32_e32 v107, v107
	v_mul_f32_e32 v108, v108, v106
	v_mul_f32_e32 v106, 0xbfb8aa3b, v109
	v_exp_f32_e32 v106, v106
	v_mul_f32_e32 v109, v113, v138
	v_pk_add_f32 v[106:107], v[106:107], 1.0 op_sel_hi:[1,0]
	s_nop 0
	v_mul_f32_e32 v106, v106, v107
	v_rcp_f32_e32 v106, v106
	s_nop 0
	v_mul_f32_e32 v106, v109, v106
; __device__ __forceinline__ unsigned cvt_pk_bf16(float lo, float hi) { unsigned r; asm volatile("v_cvt_pk_bf16_f32 %0, %1, %2" : "=v"(r) : "v"(lo), "v"(hi)); return r; }
; __device__ __forceinline__ float bf_lo(unsigned w) { return __uint_as_float(w << 16); }
; __device__ __forceinline__ float bf_hi(unsigned w) { return __uint_as_float(w & 0xffff0000u); }
;     __device__ __forceinline__ void operator()(const f32x4 (&acc)[2][2][4][2], const Unit& u, int wr, int wc, int fr, int fq, const Pre&) const {
;     ...
;                 for (int m = 0; m < 4; ++m) { const int r = row0 + ai * HALF + m * 16;
;                     const u32x4 zw = zv[m], gw = gv[m];
;                     const f32x4 a0 = acc[ai][bj][m][0] + bs[bj][0], a1 = acc[ai][bj][m][1] + bs[bj][1];
;                     u32x4 w;
;                     w.x = cvt_pk_bf16(glu_gate_f(bf_lo(gw.x), a0[0], bf_lo(zw.x)), glu_gate_f(bf_hi(gw.x), a0[1], bf_hi(zw.x)));
;                     w.y = cvt_pk_bf16(glu_gate_f(bf_lo(gw.y), a0[2], bf_lo(zw.y)), glu_gate_f(bf_hi(gw.y), a0[3], bf_hi(zw.y)));
;                     w.z = cvt_pk_bf16(glu_gate_f(bf_lo(gw.z), a1[0], bf_lo(zw.z)), glu_gate_f(bf_hi(gw.z), a1[1], bf_hi(zw.z)));
;                     w.w = cvt_pk_bf16(glu_gate_f(bf_lo(gw.w), a1[2], bf_lo(zw.w)), glu_gate_f(bf_hi(gw.w), a1[3], bf_hi(zw.w)));
;                     *(u32x4*)(O + (size_t)r * DE + c) = w; } } }
	v_cvt_pk_bf16_f32 v113, v108, v106
	v_lshlrev_b64 v[106:107], 13, v[176:177]
	v_lshl_add_u64 v[106:107], s[44:45], 0, v[106:107]
	v_lshl_add_u64 v[106:107], v[106:107], 0, v[204:205]
	global_store_dwordx4 v[106:107], v[110:113], off
	v_exp_f32_e32 v108, v94
	s_nop 0
	v_lshlrev_b32_e32 v110, 16, v130
	v_mul_f32_e32 v94, 0xbfb8aa3b, v110
	v_exp_f32_e32 v109, v94
	v_lshlrev_b32_e32 v111, 16, v134
	v_mul_f32_e32 v94, v111, v110
	v_and_b32_e32 v110, 0xffff0000, v130
	v_pk_add_f32 v[108:109], v[108:109], 1.0 op_sel_hi:[1,0]
	s_nop 0
	v_mul_f32_e32 v108, v108, v109
	v_rcp_f32_e32 v108, v108
	v_and_b32_e32 v109, 0xffff0000, v134
	v_mul_f32_e32 v109, v109, v110
	v_mul_f32_e32 v108, v94, v108
	v_mul_f32_e32 v94, 0xbfb8aa3b, v95
	v_mul_f32_e32 v95, 0xbfb8aa3b, v110
	v_exp_f32_e32 v94, v94
	v_exp_f32_e32 v95, v95
	v_lshlrev_b32_e32 v110, 16, v135
	v_pk_add_f32 v[94:95], v[94:95], 1.0 op_sel_hi:[1,0]
	s_nop 0
	v_mul_f32_e32 v94, v94, v95
	v_rcp_f32_e32 v94, v94
	v_lshlrev_b32_e32 v95, 16, v131
	v_mul_f32_e32 v94, v109, v94
	v_cvt_pk_bf16_f32 v94, v108, v94
	v_exp_f32_e32 v108, v96
	v_mul_f32_e32 v96, 0xbfb8aa3b, v95
	v_exp_f32_e32 v109, v96
	v_mul_f32_e32 v95, v110, v95
	v_pk_add_f32 v[108:109], v[108:109], 1.0 op_sel_hi:[1,0]
	s_nop 0
	v_mul_f32_e32 v96, v108, v109
	v_rcp_f32_e32 v96, v96
	v_and_b32_e32 v109, 0xffff0000, v131
	v_and_b32_e32 v108, 0xffff0000, v135
	v_mul_f32_e32 v108, v108, v109
	v_mul_f32_e32 v95, v95, v96
	v_mul_f32_e32 v96, 0xbfb8aa3b, v97
	v_mul_f32_e32 v97, 0xbfb8aa3b, v109
	v_exp_f32_e32 v96, v96
	v_exp_f32_e32 v97, v97
	v_lshlrev_b32_e32 v109, 16, v136
	v_pk_add_f32 v[96:97], v[96:97], 1.0 op_sel_hi:[1,0]
	s_nop 0
	v_mul_f32_e32 v96, v96, v97
	v_rcp_f32_e32 v96, v96
	s_nop 0
	v_mul_f32_e32 v96, v108, v96
	v_lshlrev_b32_e32 v108, 16, v132
	v_cvt_pk_bf16_f32 v95, v95, v96
	v_exp_f32_e32 v96, v90
	v_mul_f32_e32 v90, 0xbfb8aa3b, v108
	v_exp_f32_e32 v97, v90
	v_mul_f32_e32 v90, v109, v108
	v_and_b32_e32 v108, 0xffff0000, v132
	v_pk_add_f32 v[96:97], v[96:97], 1.0 op_sel_hi:[1,0]
	s_nop 0
	v_mul_f32_e32 v96, v96, v97
	v_rcp_f32_e32 v96, v96
	v_and_b32_e32 v97, 0xffff0000, v136
	v_mul_f32_e32 v97, v97, v108
	v_mul_f32_e32 v96, v90, v96
	v_mul_f32_e32 v90, 0xbfb8aa3b, v91
	v_mul_f32_e32 v91, 0xbfb8aa3b, v108
	v_exp_f32_e32 v90, v90
	v_exp_f32_e32 v91, v91
	v_lshlrev_b32_e32 v108, 16, v137
	v_pk_add_f32 v[90:91], v[90:91], 1.0 op_sel_hi:[1,0]
	s_nop 0
	v_mul_f32_e32 v90, v90, v91
	v_rcp_f32_e32 v90, v90
	s_nop 0
	v_mul_f32_e32 v90, v97, v90
	v_lshlrev_b32_e32 v97, 16, v133
	v_cvt_pk_bf16_f32 v96, v96, v90
	v_mul_f32_e32 v90, 0xbfb8aa3b, v92
	v_mul_f32_e32 v91, 0xbfb8aa3b, v97
	v_exp_f32_e32 v90, v90
	v_exp_f32_e32 v91, v91
	v_mul_f32_e32 v92, v108, v97
	v_and_b32_e32 v108, 0xffff0000, v133
	v_and_b32_e32 v97, 0xffff0000, v137
	v_pk_add_f32 v[90:91], v[90:91], 1.0 op_sel_hi:[1,0]
	s_nop 0
	v_mul_f32_e32 v90, v90, v91
	v_rcp_f32_e32 v90, v90
	v_mul_f32_e32 v91, 0xbfb8aa3b, v108
	v_exp_f32_e32 v91, v91
	v_mul_f32_e32 v92, v92, v90
	v_mul_f32_e32 v90, 0xbfb8aa3b, v93
	v_exp_f32_e32 v90, v90
	v_mul_f32_e32 v93, v97, v108
	v_pk_add_f32 v[90:91], v[90:91], 1.0 op_sel_hi:[1,0]
	s_nop 0
	v_mul_f32_e32 v90, v90, v91
	v_rcp_f32_e32 v90, v90
	s_nop 0
	v_mul_f32_e32 v90, v93, v90
	v_cvt_pk_bf16_f32 v97, v92, v90
	v_lshlrev_b64 v[90:91], 13, v[174:175]
	v_lshl_add_u64 v[90:91], s[44:45], 0, v[90:91]
	v_lshlrev_b32_e32 v92, 16, v122
	v_lshl_add_u64 v[108:109], v[90:91], 0, v[204:205]
	v_exp_f32_e32 v90, v86
	v_mul_f32_e32 v86, 0xbfb8aa3b, v92
	v_exp_f32_e32 v91, v86
	v_lshlrev_b32_e32 v93, 16, v126
	v_mul_f32_e32 v86, v93, v92
	v_and_b32_e32 v92, 0xffff0000, v122
	v_pk_add_f32 v[90:91], v[90:91], 1.0 op_sel_hi:[1,0]
	global_store_dwordx4 v[108:109], v[94:97], off
	v_mul_f32_e32 v90, v90, v91
	v_rcp_f32_e32 v90, v90
	v_and_b32_e32 v91, 0xffff0000, v126
	v_mul_f32_e32 v91, v91, v92
	v_mul_f32_e32 v90, v86, v90
	v_mul_f32_e32 v86, 0xbfb8aa3b, v87
	v_mul_f32_e32 v87, 0xbfb8aa3b, v92
	v_exp_f32_e32 v86, v86
	v_exp_f32_e32 v87, v87
	v_lshlrev_b32_e32 v92, 16, v127
	v_pk_add_f32 v[86:87], v[86:87], 1.0 op_sel_hi:[1,0]
	s_nop 0
	v_mul_f32_e32 v86, v86, v87
	v_rcp_f32_e32 v86, v86
	v_lshlrev_b32_e32 v87, 16, v123
	v_mul_f32_e32 v86, v91, v86
	v_cvt_pk_bf16_f32 v86, v90, v86
	v_exp_f32_e32 v90, v88
	v_mul_f32_e32 v88, 0xbfb8aa3b, v87
	v_exp_f32_e32 v91, v88
	v_mul_f32_e32 v87, v92, v87
	v_pk_add_f32 v[90:91], v[90:91], 1.0 op_sel_hi:[1,0]
	s_nop 0
	v_mul_f32_e32 v88, v90, v91
	v_rcp_f32_e32 v88, v88
	v_and_b32_e32 v91, 0xffff0000, v123
	v_and_b32_e32 v90, 0xffff0000, v127
	v_mul_f32_e32 v90, v90, v91
	v_mul_f32_e32 v87, v87, v88
	v_mul_f32_e32 v88, 0xbfb8aa3b, v89
	v_mul_f32_e32 v89, 0xbfb8aa3b, v91
	v_exp_f32_e32 v88, v88
	v_exp_f32_e32 v89, v89
	v_lshlrev_b32_e32 v91, 16, v128
	v_pk_add_f32 v[88:89], v[88:89], 1.0 op_sel_hi:[1,0]
	s_nop 0
	v_mul_f32_e32 v88, v88, v89
	v_rcp_f32_e32 v88, v88
	s_nop 0
	v_mul_f32_e32 v88, v90, v88
	v_lshlrev_b32_e32 v90, 16, v124
	v_cvt_pk_bf16_f32 v87, v87, v88
	v_exp_f32_e32 v88, v82
	v_mul_f32_e32 v82, 0xbfb8aa3b, v90
	v_exp_f32_e32 v89, v82
	v_mul_f32_e32 v82, v91, v90
	v_and_b32_e32 v90, 0xffff0000, v124
	v_pk_add_f32 v[88:89], v[88:89], 1.0 op_sel_hi:[1,0]
	s_nop 0
	v_mul_f32_e32 v88, v88, v89
	v_rcp_f32_e32 v88, v88
	v_and_b32_e32 v89, 0xffff0000, v128
	v_mul_f32_e32 v89, v89, v90
	v_mul_f32_e32 v88, v82, v88
	v_mul_f32_e32 v82, 0xbfb8aa3b, v83
	v_mul_f32_e32 v83, 0xbfb8aa3b, v90
	v_exp_f32_e32 v82, v82
	v_exp_f32_e32 v83, v83
	v_lshlrev_b32_e32 v90, 16, v129
	v_pk_add_f32 v[82:83], v[82:83], 1.0 op_sel_hi:[1,0]
	s_nop 0
	v_mul_f32_e32 v82, v82, v83
	v_rcp_f32_e32 v82, v82
	s_nop 0
	v_mul_f32_e32 v82, v89, v82
; __device__ __forceinline__ unsigned cvt_pk_bf16(float lo, float hi) { unsigned r; asm volatile("v_cvt_pk_bf16_f32 %0, %1, %2" : "=v"(r) : "v"(lo), "v"(hi)); return r; }
; __device__ __forceinline__ float bf_lo(unsigned w) { return __uint_as_float(w << 16); }
; __device__ __forceinline__ float bf_hi(unsigned w) { return __uint_as_float(w & 0xffff0000u); }
;     __device__ __forceinline__ void operator()(const f32x4 (&acc)[2][2][4][2], const Unit& u, int wr, int wc, int fr, int fq, const Pre&) const {
;     ...
;             for (int ai = 0; ai < 2; ++ai) { u32x4 zv[4], gv[4];
; #pragma unroll
;                 for (int m = 0; m < 4; ++m) { const int r = row0 + ai * HALF + m * 16; zv[m] = *(const u32x4*)(Z + (size_t)r * DE2 + c); gv[m] = *(const u32x4*)(Gm + (size_t)(c >> 4) * GSTR + r * 16 + (c & 15)); }
; #pragma unroll
;                 for (int m = 0; m < 4; ++m) { const int r = row0 + ai * HALF + m * 16;
;                     const u32x4 zw = zv[m], gw = gv[m];
;                     const f32x4 a0 = acc[ai][bj][m][0] + bs[bj][0], a1 = acc[ai][bj][m][1] + bs[bj][1];
;                     u32x4 w;
;                     w.x = cvt_pk_bf16(glu_gate_f(bf_lo(gw.x), a0[0], bf_lo(zw.x)), glu_gate_f(bf_hi(gw.x), a0[1], bf_hi(zw.x)));
;                     w.y = cvt_pk_bf16(glu_gate_f(bf_lo(gw.y), a0[2], bf_lo(zw.y)), glu_gate_f(bf_hi(gw.y), a0[3], bf_hi(zw.y)));
;                     w.z = cvt_pk_bf16(glu_gate_f(bf_lo(gw.z), a1[0], bf_lo(zw.z)), glu_gate_f(bf_hi(gw.z), a1[1], bf_hi(zw.z)));
;                     w.w = cvt_pk_bf16(glu_gate_f(bf_lo(gw.w), a1[2], bf_lo(zw.w)), glu_gate_f(bf_hi(gw.w), a1[3], bf_hi(zw.w)));
;                     *(u32x4*)(O + (size_t)r * DE + c) = w; } } }
	v_lshlrev_b32_e32 v89, 16, v125
	v_cvt_pk_bf16_f32 v88, v88, v82
	v_mul_f32_e32 v82, 0xbfb8aa3b, v84
	v_mul_f32_e32 v83, 0xbfb8aa3b, v89
	v_exp_f32_e32 v82, v82
	v_exp_f32_e32 v83, v83
	v_mul_f32_e32 v84, v90, v89
	v_and_b32_e32 v90, 0xffff0000, v125
	v_and_b32_e32 v89, 0xffff0000, v129
	v_pk_add_f32 v[82:83], v[82:83], 1.0 op_sel_hi:[1,0]
	s_nop 0
	v_mul_f32_e32 v82, v82, v83
	v_rcp_f32_e32 v82, v82
	v_mul_f32_e32 v83, 0xbfb8aa3b, v90
	v_exp_f32_e32 v83, v83
	v_mul_f32_e32 v84, v84, v82
	v_mul_f32_e32 v82, 0xbfb8aa3b, v85
	v_exp_f32_e32 v82, v82
	v_mul_f32_e32 v85, v89, v90
	v_pk_add_f32 v[82:83], v[82:83], 1.0 op_sel_hi:[1,0]
	s_nop 0
	v_mul_f32_e32 v82, v82, v83
	v_rcp_f32_e32 v82, v82
	s_nop 0
	v_mul_f32_e32 v82, v85, v82
	v_cvt_pk_bf16_f32 v89, v84, v82
	v_lshlrev_b64 v[82:83], 13, v[172:173]
	v_lshl_add_u64 v[82:83], s[44:45], 0, v[82:83]
	v_lshlrev_b32_e32 v84, 16, v114
	v_lshl_add_u64 v[110:111], v[82:83], 0, v[204:205]
	v_exp_f32_e32 v82, v78
	v_mul_f32_e32 v78, 0xbfb8aa3b, v84
	v_exp_f32_e32 v83, v78
	v_lshlrev_b32_e32 v85, 16, v118
	v_mul_f32_e32 v78, v85, v84
	v_and_b32_e32 v84, 0xffff0000, v114
	v_pk_add_f32 v[82:83], v[82:83], 1.0 op_sel_hi:[1,0]
	global_store_dwordx4 v[110:111], v[86:89], off
	v_mul_f32_e32 v82, v82, v83
	v_rcp_f32_e32 v82, v82
	v_and_b32_e32 v83, 0xffff0000, v118
	v_mul_f32_e32 v83, v83, v84
	v_exp_f32_e32 v118, v70
	v_mul_f32_e32 v82, v78, v82
	v_mul_f32_e32 v78, 0xbfb8aa3b, v79
	v_mul_f32_e32 v79, 0xbfb8aa3b, v84
	v_exp_f32_e32 v78, v78
	v_exp_f32_e32 v79, v79
	v_lshlrev_b32_e32 v84, 16, v119
	v_pk_add_f32 v[78:79], v[78:79], 1.0 op_sel_hi:[1,0]
	s_nop 0
	v_mul_f32_e32 v78, v78, v79
	v_rcp_f32_e32 v78, v78
	v_lshlrev_b32_e32 v79, 16, v115
	v_mul_f32_e32 v78, v83, v78
	v_cvt_pk_bf16_f32 v78, v82, v78
	v_exp_f32_e32 v82, v80
	v_mul_f32_e32 v80, 0xbfb8aa3b, v79
	v_exp_f32_e32 v83, v80
	v_mul_f32_e32 v79, v84, v79
	v_pk_add_f32 v[82:83], v[82:83], 1.0 op_sel_hi:[1,0]
	s_nop 0
	v_mul_f32_e32 v80, v82, v83
	v_rcp_f32_e32 v80, v80
	v_and_b32_e32 v83, 0xffff0000, v115
	v_and_b32_e32 v82, 0xffff0000, v119
	v_mul_f32_e32 v82, v82, v83
	v_mul_f32_e32 v79, v79, v80
	v_mul_f32_e32 v80, 0xbfb8aa3b, v81
	v_mul_f32_e32 v81, 0xbfb8aa3b, v83
	v_exp_f32_e32 v80, v80
	v_exp_f32_e32 v81, v81
	v_lshlrev_b32_e32 v83, 16, v120
	v_pk_add_f32 v[80:81], v[80:81], 1.0 op_sel_hi:[1,0]
	s_nop 0
	v_mul_f32_e32 v80, v80, v81
	v_rcp_f32_e32 v80, v80
	s_nop 0
	v_mul_f32_e32 v80, v82, v80
	v_lshlrev_b32_e32 v82, 16, v116
	v_cvt_pk_bf16_f32 v79, v79, v80
	v_exp_f32_e32 v80, v74
	v_mul_f32_e32 v74, 0xbfb8aa3b, v82
	v_exp_f32_e32 v81, v74
	v_mul_f32_e32 v74, v83, v82
	v_and_b32_e32 v82, 0xffff0000, v116
	v_pk_add_f32 v[80:81], v[80:81], 1.0 op_sel_hi:[1,0]
	s_nop 0
	v_mul_f32_e32 v80, v80, v81
	v_rcp_f32_e32 v80, v80
	v_and_b32_e32 v81, 0xffff0000, v120
	v_mul_f32_e32 v81, v81, v82
	v_mul_f32_e32 v80, v74, v80
	v_mul_f32_e32 v74, 0xbfb8aa3b, v75
	v_mul_f32_e32 v75, 0xbfb8aa3b, v82
	v_exp_f32_e32 v74, v74
	v_exp_f32_e32 v75, v75
	v_lshlrev_b32_e32 v82, 16, v121
	v_pk_add_f32 v[74:75], v[74:75], 1.0 op_sel_hi:[1,0]
	s_nop 0
	v_mul_f32_e32 v74, v74, v75
	v_rcp_f32_e32 v74, v74
	s_nop 0
	v_mul_f32_e32 v74, v81, v74
	v_lshlrev_b32_e32 v81, 16, v117
	v_cvt_pk_bf16_f32 v80, v80, v74
	v_mul_f32_e32 v74, 0xbfb8aa3b, v76
	v_mul_f32_e32 v75, 0xbfb8aa3b, v81
	v_exp_f32_e32 v74, v74
	v_exp_f32_e32 v75, v75
	v_mul_f32_e32 v76, v82, v81
	v_and_b32_e32 v82, 0xffff0000, v117
	v_and_b32_e32 v81, 0xffff0000, v121
	v_pk_add_f32 v[74:75], v[74:75], 1.0 op_sel_hi:[1,0]
	s_nop 0
	v_mul_f32_e32 v74, v74, v75
	v_rcp_f32_e32 v74, v74
	v_mul_f32_e32 v75, 0xbfb8aa3b, v82
	v_exp_f32_e32 v75, v75
	v_mul_f32_e32 v76, v76, v74
	v_mul_f32_e32 v74, 0xbfb8aa3b, v77
	v_exp_f32_e32 v74, v74
	v_mul_f32_e32 v77, v81, v82
	v_pk_add_f32 v[74:75], v[74:75], 1.0 op_sel_hi:[1,0]
	s_nop 0
	v_mul_f32_e32 v74, v74, v75
	v_rcp_f32_e32 v74, v74
	s_nop 0
	v_mul_f32_e32 v74, v77, v74
	v_cvt_pk_bf16_f32 v81, v76, v74
	v_lshlrev_b64 v[74:75], 13, v[170:171]
	v_lshl_add_u64 v[74:75], s[44:45], 0, v[74:75]
	v_lshl_add_u64 v[112:113], v[74:75], 0, v[204:205]
	v_or_b32_e32 v74, 0x80, v200
	v_ashrrev_i32_e32 v75, 31, v74
	v_ashrrev_i32_e32 v76, 4, v74
	v_mad_i64_i32 v[114:115], s[4:5], v76, s94, v[194:195]
	v_lshl_add_u64 v[76:77], s[46:47], 0, v[202:203]
	v_lshlrev_b64 v[116:117], 1, v[74:75]
	v_lshl_add_u64 v[74:75], v[76:77], 0, v[116:117]
	global_load_dwordx4 v[98:101], v[74:75], off
	s_nop 0
	global_store_dwordx4 v[112:113], v[78:81], off
	s_nop 1
	v_lshl_add_u64 v[78:79], v[114:115], 0, v[218:219]
	global_load_dwordx4 v[78:81], v[78:79], off
	v_lshl_add_u64 v[74:75], v[114:115], 0, v[206:207]
	global_load_dwordx4 v[102:105], v[74:75], off
	v_lshl_add_u64 v[74:75], s[46:47], 0, v[210:211]
	v_lshl_add_u64 v[74:75], v[74:75], 0, v[116:117]
	global_load_dwordx4 v[90:93], v[74:75], off
	v_lshl_add_u64 v[74:75], v[114:115], 0, v[208:209]
	global_load_dwordx4 v[94:97], v[74:75], off
	v_lshl_add_u64 v[74:75], s[46:47], 0, v[214:215]
	v_lshl_add_u64 v[74:75], v[74:75], 0, v[116:117]
	global_load_dwordx4 v[82:85], v[74:75], off
	v_lshl_add_u64 v[74:75], v[114:115], 0, v[212:213]
	global_load_dwordx4 v[86:89], v[74:75], off
	v_lshl_add_u64 v[74:75], s[46:47], 0, v[216:217]
	v_lshl_add_u64 v[74:75], v[74:75], 0, v[116:117]
	global_load_dwordx4 v[74:77], v[74:75], off
	s_waitcnt vmcnt(0)
; __device__ __forceinline__ unsigned cvt_pk_bf16(float lo, float hi) { unsigned r; asm volatile("v_cvt_pk_bf16_f32 %0, %1, %2" : "=v"(r) : "v"(lo), "v"(hi)); return r; }
; __device__ __forceinline__ float bf_lo(unsigned w) { return __uint_as_float(w << 16); }
; __device__ __forceinline__ float bf_hi(unsigned w) { return __uint_as_float(w & 0xffff0000u); }
;     __device__ __forceinline__ void operator()(const f32x4 (&acc)[2][2][4][2], const Unit& u, int wr, int wc, int fr, int fq, const Pre&) const {
;     ...
;                 for (int m = 0; m < 4; ++m) { const int r = row0 + ai * HALF + m * 16;
;                     const u32x4 zw = zv[m], gw = gv[m];
;                     const f32x4 a0 = acc[ai][bj][m][0] + bs[bj][0], a1 = acc[ai][bj][m][1] + bs[bj][1];
;                     u32x4 w;
;                     w.x = cvt_pk_bf16(glu_gate_f(bf_lo(gw.x), a0[0], bf_lo(zw.x)), glu_gate_f(bf_hi(gw.x), a0[1], bf_hi(zw.x)));
;                     w.y = cvt_pk_bf16(glu_gate_f(bf_lo(gw.y), a0[2], bf_lo(zw.y)), glu_gate_f(bf_hi(gw.y), a0[3], bf_hi(zw.y)));
;                     w.z = cvt_pk_bf16(glu_gate_f(bf_lo(gw.z), a1[0], bf_lo(zw.z)), glu_gate_f(bf_hi(gw.z), a1[1], bf_hi(zw.z)));
;                     w.w = cvt_pk_bf16(glu_gate_f(bf_lo(gw.w), a1[2], bf_lo(zw.w)), glu_gate_f(bf_hi(gw.w), a1[3], bf_hi(zw.w)));
;                     *(u32x4*)(O + (size_t)r * DE + c) = w; } } }
	v_lshlrev_b32_e32 v120, 16, v98
	v_mul_f32_e32 v70, 0xbfb8aa3b, v120
	v_exp_f32_e32 v119, v70
	v_and_b32_e32 v98, 0xffff0000, v98
	v_pk_add_f32 v[118:119], v[118:119], 1.0 op_sel_hi:[1,0]
	s_nop 0
	v_mul_f32_e32 v118, v118, v119
	v_rcp_f32_e32 v118, v118
	v_lshlrev_b32_e32 v121, 16, v102
	v_mul_f32_e32 v70, v121, v120
	v_and_b32_e32 v102, 0xffff0000, v102
	v_mul_f32_e32 v118, v70, v118
	v_mul_f32_e32 v70, 0xbfb8aa3b, v71
	v_mul_f32_e32 v71, 0xbfb8aa3b, v98
	v_exp_f32_e32 v70, v70
	v_exp_f32_e32 v71, v71
	v_mul_f32_e32 v98, v102, v98
	v_pk_add_f32 v[70:71], v[70:71], 1.0 op_sel_hi:[1,0]
	s_nop 0
	v_mul_f32_e32 v70, v70, v71
	v_rcp_f32_e32 v70, v70
	v_lshlrev_b32_e32 v71, 16, v99
	v_and_b32_e32 v99, 0xffff0000, v99
	v_mul_f32_e32 v70, v98, v70
	v_cvt_pk_bf16_f32 v70, v118, v70
	v_exp_f32_e32 v118, v72
	v_mul_f32_e32 v72, 0xbfb8aa3b, v71
	v_exp_f32_e32 v119, v72
	v_lshlrev_b32_e32 v98, 16, v103
	v_mul_f32_e32 v71, v98, v71
	v_and_b32_e32 v98, 0xffff0000, v103
	v_pk_add_f32 v[118:119], v[118:119], 1.0 op_sel_hi:[1,0]
	v_mul_f32_e32 v98, v98, v99
	v_mul_f32_e32 v72, v118, v119
	v_rcp_f32_e32 v72, v72
	s_nop 0
	v_mul_f32_e32 v71, v71, v72
	v_mul_f32_e32 v72, 0xbfb8aa3b, v73
	v_mul_f32_e32 v73, 0xbfb8aa3b, v99
	v_exp_f32_e32 v72, v72
	v_exp_f32_e32 v73, v73
	v_lshlrev_b32_e32 v99, 16, v104
	v_pk_add_f32 v[72:73], v[72:73], 1.0 op_sel_hi:[1,0]
	s_nop 0
	v_mul_f32_e32 v72, v72, v73
	v_rcp_f32_e32 v72, v72
	s_nop 0
	v_mul_f32_e32 v72, v98, v72
	v_lshlrev_b32_e32 v98, 16, v100
	v_cvt_pk_bf16_f32 v71, v71, v72
	v_exp_f32_e32 v72, v66
	v_mul_f32_e32 v66, 0xbfb8aa3b, v98
	v_exp_f32_e32 v73, v66
	v_mul_f32_e32 v66, v99, v98
	v_and_b32_e32 v98, 0xffff0000, v100
	v_pk_add_f32 v[72:73], v[72:73], 1.0 op_sel_hi:[1,0]
	s_nop 0
	v_mul_f32_e32 v72, v72, v73
	v_rcp_f32_e32 v72, v72
	v_and_b32_e32 v73, 0xffff0000, v104
	v_mul_f32_e32 v73, v73, v98
	v_mul_f32_e32 v72, v66, v72
	v_mul_f32_e32 v66, 0xbfb8aa3b, v67
	v_mul_f32_e32 v67, 0xbfb8aa3b, v98
	v_exp_f32_e32 v66, v66
	v_exp_f32_e32 v67, v67
	v_lshlrev_b32_e32 v98, 16, v105
	v_pk_add_f32 v[66:67], v[66:67], 1.0 op_sel_hi:[1,0]
	s_nop 0
	v_mul_f32_e32 v66, v66, v67
	v_rcp_f32_e32 v66, v66
	s_nop 0
	v_mul_f32_e32 v66, v73, v66
	v_lshlrev_b32_e32 v73, 16, v101
	v_cvt_pk_bf16_f32 v72, v72, v66
	v_mul_f32_e32 v66, 0xbfb8aa3b, v68
	v_mul_f32_e32 v67, 0xbfb8aa3b, v73
	v_exp_f32_e32 v66, v66
	v_exp_f32_e32 v67, v67
	v_mul_f32_e32 v68, v98, v73
	v_and_b32_e32 v98, 0xffff0000, v101
	v_and_b32_e32 v73, 0xffff0000, v105
	v_pk_add_f32 v[66:67], v[66:67], 1.0 op_sel_hi:[1,0]
	s_nop 0
	v_mul_f32_e32 v66, v66, v67
	v_rcp_f32_e32 v66, v66
	v_mul_f32_e32 v67, 0xbfb8aa3b, v98
	v_exp_f32_e32 v67, v67
	v_mul_f32_e32 v68, v68, v66
	v_mul_f32_e32 v66, 0xbfb8aa3b, v69
	v_exp_f32_e32 v66, v66
	v_mul_f32_e32 v69, v73, v98
	v_pk_add_f32 v[66:67], v[66:67], 1.0 op_sel_hi:[1,0]
	s_nop 0
	v_mul_f32_e32 v66, v66, v67
	v_rcp_f32_e32 v66, v66
	s_nop 0
	v_mul_f32_e32 v66, v69, v66
	v_cvt_pk_bf16_f32 v73, v68, v66
	v_lshlrev_b32_e32 v68, 16, v90
	v_exp_f32_e32 v66, v62
	v_mul_f32_e32 v62, 0xbfb8aa3b, v68
	v_exp_f32_e32 v67, v62
	v_lshlrev_b32_e32 v69, 16, v94
	v_mul_f32_e32 v62, v69, v68
	v_and_b32_e32 v68, 0xffff0000, v90
	v_pk_add_f32 v[66:67], v[66:67], 1.0 op_sel_hi:[1,0]
	global_store_dwordx4 v[162:163], v[70:73], off offset:256
	v_mul_f32_e32 v66, v66, v67
	v_rcp_f32_e32 v66, v66
	v_and_b32_e32 v67, 0xffff0000, v94
	v_mul_f32_e32 v67, v67, v68
	v_mul_f32_e32 v66, v62, v66
	v_mul_f32_e32 v62, 0xbfb8aa3b, v63
	v_mul_f32_e32 v63, 0xbfb8aa3b, v68
	v_exp_f32_e32 v62, v62
	v_exp_f32_e32 v63, v63
	v_lshlrev_b32_e32 v68, 16, v95
	v_pk_add_f32 v[62:63], v[62:63], 1.0 op_sel_hi:[1,0]
	s_nop 0
	v_mul_f32_e32 v62, v62, v63
	v_rcp_f32_e32 v62, v62
	v_lshlrev_b32_e32 v63, 16, v91
	v_mul_f32_e32 v62, v67, v62
	v_cvt_pk_bf16_f32 v62, v66, v62
	v_exp_f32_e32 v66, v64
	v_mul_f32_e32 v64, 0xbfb8aa3b, v63
	v_exp_f32_e32 v67, v64
	v_mul_f32_e32 v63, v68, v63
	v_pk_add_f32 v[66:67], v[66:67], 1.0 op_sel_hi:[1,0]
	s_nop 0
	v_mul_f32_e32 v64, v66, v67
	v_rcp_f32_e32 v64, v64
	v_and_b32_e32 v67, 0xffff0000, v91
	v_and_b32_e32 v66, 0xffff0000, v95
	v_mul_f32_e32 v66, v66, v67
	v_mul_f32_e32 v63, v63, v64
	v_mul_f32_e32 v64, 0xbfb8aa3b, v65
	v_mul_f32_e32 v65, 0xbfb8aa3b, v67
	v_exp_f32_e32 v64, v64
	v_exp_f32_e32 v65, v65
	v_lshlrev_b32_e32 v67, 16, v96
	v_pk_add_f32 v[64:65], v[64:65], 1.0 op_sel_hi:[1,0]
	s_nop 0
	v_mul_f32_e32 v64, v64, v65
	v_rcp_f32_e32 v64, v64
	s_nop 0
	v_mul_f32_e32 v64, v66, v64
	v_lshlrev_b32_e32 v66, 16, v92
	v_cvt_pk_bf16_f32 v63, v63, v64
	v_exp_f32_e32 v64, v58
	v_mul_f32_e32 v58, 0xbfb8aa3b, v66
	v_exp_f32_e32 v65, v58
	v_mul_f32_e32 v58, v67, v66
	v_and_b32_e32 v66, 0xffff0000, v92
	v_pk_add_f32 v[64:65], v[64:65], 1.0 op_sel_hi:[1,0]
	s_nop 0
	v_mul_f32_e32 v64, v64, v65
	v_rcp_f32_e32 v64, v64
	v_and_b32_e32 v65, 0xffff0000, v96
	v_mul_f32_e32 v65, v65, v66
	v_mul_f32_e32 v64, v58, v64
	v_mul_f32_e32 v58, 0xbfb8aa3b, v59
	v_mul_f32_e32 v59, 0xbfb8aa3b, v66
	v_exp_f32_e32 v58, v58
	v_exp_f32_e32 v59, v59
	v_lshlrev_b32_e32 v66, 16, v97
	v_pk_add_f32 v[58:59], v[58:59], 1.0 op_sel_hi:[1,0]
	s_nop 0
	v_mul_f32_e32 v58, v58, v59
	v_rcp_f32_e32 v58, v58
	s_nop 0
	v_mul_f32_e32 v58, v65, v58
	v_lshlrev_b32_e32 v65, 16, v93
	v_cvt_pk_bf16_f32 v64, v64, v58
	v_mul_f32_e32 v58, 0xbfb8aa3b, v60
	v_mul_f32_e32 v59, 0xbfb8aa3b, v65
	v_exp_f32_e32 v58, v58
	v_exp_f32_e32 v59, v59
	v_mul_f32_e32 v60, v66, v65
	v_and_b32_e32 v66, 0xffff0000, v93
	v_and_b32_e32 v65, 0xffff0000, v97
	v_pk_add_f32 v[58:59], v[58:59], 1.0 op_sel_hi:[1,0]
	s_nop 0
	v_mul_f32_e32 v58, v58, v59
	v_rcp_f32_e32 v58, v58
	v_mul_f32_e32 v59, 0xbfb8aa3b, v66
; __device__ __forceinline__ unsigned cvt_pk_bf16(float lo, float hi) { unsigned r; asm volatile("v_cvt_pk_bf16_f32 %0, %1, %2" : "=v"(r) : "v"(lo), "v"(hi)); return r; }
; __device__ __forceinline__ float bf_lo(unsigned w) { return __uint_as_float(w << 16); }
; __device__ __forceinline__ float bf_hi(unsigned w) { return __uint_as_float(w & 0xffff0000u); }
;     __device__ __forceinline__ void operator()(const f32x4 (&acc)[2][2][4][2], const Unit& u, int wr, int wc, int fr, int fq, const Pre&) const {
;     ...
;                 for (int m = 0; m < 4; ++m) { const int r = row0 + ai * HALF + m * 16;
;                     const u32x4 zw = zv[m], gw = gv[m];
;                     const f32x4 a0 = acc[ai][bj][m][0] + bs[bj][0], a1 = acc[ai][bj][m][1] + bs[bj][1];
;                     u32x4 w;
;                     w.x = cvt_pk_bf16(glu_gate_f(bf_lo(gw.x), a0[0], bf_lo(zw.x)), glu_gate_f(bf_hi(gw.x), a0[1], bf_hi(zw.x)));
;                     w.y = cvt_pk_bf16(glu_gate_f(bf_lo(gw.y), a0[2], bf_lo(zw.y)), glu_gate_f(bf_hi(gw.y), a0[3], bf_hi(zw.y)));
;                     w.z = cvt_pk_bf16(glu_gate_f(bf_lo(gw.z), a1[0], bf_lo(zw.z)), glu_gate_f(bf_hi(gw.z), a1[1], bf_hi(zw.z)));
;                     w.w = cvt_pk_bf16(glu_gate_f(bf_lo(gw.w), a1[2], bf_lo(zw.w)), glu_gate_f(bf_hi(gw.w), a1[3], bf_hi(zw.w)));
;                     *(u32x4*)(O + (size_t)r * DE + c) = w; } } }
	v_exp_f32_e32 v59, v59
	v_mul_f32_e32 v60, v60, v58
	v_mul_f32_e32 v58, 0xbfb8aa3b, v61
	v_exp_f32_e32 v58, v58
	v_mul_f32_e32 v61, v65, v66
	v_pk_add_f32 v[58:59], v[58:59], 1.0 op_sel_hi:[1,0]
	s_nop 0
	v_mul_f32_e32 v58, v58, v59
	v_rcp_f32_e32 v58, v58
	s_nop 0
	v_mul_f32_e32 v58, v61, v58
	v_cvt_pk_bf16_f32 v65, v60, v58
	v_lshlrev_b32_e32 v60, 16, v82
	v_exp_f32_e32 v58, v54
	v_mul_f32_e32 v54, 0xbfb8aa3b, v60
	v_exp_f32_e32 v59, v54
	v_lshlrev_b32_e32 v61, 16, v86
	v_mul_f32_e32 v54, v61, v60
	v_and_b32_e32 v60, 0xffff0000, v82
	v_pk_add_f32 v[58:59], v[58:59], 1.0 op_sel_hi:[1,0]
	global_store_dwordx4 v[154:155], v[62:65], off offset:256
	v_mul_f32_e32 v58, v58, v59
	v_rcp_f32_e32 v58, v58
	v_and_b32_e32 v59, 0xffff0000, v86
	v_mul_f32_e32 v59, v59, v60
	v_mul_f32_e32 v58, v54, v58
	v_mul_f32_e32 v54, 0xbfb8aa3b, v55
	v_mul_f32_e32 v55, 0xbfb8aa3b, v60
	v_exp_f32_e32 v54, v54
	v_exp_f32_e32 v55, v55
	v_lshlrev_b32_e32 v60, 16, v87
	v_pk_add_f32 v[54:55], v[54:55], 1.0 op_sel_hi:[1,0]
	s_nop 0
	v_mul_f32_e32 v54, v54, v55
	v_rcp_f32_e32 v54, v54
	v_lshlrev_b32_e32 v55, 16, v83
	v_mul_f32_e32 v54, v59, v54
	v_cvt_pk_bf16_f32 v54, v58, v54
	v_exp_f32_e32 v58, v56
	v_mul_f32_e32 v56, 0xbfb8aa3b, v55
	v_exp_f32_e32 v59, v56
	v_mul_f32_e32 v55, v60, v55
	v_pk_add_f32 v[58:59], v[58:59], 1.0 op_sel_hi:[1,0]
	s_nop 0
	v_mul_f32_e32 v56, v58, v59
	v_rcp_f32_e32 v56, v56
	v_and_b32_e32 v59, 0xffff0000, v83
	v_and_b32_e32 v58, 0xffff0000, v87
	v_mul_f32_e32 v58, v58, v59
	v_mul_f32_e32 v55, v55, v56
	v_mul_f32_e32 v56, 0xbfb8aa3b, v57
	v_mul_f32_e32 v57, 0xbfb8aa3b, v59
	v_exp_f32_e32 v56, v56
	v_exp_f32_e32 v57, v57
	v_lshlrev_b32_e32 v59, 16, v88
	v_pk_add_f32 v[56:57], v[56:57], 1.0 op_sel_hi:[1,0]
	s_nop 0
	v_mul_f32_e32 v56, v56, v57
	v_rcp_f32_e32 v56, v56
	s_nop 0
	v_mul_f32_e32 v56, v58, v56
	v_lshlrev_b32_e32 v58, 16, v84
	v_cvt_pk_bf16_f32 v55, v55, v56
	v_exp_f32_e32 v56, v50
	v_mul_f32_e32 v50, 0xbfb8aa3b, v58
	v_exp_f32_e32 v57, v50
	v_mul_f32_e32 v50, v59, v58
	v_and_b32_e32 v58, 0xffff0000, v84
	v_pk_add_f32 v[56:57], v[56:57], 1.0 op_sel_hi:[1,0]
	s_nop 0
	v_mul_f32_e32 v56, v56, v57
	v_rcp_f32_e32 v56, v56
	v_and_b32_e32 v57, 0xffff0000, v88
	v_mul_f32_e32 v57, v57, v58
	v_mul_f32_e32 v56, v50, v56
	v_mul_f32_e32 v50, 0xbfb8aa3b, v51
	v_mul_f32_e32 v51, 0xbfb8aa3b, v58
	v_exp_f32_e32 v50, v50
	v_exp_f32_e32 v51, v51
	v_lshlrev_b32_e32 v58, 16, v89
	v_pk_add_f32 v[50:51], v[50:51], 1.0 op_sel_hi:[1,0]
	s_nop 0
	v_mul_f32_e32 v50, v50, v51
	v_rcp_f32_e32 v50, v50
	s_nop 0
	v_mul_f32_e32 v50, v57, v50
	v_lshlrev_b32_e32 v57, 16, v85
	v_cvt_pk_bf16_f32 v56, v56, v50
	v_mul_f32_e32 v50, 0xbfb8aa3b, v52
	v_mul_f32_e32 v51, 0xbfb8aa3b, v57
	v_exp_f32_e32 v50, v50
	v_exp_f32_e32 v51, v51
	v_mul_f32_e32 v52, v58, v57
	v_and_b32_e32 v58, 0xffff0000, v85
	v_and_b32_e32 v57, 0xffff0000, v89
	v_pk_add_f32 v[50:51], v[50:51], 1.0 op_sel_hi:[1,0]
	s_nop 0
	v_mul_f32_e32 v50, v50, v51
	v_rcp_f32_e32 v50, v50
	v_mul_f32_e32 v51, 0xbfb8aa3b, v58
	v_exp_f32_e32 v51, v51
	v_mul_f32_e32 v52, v52, v50
	v_mul_f32_e32 v50, 0xbfb8aa3b, v53
	v_exp_f32_e32 v50, v50
	v_mul_f32_e32 v53, v57, v58
	v_pk_add_f32 v[50:51], v[50:51], 1.0 op_sel_hi:[1,0]
	s_nop 0
	v_mul_f32_e32 v50, v50, v51
	v_rcp_f32_e32 v50, v50
	s_nop 0
	v_mul_f32_e32 v50, v53, v50
	v_cvt_pk_bf16_f32 v57, v52, v50
	v_lshlrev_b32_e32 v52, 16, v74
	v_exp_f32_e32 v50, v46
	v_mul_f32_e32 v46, 0xbfb8aa3b, v52
	v_exp_f32_e32 v51, v46
	v_lshlrev_b32_e32 v53, 16, v78
	v_mul_f32_e32 v46, v53, v52
	v_and_b32_e32 v52, 0xffff0000, v74
	v_pk_add_f32 v[50:51], v[50:51], 1.0 op_sel_hi:[1,0]
	global_store_dwordx4 v[146:147], v[54:57], off offset:256
	v_mul_f32_e32 v50, v50, v51
	v_rcp_f32_e32 v50, v50
	v_and_b32_e32 v51, 0xffff0000, v78
	v_mul_f32_e32 v51, v51, v52
	v_exp_f32_e32 v74, v38
	v_mul_f32_e32 v50, v46, v50
	v_mul_f32_e32 v46, 0xbfb8aa3b, v47
	v_mul_f32_e32 v47, 0xbfb8aa3b, v52
	v_exp_f32_e32 v46, v46
	v_exp_f32_e32 v47, v47
	v_lshlrev_b32_e32 v52, 16, v79
	v_pk_add_f32 v[46:47], v[46:47], 1.0 op_sel_hi:[1,0]
	s_nop 0
	v_mul_f32_e32 v46, v46, v47
	v_rcp_f32_e32 v46, v46
	v_lshlrev_b32_e32 v47, 16, v75
	v_mul_f32_e32 v46, v51, v46
	v_cvt_pk_bf16_f32 v46, v50, v46
	v_exp_f32_e32 v50, v48
	v_mul_f32_e32 v48, 0xbfb8aa3b, v47
	v_exp_f32_e32 v51, v48
	v_mul_f32_e32 v47, v52, v47
	v_pk_add_f32 v[50:51], v[50:51], 1.0 op_sel_hi:[1,0]
	s_nop 0
	v_mul_f32_e32 v48, v50, v51
	v_rcp_f32_e32 v48, v48
	v_and_b32_e32 v51, 0xffff0000, v75
	v_and_b32_e32 v50, 0xffff0000, v79
	v_mul_f32_e32 v50, v50, v51
	v_mul_f32_e32 v47, v47, v48
	v_mul_f32_e32 v48, 0xbfb8aa3b, v49
	v_mul_f32_e32 v49, 0xbfb8aa3b, v51
	v_exp_f32_e32 v48, v48
	v_exp_f32_e32 v49, v49
	v_lshlrev_b32_e32 v51, 16, v80
	v_pk_add_f32 v[48:49], v[48:49], 1.0 op_sel_hi:[1,0]
	s_nop 0
	v_mul_f32_e32 v48, v48, v49
	v_rcp_f32_e32 v48, v48
	s_nop 0
	v_mul_f32_e32 v48, v50, v48
	v_lshlrev_b32_e32 v50, 16, v76
	v_cvt_pk_bf16_f32 v47, v47, v48
	v_exp_f32_e32 v48, v42
	v_mul_f32_e32 v42, 0xbfb8aa3b, v50
	v_exp_f32_e32 v49, v42
	v_mul_f32_e32 v42, v51, v50
	v_and_b32_e32 v50, 0xffff0000, v76
	v_pk_add_f32 v[48:49], v[48:49], 1.0 op_sel_hi:[1,0]
	s_nop 0
	v_mul_f32_e32 v48, v48, v49
	v_rcp_f32_e32 v48, v48
	v_and_b32_e32 v49, 0xffff0000, v80
	v_mul_f32_e32 v49, v49, v50
	v_mul_f32_e32 v48, v42, v48
	v_mul_f32_e32 v42, 0xbfb8aa3b, v43
	v_mul_f32_e32 v43, 0xbfb8aa3b, v50
	v_exp_f32_e32 v42, v42
	v_exp_f32_e32 v43, v43
	v_lshlrev_b32_e32 v50, 16, v81
	v_pk_add_f32 v[42:43], v[42:43], 1.0 op_sel_hi:[1,0]
	s_nop 0
	v_mul_f32_e32 v42, v42, v43
	v_rcp_f32_e32 v42, v42
	s_nop 0
	v_mul_f32_e32 v42, v49, v42
	v_lshlrev_b32_e32 v49, 16, v77
	v_cvt_pk_bf16_f32 v48, v48, v42
; __device__ __forceinline__ unsigned cvt_pk_bf16(float lo, float hi) { unsigned r; asm volatile("v_cvt_pk_bf16_f32 %0, %1, %2" : "=v"(r) : "v"(lo), "v"(hi)); return r; }
; __device__ __forceinline__ float bf_lo(unsigned w) { return __uint_as_float(w << 16); }
; __device__ __forceinline__ float bf_hi(unsigned w) { return __uint_as_float(w & 0xffff0000u); }
;     __device__ __forceinline__ void operator()(const f32x4 (&acc)[2][2][4][2], const Unit& u, int wr, int wc, int fr, int fq, const Pre&) const {
;     ...
;             for (int ai = 0; ai < 2; ++ai) { u32x4 zv[4], gv[4];
; #pragma unroll
;                 for (int m = 0; m < 4; ++m) { const int r = row0 + ai * HALF + m * 16; zv[m] = *(const u32x4*)(Z + (size_t)r * DE2 + c); gv[m] = *(const u32x4*)(Gm + (size_t)(c >> 4) * GSTR + r * 16 + (c & 15)); }
; #pragma unroll
;                 for (int m = 0; m < 4; ++m) { const int r = row0 + ai * HALF + m * 16;
;                     const u32x4 zw = zv[m], gw = gv[m];
;                     const f32x4 a0 = acc[ai][bj][m][0] + bs[bj][0], a1 = acc[ai][bj][m][1] + bs[bj][1];
;                     u32x4 w;
;                     w.x = cvt_pk_bf16(glu_gate_f(bf_lo(gw.x), a0[0], bf_lo(zw.x)), glu_gate_f(bf_hi(gw.x), a0[1], bf_hi(zw.x)));
;                     w.y = cvt_pk_bf16(glu_gate_f(bf_lo(gw.y), a0[2], bf_lo(zw.y)), glu_gate_f(bf_hi(gw.y), a0[3], bf_hi(zw.y)));
;                     w.z = cvt_pk_bf16(glu_gate_f(bf_lo(gw.z), a1[0], bf_lo(zw.z)), glu_gate_f(bf_hi(gw.z), a1[1], bf_hi(zw.z)));
;                     w.w = cvt_pk_bf16(glu_gate_f(bf_lo(gw.w), a1[2], bf_lo(zw.w)), glu_gate_f(bf_hi(gw.w), a1[3], bf_hi(zw.w)));
;                     *(u32x4*)(O + (size_t)r * DE + c) = w; } } }
	v_mul_f32_e32 v42, 0xbfb8aa3b, v44
	v_mul_f32_e32 v43, 0xbfb8aa3b, v49
	v_exp_f32_e32 v42, v42
	v_exp_f32_e32 v43, v43
	v_mul_f32_e32 v44, v50, v49
	v_and_b32_e32 v50, 0xffff0000, v77
	v_and_b32_e32 v49, 0xffff0000, v81
	v_pk_add_f32 v[42:43], v[42:43], 1.0 op_sel_hi:[1,0]
	s_nop 0
	v_mul_f32_e32 v42, v42, v43
	v_rcp_f32_e32 v42, v42
	v_mul_f32_e32 v43, 0xbfb8aa3b, v50
	v_exp_f32_e32 v43, v43
	v_mul_f32_e32 v44, v44, v42
	v_mul_f32_e32 v42, 0xbfb8aa3b, v45
	v_exp_f32_e32 v42, v42
	v_mul_f32_e32 v45, v49, v50
	v_pk_add_f32 v[42:43], v[42:43], 1.0 op_sel_hi:[1,0]
	s_nop 0
	v_mul_f32_e32 v42, v42, v43
	v_rcp_f32_e32 v42, v42
	s_nop 0
	v_mul_f32_e32 v42, v45, v42
	v_cvt_pk_bf16_f32 v49, v44, v42
	v_lshl_add_u64 v[42:43], s[46:47], 0, v[150:151]
	global_store_dwordx4 v[148:149], v[46:49], off offset:256
	v_lshl_add_u64 v[42:43], v[42:43], 0, v[116:117]
	global_load_dwordx4 v[66:69], v[42:43], off
	v_lshl_add_u64 v[46:47], v[114:115], 0, v[168:169]
	global_load_dwordx4 v[46:49], v[46:47], off
	v_lshl_add_u64 v[42:43], v[114:115], 0, v[152:153]
	global_load_dwordx4 v[70:73], v[42:43], off
	v_lshl_add_u64 v[42:43], s[46:47], 0, v[156:157]
	v_lshl_add_u64 v[42:43], v[42:43], 0, v[116:117]
	global_load_dwordx4 v[58:61], v[42:43], off
	v_lshl_add_u64 v[42:43], v[114:115], 0, v[158:159]
	global_load_dwordx4 v[62:65], v[42:43], off
	v_lshl_add_u64 v[42:43], s[46:47], 0, v[160:161]
	v_lshl_add_u64 v[42:43], v[42:43], 0, v[116:117]
	global_load_dwordx4 v[50:53], v[42:43], off
	v_lshl_add_u64 v[42:43], v[114:115], 0, v[164:165]
	global_load_dwordx4 v[54:57], v[42:43], off
	v_lshl_add_u64 v[42:43], s[46:47], 0, v[166:167]
	v_lshl_add_u64 v[42:43], v[42:43], 0, v[116:117]
	global_load_dwordx4 v[42:45], v[42:43], off
	s_waitcnt vmcnt(0)
	v_lshlrev_b32_e32 v76, 16, v66
	v_mul_f32_e32 v38, 0xbfb8aa3b, v76
	v_exp_f32_e32 v75, v38
	v_and_b32_e32 v66, 0xffff0000, v66
	v_lshlrev_b32_e32 v77, 16, v70
	v_mul_f32_e32 v38, v77, v76
	v_pk_add_f32 v[74:75], v[74:75], 1.0 op_sel_hi:[1,0]
	v_and_b32_e32 v70, 0xffff0000, v70
	v_mul_f32_e32 v74, v74, v75
	v_rcp_f32_e32 v74, v74
	s_nop 0
	v_mul_f32_e32 v74, v38, v74
	v_mul_f32_e32 v38, 0xbfb8aa3b, v39
	v_mul_f32_e32 v39, 0xbfb8aa3b, v66
	v_exp_f32_e32 v38, v38
	v_exp_f32_e32 v39, v39
	v_mul_f32_e32 v66, v70, v66
	v_pk_add_f32 v[38:39], v[38:39], 1.0 op_sel_hi:[1,0]
	s_nop 0
	v_mul_f32_e32 v38, v38, v39
	v_rcp_f32_e32 v38, v38
	v_lshlrev_b32_e32 v39, 16, v67
	v_and_b32_e32 v67, 0xffff0000, v67
	v_mul_f32_e32 v38, v66, v38
	v_cvt_pk_bf16_f32 v38, v74, v38
	v_exp_f32_e32 v74, v40
	v_mul_f32_e32 v40, 0xbfb8aa3b, v39
	v_exp_f32_e32 v75, v40
	v_lshlrev_b32_e32 v66, 16, v71
	v_mul_f32_e32 v39, v66, v39
	v_and_b32_e32 v66, 0xffff0000, v71
	v_pk_add_f32 v[74:75], v[74:75], 1.0 op_sel_hi:[1,0]
	v_mul_f32_e32 v66, v66, v67
	v_mul_f32_e32 v40, v74, v75
	v_rcp_f32_e32 v40, v40
	s_nop 0
	v_mul_f32_e32 v39, v39, v40
	v_mul_f32_e32 v40, 0xbfb8aa3b, v41
	v_mul_f32_e32 v41, 0xbfb8aa3b, v67
	v_exp_f32_e32 v40, v40
	v_exp_f32_e32 v41, v41
	v_lshlrev_b32_e32 v67, 16, v72
	v_pk_add_f32 v[40:41], v[40:41], 1.0 op_sel_hi:[1,0]
	s_nop 0
	v_mul_f32_e32 v40, v40, v41
	v_rcp_f32_e32 v40, v40
	s_nop 0
	v_mul_f32_e32 v40, v66, v40
	v_lshlrev_b32_e32 v66, 16, v68
	v_cvt_pk_bf16_f32 v39, v39, v40
	v_exp_f32_e32 v40, v34
	v_mul_f32_e32 v34, 0xbfb8aa3b, v66
	v_exp_f32_e32 v41, v34
	v_mul_f32_e32 v34, v67, v66
	v_and_b32_e32 v66, 0xffff0000, v68
	v_pk_add_f32 v[40:41], v[40:41], 1.0 op_sel_hi:[1,0]
	s_nop 0
	v_mul_f32_e32 v40, v40, v41
	v_rcp_f32_e32 v40, v40
	v_and_b32_e32 v41, 0xffff0000, v72
	v_mul_f32_e32 v41, v41, v66
	v_mul_f32_e32 v40, v34, v40
	v_mul_f32_e32 v34, 0xbfb8aa3b, v35
	v_mul_f32_e32 v35, 0xbfb8aa3b, v66
	v_exp_f32_e32 v34, v34
	v_exp_f32_e32 v35, v35
	v_lshlrev_b32_e32 v66, 16, v73
	v_pk_add_f32 v[34:35], v[34:35], 1.0 op_sel_hi:[1,0]
	s_nop 0
	v_mul_f32_e32 v34, v34, v35
	v_rcp_f32_e32 v34, v34
	s_nop 0
	v_mul_f32_e32 v34, v41, v34
	v_lshlrev_b32_e32 v41, 16, v69
	v_cvt_pk_bf16_f32 v40, v40, v34
	v_mul_f32_e32 v34, 0xbfb8aa3b, v36
	v_mul_f32_e32 v35, 0xbfb8aa3b, v41
	v_exp_f32_e32 v34, v34
	v_exp_f32_e32 v35, v35
	v_mul_f32_e32 v36, v66, v41
	v_and_b32_e32 v66, 0xffff0000, v69
	v_and_b32_e32 v41, 0xffff0000, v73
	v_pk_add_f32 v[34:35], v[34:35], 1.0 op_sel_hi:[1,0]
	s_nop 0
	v_mul_f32_e32 v34, v34, v35
	v_rcp_f32_e32 v34, v34
	v_mul_f32_e32 v35, 0xbfb8aa3b, v66
	v_exp_f32_e32 v35, v35
	v_mul_f32_e32 v36, v36, v34
	v_mul_f32_e32 v34, 0xbfb8aa3b, v37
	v_exp_f32_e32 v34, v34
	v_mul_f32_e32 v37, v41, v66
	v_pk_add_f32 v[34:35], v[34:35], 1.0 op_sel_hi:[1,0]
	s_nop 0
	v_mul_f32_e32 v34, v34, v35
	v_rcp_f32_e32 v34, v34
	s_nop 0
	v_mul_f32_e32 v34, v37, v34
	v_cvt_pk_bf16_f32 v41, v36, v34
	v_lshlrev_b32_e32 v36, 16, v58
	v_exp_f32_e32 v34, v22
	v_mul_f32_e32 v22, 0xbfb8aa3b, v36
	v_exp_f32_e32 v35, v22
	v_lshlrev_b32_e32 v37, 16, v62
	v_mul_f32_e32 v22, v37, v36
	v_and_b32_e32 v36, 0xffff0000, v58
	v_pk_add_f32 v[34:35], v[34:35], 1.0 op_sel_hi:[1,0]
	global_store_dwordx4 v[106:107], v[38:41], off offset:256
	v_mul_f32_e32 v34, v34, v35
	v_rcp_f32_e32 v34, v34
	v_and_b32_e32 v35, 0xffff0000, v62
	v_mul_f32_e32 v35, v35, v36
	v_mul_f32_e32 v34, v22, v34
	v_mul_f32_e32 v22, 0xbfb8aa3b, v23
	v_mul_f32_e32 v23, 0xbfb8aa3b, v36
	v_exp_f32_e32 v22, v22
	v_exp_f32_e32 v23, v23
	v_lshlrev_b32_e32 v36, 16, v63
	v_pk_add_f32 v[22:23], v[22:23], 1.0 op_sel_hi:[1,0]
	s_nop 0
	v_mul_f32_e32 v22, v22, v23
	v_rcp_f32_e32 v22, v22
	v_lshlrev_b32_e32 v23, 16, v59
	v_mul_f32_e32 v22, v35, v22
	v_cvt_pk_bf16_f32 v22, v34, v22
	v_exp_f32_e32 v34, v24
	v_mul_f32_e32 v24, 0xbfb8aa3b, v23
	v_exp_f32_e32 v35, v24
	v_mul_f32_e32 v23, v36, v23
; __device__ __forceinline__ unsigned cvt_pk_bf16(float lo, float hi) { unsigned r; asm volatile("v_cvt_pk_bf16_f32 %0, %1, %2" : "=v"(r) : "v"(lo), "v"(hi)); return r; }
; __device__ __forceinline__ float bf_lo(unsigned w) { return __uint_as_float(w << 16); }
; __device__ __forceinline__ float bf_hi(unsigned w) { return __uint_as_float(w & 0xffff0000u); }
; __device__ __forceinline__ float fast_rcp(float x) { return __builtin_amdgcn_rcpf(x); }
; __device__ __forceinline__ float glu_gate_f(float g, float v, float z) {
;     const float ev = __builtin_amdgcn_exp2f(v * -1.44269504f), ez = __builtin_amdgcn_exp2f(z * -1.44269504f);
;     return g * z * fast_rcp((1.0f + ev) * (1.0f + ez));
;     __device__ __forceinline__ void operator()(const f32x4 (&acc)[2][2][4][2], const Unit& u, int wr, int wc, int fr, int fq, const Pre&) const {
;     ...
;                 for (int m = 0; m < 4; ++m) { const int r = row0 + ai * HALF + m * 16;
;                     const u32x4 zw = zv[m], gw = gv[m];
;                     const f32x4 a0 = acc[ai][bj][m][0] + bs[bj][0], a1 = acc[ai][bj][m][1] + bs[bj][1];
;                     u32x4 w;
;                     w.x = cvt_pk_bf16(glu_gate_f(bf_lo(gw.x), a0[0], bf_lo(zw.x)), glu_gate_f(bf_hi(gw.x), a0[1], bf_hi(zw.x)));
;                     w.y = cvt_pk_bf16(glu_gate_f(bf_lo(gw.y), a0[2], bf_lo(zw.y)), glu_gate_f(bf_hi(gw.y), a0[3], bf_hi(zw.y)));
;                     w.z = cvt_pk_bf16(glu_gate_f(bf_lo(gw.z), a1[0], bf_lo(zw.z)), glu_gate_f(bf_hi(gw.z), a1[1], bf_hi(zw.z)));
;                     w.w = cvt_pk_bf16(glu_gate_f(bf_lo(gw.w), a1[2], bf_lo(zw.w)), glu_gate_f(bf_hi(gw.w), a1[3], bf_hi(zw.w)));
;                     *(u32x4*)(O + (size_t)r * DE + c) = w; } } }
	v_pk_add_f32 v[34:35], v[34:35], 1.0 op_sel_hi:[1,0]
	s_nop 0
	v_mul_f32_e32 v24, v34, v35
	v_rcp_f32_e32 v24, v24
	v_and_b32_e32 v35, 0xffff0000, v59
	v_and_b32_e32 v34, 0xffff0000, v63
	v_mul_f32_e32 v34, v34, v35
	v_mul_f32_e32 v23, v23, v24
	v_mul_f32_e32 v24, 0xbfb8aa3b, v25
	v_mul_f32_e32 v25, 0xbfb8aa3b, v35
	v_exp_f32_e32 v24, v24
	v_exp_f32_e32 v25, v25
	v_lshlrev_b32_e32 v35, 16, v64
	v_pk_add_f32 v[24:25], v[24:25], 1.0 op_sel_hi:[1,0]
	s_nop 0
	v_mul_f32_e32 v24, v24, v25
	v_rcp_f32_e32 v24, v24
	s_nop 0
	v_mul_f32_e32 v24, v34, v24
	v_lshlrev_b32_e32 v34, 16, v60
	v_cvt_pk_bf16_f32 v23, v23, v24
	v_exp_f32_e32 v24, v18
	v_mul_f32_e32 v18, 0xbfb8aa3b, v34
	v_exp_f32_e32 v25, v18
	v_mul_f32_e32 v18, v35, v34
	v_and_b32_e32 v34, 0xffff0000, v60
	v_pk_add_f32 v[24:25], v[24:25], 1.0 op_sel_hi:[1,0]
	s_nop 0
	v_mul_f32_e32 v24, v24, v25
	v_rcp_f32_e32 v24, v24
	v_and_b32_e32 v25, 0xffff0000, v64
	v_mul_f32_e32 v25, v25, v34
	v_mul_f32_e32 v24, v18, v24
	v_mul_f32_e32 v18, 0xbfb8aa3b, v19
	v_mul_f32_e32 v19, 0xbfb8aa3b, v34
	v_exp_f32_e32 v18, v18
	v_exp_f32_e32 v19, v19
	v_lshlrev_b32_e32 v34, 16, v65
	v_pk_add_f32 v[18:19], v[18:19], 1.0 op_sel_hi:[1,0]
	s_nop 0
	v_mul_f32_e32 v18, v18, v19
	v_rcp_f32_e32 v18, v18
	s_nop 0
	v_mul_f32_e32 v18, v25, v18
	v_lshlrev_b32_e32 v25, 16, v61
	v_cvt_pk_bf16_f32 v24, v24, v18
	v_mul_f32_e32 v18, 0xbfb8aa3b, v20
	v_mul_f32_e32 v19, 0xbfb8aa3b, v25
	v_exp_f32_e32 v18, v18
	v_exp_f32_e32 v19, v19
	v_mul_f32_e32 v20, v34, v25
	v_and_b32_e32 v34, 0xffff0000, v61
	v_and_b32_e32 v25, 0xffff0000, v65
	v_pk_add_f32 v[18:19], v[18:19], 1.0 op_sel_hi:[1,0]
	s_nop 0
	v_mul_f32_e32 v18, v18, v19
	v_rcp_f32_e32 v18, v18
	v_mul_f32_e32 v19, 0xbfb8aa3b, v34
	v_exp_f32_e32 v19, v19
	v_mul_f32_e32 v20, v20, v18
	v_mul_f32_e32 v18, 0xbfb8aa3b, v21
	v_exp_f32_e32 v18, v18
	v_mul_f32_e32 v21, v25, v34
	v_pk_add_f32 v[18:19], v[18:19], 1.0 op_sel_hi:[1,0]
	s_nop 0
	v_mul_f32_e32 v18, v18, v19
	v_rcp_f32_e32 v18, v18
	s_nop 0
	v_mul_f32_e32 v18, v21, v18
	v_cvt_pk_bf16_f32 v25, v20, v18
	v_lshlrev_b32_e32 v20, 16, v50
	v_exp_f32_e32 v18, v14
	v_mul_f32_e32 v14, 0xbfb8aa3b, v20
	v_exp_f32_e32 v19, v14
	v_lshlrev_b32_e32 v21, 16, v54
	v_mul_f32_e32 v14, v21, v20
	v_and_b32_e32 v20, 0xffff0000, v50
	v_pk_add_f32 v[18:19], v[18:19], 1.0 op_sel_hi:[1,0]
	global_store_dwordx4 v[108:109], v[22:25], off offset:256
	v_mul_f32_e32 v18, v18, v19
	v_rcp_f32_e32 v18, v18
	v_and_b32_e32 v19, 0xffff0000, v54
	v_mul_f32_e32 v19, v19, v20
	v_mul_f32_e32 v18, v14, v18
	v_mul_f32_e32 v14, 0xbfb8aa3b, v15
	v_mul_f32_e32 v15, 0xbfb8aa3b, v20
	v_exp_f32_e32 v14, v14
	v_exp_f32_e32 v15, v15
	v_lshlrev_b32_e32 v20, 16, v55
	v_pk_add_f32 v[14:15], v[14:15], 1.0 op_sel_hi:[1,0]
	s_nop 0
	v_mul_f32_e32 v14, v14, v15
	v_rcp_f32_e32 v14, v14
	v_lshlrev_b32_e32 v15, 16, v51
	v_mul_f32_e32 v14, v19, v14
	v_cvt_pk_bf16_f32 v14, v18, v14
	v_exp_f32_e32 v18, v16
	v_mul_f32_e32 v16, 0xbfb8aa3b, v15
	v_exp_f32_e32 v19, v16
	v_mul_f32_e32 v15, v20, v15
	v_pk_add_f32 v[18:19], v[18:19], 1.0 op_sel_hi:[1,0]
	s_nop 0
	v_mul_f32_e32 v16, v18, v19
	v_rcp_f32_e32 v16, v16
	v_and_b32_e32 v19, 0xffff0000, v51
	v_and_b32_e32 v18, 0xffff0000, v55
	v_mul_f32_e32 v18, v18, v19
	v_mul_f32_e32 v15, v15, v16
	v_mul_f32_e32 v16, 0xbfb8aa3b, v17
	v_mul_f32_e32 v17, 0xbfb8aa3b, v19
	v_exp_f32_e32 v16, v16
	v_exp_f32_e32 v17, v17
	v_lshlrev_b32_e32 v19, 16, v56
	v_pk_add_f32 v[16:17], v[16:17], 1.0 op_sel_hi:[1,0]
	s_nop 0
	v_mul_f32_e32 v16, v16, v17
	v_rcp_f32_e32 v16, v16
	s_nop 0
	v_mul_f32_e32 v16, v18, v16
	v_lshlrev_b32_e32 v18, 16, v52
	v_cvt_pk_bf16_f32 v15, v15, v16
	v_exp_f32_e32 v16, v10
	v_mul_f32_e32 v10, 0xbfb8aa3b, v18
	v_exp_f32_e32 v17, v10
	v_mul_f32_e32 v10, v19, v18
	v_and_b32_e32 v18, 0xffff0000, v52
	v_pk_add_f32 v[16:17], v[16:17], 1.0 op_sel_hi:[1,0]
	s_nop 0
	v_mul_f32_e32 v16, v16, v17
	v_rcp_f32_e32 v16, v16
	v_and_b32_e32 v17, 0xffff0000, v56
	v_mul_f32_e32 v17, v17, v18
	v_mul_f32_e32 v16, v10, v16
	v_mul_f32_e32 v10, 0xbfb8aa3b, v11
	v_mul_f32_e32 v11, 0xbfb8aa3b, v18
	v_exp_f32_e32 v10, v10
; __device__ __forceinline__ unsigned cvt_pk_bf16(float lo, float hi) { unsigned r; asm volatile("v_cvt_pk_bf16_f32 %0, %1, %2" : "=v"(r) : "v"(lo), "v"(hi)); return r; }
; __device__ __forceinline__ float bf_lo(unsigned w) { return __uint_as_float(w << 16); }
; __device__ __forceinline__ float bf_hi(unsigned w) { return __uint_as_float(w & 0xffff0000u); }
; #define PG8_WAIT_V(n) asm volatile("s_waitcnt vmcnt(" #n ")" ::: "memory")
; #define PG8_BAR __builtin_amdgcn_s_barrier()
; template <class Epi>
; __device__ __forceinline__ void gemm_phase(LAS unsigned char* lds, const Gemm g, const StaticOrder& S, const Epi& E) {
;     ...
;         if (!has_next) break;
; #pragma unroll
;         for (int a = 0; a < 2; ++a)
; #pragma unroll
;             for (int b = 0; b < 2; ++b)
; #pragma unroll
;                 for (int m = 0; m < 4; ++m)
; #pragma unroll
;                     for (int n = 0; n < 2; ++n) acc[a][b][m][n] = (f32x4){0.f, 0.f, 0.f, 0.f};
;         cur = nxt; cA = nA; cB = nB; ++ui;
;         pre = E.pre(cur, wr, fr);
;     }
;     PG8_WAIT_V(0);
;     if (wr == 0) PG8_BAR;
;     PG8_BAR;
;     __device__ __forceinline__ void operator()(const f32x4 (&acc)[2][2][4][2], const Unit& u, int wr, int wc, int fr, int fq, const Pre&) const {
;     ...
;                 for (int m = 0; m < 4; ++m) { const int r = row0 + ai * HALF + m * 16;
;                     const u32x4 zw = zv[m], gw = gv[m];
;                     const f32x4 a0 = acc[ai][bj][m][0] + bs[bj][0], a1 = acc[ai][bj][m][1] + bs[bj][1];
;                     u32x4 w;
;                     w.x = cvt_pk_bf16(glu_gate_f(bf_lo(gw.x), a0[0], bf_lo(zw.x)), glu_gate_f(bf_hi(gw.x), a0[1], bf_hi(zw.x)));
;                     w.y = cvt_pk_bf16(glu_gate_f(bf_lo(gw.y), a0[2], bf_lo(zw.y)), glu_gate_f(bf_hi(gw.y), a0[3], bf_hi(zw.y)));
;                     w.z = cvt_pk_bf16(glu_gate_f(bf_lo(gw.z), a1[0], bf_lo(zw.z)), glu_gate_f(bf_hi(gw.z), a1[1], bf_hi(zw.z)));
;                     w.w = cvt_pk_bf16(glu_gate_f(bf_lo(gw.w), a1[2], bf_lo(zw.w)), glu_gate_f(bf_hi(gw.w), a1[3], bf_hi(zw.w)));
;                     *(u32x4*)(O + (size_t)r * DE + c) = w; } } }
	v_exp_f32_e32 v11, v11
	v_lshlrev_b32_e32 v18, 16, v57
	v_pk_add_f32 v[10:11], v[10:11], 1.0 op_sel_hi:[1,0]
	s_nop 0
	v_mul_f32_e32 v10, v10, v11
	v_rcp_f32_e32 v10, v10
	s_nop 0
	v_mul_f32_e32 v10, v17, v10
	v_lshlrev_b32_e32 v17, 16, v53
	v_cvt_pk_bf16_f32 v16, v16, v10
	v_mul_f32_e32 v10, 0xbfb8aa3b, v12
	v_mul_f32_e32 v11, 0xbfb8aa3b, v17
	v_exp_f32_e32 v10, v10
	v_exp_f32_e32 v11, v11
	v_mul_f32_e32 v12, v18, v17
	v_and_b32_e32 v18, 0xffff0000, v53
	v_and_b32_e32 v17, 0xffff0000, v57
	v_pk_add_f32 v[10:11], v[10:11], 1.0 op_sel_hi:[1,0]
	s_nop 0
	v_mul_f32_e32 v10, v10, v11
	v_rcp_f32_e32 v10, v10
	v_mul_f32_e32 v11, 0xbfb8aa3b, v18
	v_exp_f32_e32 v11, v11
	v_mul_f32_e32 v12, v12, v10
	v_mul_f32_e32 v10, 0xbfb8aa3b, v13
	v_exp_f32_e32 v10, v10
	v_mul_f32_e32 v13, v17, v18
	v_pk_add_f32 v[10:11], v[10:11], 1.0 op_sel_hi:[1,0]
	s_nop 0
	v_mul_f32_e32 v10, v10, v11
	v_rcp_f32_e32 v10, v10
	s_nop 0
	v_mul_f32_e32 v10, v13, v10
	v_cvt_pk_bf16_f32 v17, v12, v10
	v_lshlrev_b32_e32 v12, 16, v42
	v_exp_f32_e32 v10, v6
	v_mul_f32_e32 v6, 0xbfb8aa3b, v12
	v_exp_f32_e32 v11, v6
	v_lshlrev_b32_e32 v13, 16, v46
	v_mul_f32_e32 v6, v13, v12
	v_and_b32_e32 v12, 0xffff0000, v42
	v_pk_add_f32 v[10:11], v[10:11], 1.0 op_sel_hi:[1,0]
	global_store_dwordx4 v[110:111], v[14:17], off offset:256
	v_mul_f32_e32 v10, v10, v11
	v_rcp_f32_e32 v10, v10
	v_and_b32_e32 v11, 0xffff0000, v46
	v_mul_f32_e32 v11, v11, v12
	v_mul_f32_e32 v10, v6, v10
	v_mul_f32_e32 v6, 0xbfb8aa3b, v7
	v_mul_f32_e32 v7, 0xbfb8aa3b, v12
	v_exp_f32_e32 v6, v6
	v_exp_f32_e32 v7, v7
	v_lshlrev_b32_e32 v12, 16, v47
	v_pk_add_f32 v[6:7], v[6:7], 1.0 op_sel_hi:[1,0]
	s_nop 0
	v_mul_f32_e32 v6, v6, v7
	v_rcp_f32_e32 v6, v6
	v_lshlrev_b32_e32 v7, 16, v43
	v_mul_f32_e32 v6, v11, v6
	v_cvt_pk_bf16_f32 v6, v10, v6
	v_exp_f32_e32 v10, v8
	v_mul_f32_e32 v8, 0xbfb8aa3b, v7
	v_exp_f32_e32 v11, v8
	v_mul_f32_e32 v7, v12, v7
	v_pk_add_f32 v[10:11], v[10:11], 1.0 op_sel_hi:[1,0]
	s_nop 0
	v_mul_f32_e32 v8, v10, v11
	v_rcp_f32_e32 v8, v8
	v_and_b32_e32 v11, 0xffff0000, v43
	v_and_b32_e32 v10, 0xffff0000, v47
	v_mul_f32_e32 v10, v10, v11
	v_mul_f32_e32 v7, v7, v8
	v_mul_f32_e32 v8, 0xbfb8aa3b, v9
	v_mul_f32_e32 v9, 0xbfb8aa3b, v11
	v_exp_f32_e32 v8, v8
	v_exp_f32_e32 v9, v9
	v_lshlrev_b32_e32 v11, 16, v48
	v_pk_add_f32 v[8:9], v[8:9], 1.0 op_sel_hi:[1,0]
	s_nop 0
	v_mul_f32_e32 v8, v8, v9
	v_rcp_f32_e32 v8, v8
	s_nop 0
	v_mul_f32_e32 v8, v10, v8
	v_lshlrev_b32_e32 v10, 16, v44
	v_cvt_pk_bf16_f32 v7, v7, v8
	v_exp_f32_e32 v8, v2
	v_mul_f32_e32 v2, 0xbfb8aa3b, v10
	v_exp_f32_e32 v9, v2
	v_mul_f32_e32 v2, v11, v10
	v_and_b32_e32 v10, 0xffff0000, v44
	v_pk_add_f32 v[8:9], v[8:9], 1.0 op_sel_hi:[1,0]
	s_nop 0
	v_mul_f32_e32 v8, v8, v9
	v_rcp_f32_e32 v8, v8
	v_and_b32_e32 v9, 0xffff0000, v48
	v_mul_f32_e32 v9, v9, v10
	v_mul_f32_e32 v8, v2, v8
	v_mul_f32_e32 v2, 0xbfb8aa3b, v3
	v_mul_f32_e32 v3, 0xbfb8aa3b, v10
	v_exp_f32_e32 v2, v2
	v_exp_f32_e32 v3, v3
	v_lshlrev_b32_e32 v10, 16, v49
	v_pk_add_f32 v[2:3], v[2:3], 1.0 op_sel_hi:[1,0]
	s_nop 0
	v_mul_f32_e32 v2, v2, v3
	v_rcp_f32_e32 v2, v2
	s_nop 0
	v_mul_f32_e32 v2, v9, v2
	v_lshlrev_b32_e32 v9, 16, v45
	v_cvt_pk_bf16_f32 v8, v8, v2
	v_mul_f32_e32 v2, 0xbfb8aa3b, v4
	v_mul_f32_e32 v3, 0xbfb8aa3b, v9
	v_exp_f32_e32 v2, v2
	v_exp_f32_e32 v3, v3
	v_mul_f32_e32 v4, v10, v9
	v_and_b32_e32 v10, 0xffff0000, v45
	v_and_b32_e32 v9, 0xffff0000, v49
	v_pk_add_f32 v[2:3], v[2:3], 1.0 op_sel_hi:[1,0]
	s_nop 0
	v_mul_f32_e32 v2, v2, v3
	v_rcp_f32_e32 v2, v2
	v_mul_f32_e32 v3, 0xbfb8aa3b, v10
	v_exp_f32_e32 v3, v3
	v_mul_f32_e32 v4, v4, v2
	v_mul_f32_e32 v2, 0xbfb8aa3b, v5
	v_exp_f32_e32 v2, v2
	v_mul_f32_e32 v5, v9, v10
	v_pk_add_f32 v[2:3], v[2:3], 1.0 op_sel_hi:[1,0]
	s_nop 0
	v_mul_f32_e32 v2, v2, v3
	v_rcp_f32_e32 v2, v2
	s_nop 0
	v_mul_f32_e32 v2, v5, v2
	v_cvt_pk_bf16_f32 v9, v4, v2
	global_store_dwordx4 v[112:113], v[6:9], off offset:256
	s_cbranch_vccz .LBB0_789
	s_waitcnt vmcnt(0)
	v_readlane_b32 s36, v254, 56
	s_cmpk_gt_u32 s18, 0xff
	v_readlane_b32 s37, v254, 57
	s_cbranch_scc1 .LBB0_800
	s_barrier
